# baseline (speedup 1.0000x reference)
.LBB0_65:
	ds_read_b128 v[128:131], v173
	ds_read_b128 v[132:135], v173 offset:1024
	ds_read_b128 v[158:161], v173 offset:2048
	ds_read_b128 v[178:181], v173 offset:3072
	ds_read_b128 v[182:185], v174
	ds_read_b128 v[186:189], v174 offset:1024
	ds_read_b128 v[190:193], v174 offset:2048
	ds_read_b128 v[194:197], v174 offset:3072
	s_add_u32 s3, s14, 0xfff80080
	s_addc_u32 s34, s15, -1
	s_cmp_eq_u32 s37, 28
	s_cselect_b32 s91, s0, s34
	s_cselect_b32 s90, s1, s3
	s_cselect_b32 s35, s7, s36
	s_cselect_b32 s34, s13, s24
	s_add_i32 m0, s27, 0xc000
	ds_read_b128 v[198:201], v175
	ds_read_b128 v[202:205], v175 offset:1024
	ds_read_b128 v[206:209], v175 offset:2048
	ds_read_b128 v[210:213], v175 offset:3072
	ds_read_b128 v[214:217], v175 offset:4096
	ds_read_b128 v[218:221], v175 offset:5120
	ds_read_b128 v[222:225], v175 offset:6144
	ds_read_b128 v[230:233], v175 offset:7168
	global_load_lds_dwordx4 v148, s[14:15]
	s_add_i32 m0, s27, 0xe000
	s_nop 0
	global_load_lds_dwordx4 v150, s[14:15]
	s_waitcnt vmcnt(8)
	s_waitcnt lgkmcnt(0)
	s_barrier
	v_mfma_f32_16x16x32_bf16 v[124:127], v[128:131], v[198:201], v[124:127]
	v_mfma_f32_16x16x32_bf16 v[120:123], v[158:161], v[198:201], v[120:123]
	v_mfma_f32_16x16x32_bf16 v[108:111], v[128:131], v[206:209], v[108:111]
	v_mfma_f32_16x16x32_bf16 v[104:107], v[158:161], v[206:209], v[104:107]
	v_mfma_f32_16x16x32_bf16 v[92:95], v[128:131], v[214:217], v[92:95]
	v_mfma_f32_16x16x32_bf16 v[88:91], v[158:161], v[214:217], v[88:91]
	v_mfma_f32_16x16x32_bf16 v[76:79], v[128:131], v[222:225], v[76:79]
	v_mfma_f32_16x16x32_bf16 v[72:75], v[158:161], v[222:225], v[72:75]
	v_mfma_f32_16x16x32_bf16 v[124:127], v[132:135], v[202:205], v[124:127]
	v_mfma_f32_16x16x32_bf16 v[120:123], v[178:181], v[202:205], v[120:123]
	v_mfma_f32_16x16x32_bf16 v[108:111], v[132:135], v[210:213], v[108:111]
	v_mfma_f32_16x16x32_bf16 v[104:107], v[178:181], v[210:213], v[104:107]
	v_mfma_f32_16x16x32_bf16 v[92:95], v[132:135], v[218:221], v[92:95]
	v_mfma_f32_16x16x32_bf16 v[88:91], v[178:181], v[218:221], v[88:91]
	v_mfma_f32_16x16x32_bf16 v[76:79], v[132:135], v[230:233], v[76:79]
	v_mfma_f32_16x16x32_bf16 v[72:75], v[178:181], v[230:233], v[72:75]
	v_mfma_f32_16x16x32_bf16 v[116:119], v[182:185], v[198:201], v[116:119]
	v_mfma_f32_16x16x32_bf16 v[112:115], v[190:193], v[198:201], v[112:115]
	v_mfma_f32_16x16x32_bf16 v[100:103], v[182:185], v[206:209], v[100:103]
	v_mfma_f32_16x16x32_bf16 v[96:99], v[190:193], v[206:209], v[96:99]
	v_mfma_f32_16x16x32_bf16 v[84:87], v[182:185], v[214:217], v[84:87]
	v_mfma_f32_16x16x32_bf16 v[80:83], v[190:193], v[214:217], v[80:83]
	v_mfma_f32_16x16x32_bf16 v[68:71], v[182:185], v[222:225], v[68:71]
	v_mfma_f32_16x16x32_bf16 v[64:67], v[190:193], v[222:225], v[64:67]
	v_mfma_f32_16x16x32_bf16 v[116:119], v[186:189], v[202:205], v[116:119]
	v_mfma_f32_16x16x32_bf16 v[112:115], v[194:197], v[202:205], v[112:115]
	v_mfma_f32_16x16x32_bf16 v[100:103], v[186:189], v[210:213], v[100:103]
	v_mfma_f32_16x16x32_bf16 v[96:99], v[194:197], v[210:213], v[96:99]
	v_mfma_f32_16x16x32_bf16 v[84:87], v[186:189], v[218:221], v[84:87]
	v_mfma_f32_16x16x32_bf16 v[80:83], v[194:197], v[218:221], v[80:83]
	v_mfma_f32_16x16x32_bf16 v[68:71], v[186:189], v[230:233], v[68:71]
	v_mfma_f32_16x16x32_bf16 v[64:67], v[194:197], v[230:233], v[64:67]
	s_barrier
	s_add_i32 s3, s78, s25
	s_mov_b32 m0, s3
	ds_read_b128 v[198:201], v175 offset:16384
	ds_read_b128 v[202:205], v175 offset:17408
	ds_read_b128 v[206:209], v175 offset:18432
	ds_read_b128 v[210:213], v175 offset:19456
	ds_read_b128 v[214:217], v175 offset:20480
	ds_read_b128 v[218:221], v175 offset:21504
	ds_read_b128 v[222:225], v175 offset:22528
	ds_read_b128 v[230:233], v175 offset:23552
	global_load_lds_dwordx4 v138, s[34:35]
	s_add_i32 m0, s3, 0x2000
	s_add_u32 s42, s34, 0x80000
	s_addc_u32 s43, s35, 0
	s_add_i32 s3, s79, s25
	global_load_lds_dwordx4 v142, s[34:35]
	s_mov_b32 m0, s3
	s_nop 0
	global_load_lds_dwordx4 v138, s[42:43]
	s_add_i32 m0, s3, 0x2000
	s_nop 0
	global_load_lds_dwordx4 v142, s[42:43]
	s_mov_b32 m0, s27
	s_nop 0
	global_load_lds_dwordx4 v136, s[90:91]
	s_mov_b32 m0, s30
	s_nop 0
	global_load_lds_dwordx4 v140, s[90:91]
	s_waitcnt vmcnt(8)
	s_waitcnt lgkmcnt(0)
	s_barrier
	v_mfma_f32_16x16x32_bf16 v[60:63], v[128:131], v[198:201], v[60:63]
	v_mfma_f32_16x16x32_bf16 v[56:59], v[158:161], v[198:201], v[56:59]
	v_mfma_f32_16x16x32_bf16 v[44:47], v[128:131], v[206:209], v[44:47]
	v_mfma_f32_16x16x32_bf16 v[40:43], v[158:161], v[206:209], v[40:43]
	v_mfma_f32_16x16x32_bf16 v[28:31], v[128:131], v[214:217], v[28:31]
	v_mfma_f32_16x16x32_bf16 v[24:27], v[158:161], v[214:217], v[24:27]
	v_mfma_f32_16x16x32_bf16 v[12:15], v[128:131], v[222:225], v[12:15]
	v_mfma_f32_16x16x32_bf16 v[8:11], v[158:161], v[222:225], v[8:11]
	v_mfma_f32_16x16x32_bf16 v[60:63], v[132:135], v[202:205], v[60:63]
	v_mfma_f32_16x16x32_bf16 v[56:59], v[178:181], v[202:205], v[56:59]
	v_mfma_f32_16x16x32_bf16 v[44:47], v[132:135], v[210:213], v[44:47]
	v_mfma_f32_16x16x32_bf16 v[40:43], v[178:181], v[210:213], v[40:43]
	v_mfma_f32_16x16x32_bf16 v[28:31], v[132:135], v[218:221], v[28:31]
	v_mfma_f32_16x16x32_bf16 v[24:27], v[178:181], v[218:221], v[24:27]
	v_mfma_f32_16x16x32_bf16 v[12:15], v[132:135], v[230:233], v[12:15]
	v_mfma_f32_16x16x32_bf16 v[8:11], v[178:181], v[230:233], v[8:11]
	v_mfma_f32_16x16x32_bf16 v[52:55], v[182:185], v[198:201], v[52:55]
	v_mfma_f32_16x16x32_bf16 v[48:51], v[190:193], v[198:201], v[48:51]
	v_mfma_f32_16x16x32_bf16 v[36:39], v[182:185], v[206:209], v[36:39]
	v_mfma_f32_16x16x32_bf16 v[32:35], v[190:193], v[206:209], v[32:35]
	v_mfma_f32_16x16x32_bf16 v[20:23], v[182:185], v[214:217], v[20:23]
	v_mfma_f32_16x16x32_bf16 v[16:19], v[190:193], v[214:217], v[16:19]
	v_mfma_f32_16x16x32_bf16 v[4:7], v[182:185], v[222:225], v[4:7]
	v_mfma_f32_16x16x32_bf16 v[0:3], v[190:193], v[222:225], v[0:3]
	v_mfma_f32_16x16x32_bf16 v[52:55], v[186:189], v[202:205], v[52:55]
	v_mfma_f32_16x16x32_bf16 v[48:51], v[194:197], v[202:205], v[48:51]
	v_mfma_f32_16x16x32_bf16 v[36:39], v[186:189], v[210:213], v[36:39]
	v_mfma_f32_16x16x32_bf16 v[32:35], v[194:197], v[210:213], v[32:35]
	v_mfma_f32_16x16x32_bf16 v[20:23], v[186:189], v[218:221], v[20:23]
	v_mfma_f32_16x16x32_bf16 v[16:19], v[194:197], v[218:221], v[16:19]
	v_mfma_f32_16x16x32_bf16 v[4:7], v[186:189], v[230:233], v[4:7]
	v_mfma_f32_16x16x32_bf16 v[0:3], v[194:197], v[230:233], v[0:3]
	s_barrier
	s_add_i32 s3, 0, 0x18000
	v_add_u32_e32 v144, s3, v165
	s_add_i32 s44, 0, 0x1c000
	ds_read_b128 v[128:131], v144
	ds_read_b128 v[132:135], v144 offset:1024
	ds_read_b128 v[158:161], v144 offset:2048
	ds_read_b128 v[178:181], v144 offset:3072
	v_add_u32_e32 v144, s44, v165
	ds_read_b128 v[182:185], v144
	ds_read_b128 v[186:189], v144 offset:1024
	ds_read_b128 v[190:193], v144 offset:2048
	ds_read_b128 v[194:197], v144 offset:3072
	s_add_u32 s42, s90, 0x80000
	s_addc_u32 s43, s91, 0
	s_mov_b32 m0, s31
	ds_read_b128 v[198:201], v175 offset:32768
	ds_read_b128 v[202:205], v175 offset:33792
	ds_read_b128 v[206:209], v175 offset:34816
	ds_read_b128 v[210:213], v175 offset:35840
	ds_read_b128 v[214:217], v175 offset:36864
	ds_read_b128 v[218:221], v175 offset:37888
	ds_read_b128 v[222:225], v175 offset:38912
	ds_read_b128 v[230:233], v175 offset:39936
	global_load_lds_dwordx4 v136, s[42:43]
	s_mov_b32 m0, s33
	s_nop 0
	global_load_lds_dwordx4 v140, s[42:43]
	s_waitcnt vmcnt(8)
	s_waitcnt lgkmcnt(0)
	s_barrier
	v_mfma_f32_16x16x32_bf16 v[124:127], v[128:131], v[198:201], v[124:127]
	v_mfma_f32_16x16x32_bf16 v[120:123], v[158:161], v[198:201], v[120:123]
	v_mfma_f32_16x16x32_bf16 v[108:111], v[128:131], v[206:209], v[108:111]
	v_mfma_f32_16x16x32_bf16 v[104:107], v[158:161], v[206:209], v[104:107]
	v_mfma_f32_16x16x32_bf16 v[92:95], v[128:131], v[214:217], v[92:95]
	v_mfma_f32_16x16x32_bf16 v[88:91], v[158:161], v[214:217], v[88:91]
	v_mfma_f32_16x16x32_bf16 v[76:79], v[128:131], v[222:225], v[76:79]
	v_mfma_f32_16x16x32_bf16 v[72:75], v[158:161], v[222:225], v[72:75]
	v_mfma_f32_16x16x32_bf16 v[124:127], v[132:135], v[202:205], v[124:127]
	v_mfma_f32_16x16x32_bf16 v[120:123], v[178:181], v[202:205], v[120:123]
	v_mfma_f32_16x16x32_bf16 v[108:111], v[132:135], v[210:213], v[108:111]
	v_mfma_f32_16x16x32_bf16 v[104:107], v[178:181], v[210:213], v[104:107]
	v_mfma_f32_16x16x32_bf16 v[92:95], v[132:135], v[218:221], v[92:95]
	v_mfma_f32_16x16x32_bf16 v[88:91], v[178:181], v[218:221], v[88:91]
	v_mfma_f32_16x16x32_bf16 v[76:79], v[132:135], v[230:233], v[76:79]
	v_mfma_f32_16x16x32_bf16 v[72:75], v[178:181], v[230:233], v[72:75]
	v_mfma_f32_16x16x32_bf16 v[116:119], v[182:185], v[198:201], v[116:119]
	v_mfma_f32_16x16x32_bf16 v[112:115], v[190:193], v[198:201], v[112:115]
	v_mfma_f32_16x16x32_bf16 v[100:103], v[182:185], v[206:209], v[100:103]
	v_mfma_f32_16x16x32_bf16 v[96:99], v[190:193], v[206:209], v[96:99]
	v_mfma_f32_16x16x32_bf16 v[84:87], v[182:185], v[214:217], v[84:87]
	v_mfma_f32_16x16x32_bf16 v[80:83], v[190:193], v[214:217], v[80:83]
	v_mfma_f32_16x16x32_bf16 v[68:71], v[182:185], v[222:225], v[68:71]
	v_mfma_f32_16x16x32_bf16 v[64:67], v[190:193], v[222:225], v[64:67]
	v_mfma_f32_16x16x32_bf16 v[116:119], v[186:189], v[202:205], v[116:119]
	v_mfma_f32_16x16x32_bf16 v[112:115], v[194:197], v[202:205], v[112:115]
	v_mfma_f32_16x16x32_bf16 v[100:103], v[186:189], v[210:213], v[100:103]
	v_mfma_f32_16x16x32_bf16 v[96:99], v[194:197], v[210:213], v[96:99]
	v_mfma_f32_16x16x32_bf16 v[84:87], v[186:189], v[218:221], v[84:87]
	v_mfma_f32_16x16x32_bf16 v[80:83], v[194:197], v[218:221], v[80:83]
	v_mfma_f32_16x16x32_bf16 v[68:71], v[186:189], v[230:233], v[68:71]
	v_mfma_f32_16x16x32_bf16 v[64:67], v[194:197], v[230:233], v[64:67]
	s_barrier
	s_add_i32 s3, s3, s25
	s_add_u32 s34, s34, 0x80
	s_addc_u32 s35, s35, 0
	s_mov_b32 m0, s3
	ds_read_b128 v[198:201], v175 offset:49152
	ds_read_b128 v[202:205], v175 offset:50176
	ds_read_b128 v[206:209], v175 offset:51200
	ds_read_b128 v[210:213], v175 offset:52224
	ds_read_b128 v[214:217], v175 offset:53248
	ds_read_b128 v[218:221], v175 offset:54272
	ds_read_b128 v[222:225], v175 offset:55296
	ds_read_b128 v[230:233], v175 offset:56320
	global_load_lds_dwordx4 v138, s[34:35]
	s_add_i32 m0, s3, 0x2000
	s_add_i32 s3, s44, s25
	global_load_lds_dwordx4 v142, s[34:35]
	s_add_u32 s34, s34, 0x80000
	s_addc_u32 s35, s35, 0
	s_mov_b32 m0, s3
	s_nop 0
	global_load_lds_dwordx4 v138, s[34:35]
	s_add_i32 m0, s3, 0x2000
	s_nop 0
	global_load_lds_dwordx4 v142, s[34:35]
	s_add_u32 s90, s90, 0x80
	s_addc_u32 s91, s91, 0
	s_mov_b32 m0, s58
	s_nop 0
	global_load_lds_dwordx4 v136, s[90:91]
	s_mov_b32 m0, s59
	s_nop 0
	global_load_lds_dwordx4 v140, s[90:91]
	s_waitcnt vmcnt(8)
	s_waitcnt lgkmcnt(0)
	s_barrier
	v_mfma_f32_16x16x32_bf16 v[60:63], v[128:131], v[198:201], v[60:63]
	v_mfma_f32_16x16x32_bf16 v[56:59], v[158:161], v[198:201], v[56:59]
	v_mfma_f32_16x16x32_bf16 v[44:47], v[128:131], v[206:209], v[44:47]
	v_mfma_f32_16x16x32_bf16 v[40:43], v[158:161], v[206:209], v[40:43]
	v_mfma_f32_16x16x32_bf16 v[28:31], v[128:131], v[214:217], v[28:31]
	v_mfma_f32_16x16x32_bf16 v[24:27], v[158:161], v[214:217], v[24:27]
	v_mfma_f32_16x16x32_bf16 v[12:15], v[128:131], v[222:225], v[12:15]
	v_mfma_f32_16x16x32_bf16 v[8:11], v[158:161], v[222:225], v[8:11]
	v_mfma_f32_16x16x32_bf16 v[60:63], v[132:135], v[202:205], v[60:63]
	v_mfma_f32_16x16x32_bf16 v[56:59], v[178:181], v[202:205], v[56:59]
	v_mfma_f32_16x16x32_bf16 v[44:47], v[132:135], v[210:213], v[44:47]
	v_mfma_f32_16x16x32_bf16 v[40:43], v[178:181], v[210:213], v[40:43]
	v_mfma_f32_16x16x32_bf16 v[28:31], v[132:135], v[218:221], v[28:31]
	v_mfma_f32_16x16x32_bf16 v[24:27], v[178:181], v[218:221], v[24:27]
	v_mfma_f32_16x16x32_bf16 v[12:15], v[132:135], v[230:233], v[12:15]
	v_mfma_f32_16x16x32_bf16 v[8:11], v[178:181], v[230:233], v[8:11]
	v_mfma_f32_16x16x32_bf16 v[52:55], v[182:185], v[198:201], v[52:55]
	v_mfma_f32_16x16x32_bf16 v[48:51], v[190:193], v[198:201], v[48:51]
	v_mfma_f32_16x16x32_bf16 v[36:39], v[182:185], v[206:209], v[36:39]
	v_mfma_f32_16x16x32_bf16 v[32:35], v[190:193], v[206:209], v[32:35]
	v_mfma_f32_16x16x32_bf16 v[20:23], v[182:185], v[214:217], v[20:23]
	v_mfma_f32_16x16x32_bf16 v[16:19], v[190:193], v[214:217], v[16:19]
	v_mfma_f32_16x16x32_bf16 v[4:7], v[182:185], v[222:225], v[4:7]
	v_mfma_f32_16x16x32_bf16 v[0:3], v[190:193], v[222:225], v[0:3]
	v_mfma_f32_16x16x32_bf16 v[52:55], v[186:189], v[202:205], v[52:55]
	v_mfma_f32_16x16x32_bf16 v[48:51], v[194:197], v[202:205], v[48:51]
	v_mfma_f32_16x16x32_bf16 v[36:39], v[186:189], v[210:213], v[36:39]
	v_mfma_f32_16x16x32_bf16 v[32:35], v[194:197], v[210:213], v[32:35]
	v_mfma_f32_16x16x32_bf16 v[20:23], v[186:189], v[218:221], v[20:23]
	v_mfma_f32_16x16x32_bf16 v[16:19], v[194:197], v[218:221], v[16:19]
	v_mfma_f32_16x16x32_bf16 v[4:7], v[186:189], v[230:233], v[4:7]
	v_mfma_f32_16x16x32_bf16 v[0:3], v[194:197], v[230:233], v[0:3]
	s_barrier
	s_add_i32 s37, s37, 2
	s_add_u32 s14, s14, 0x100
	s_addc_u32 s15, s15, 0
	s_add_u32 s24, s24, 0x100
	s_addc_u32 s36, s36, 0
	s_cmp_gt_u32 s37, 29
	s_cbranch_scc0 .LBB0_65
	s_and_b64 vcc, exec, s[48:49]
	s_cbranch_vccz .LBB0_68
	s_barrier

.LBB0_539:
	ds_read_b128 v[144:147], v153
	ds_read_b128 v[156:159], v153 offset:1024
	ds_read_b128 v[160:163], v153 offset:2048
	ds_read_b128 v[164:167], v153 offset:3072
	ds_read_b128 v[168:171], v154
	ds_read_b128 v[172:175], v154 offset:1024
	ds_read_b128 v[176:179], v154 offset:2048
	ds_read_b128 v[180:183], v154 offset:3072
	s_add_u32 s3, s86, 0xfffc0080
	s_addc_u32 s37, s87, -1
	s_cmp_eq_u32 s36, 12
	s_cselect_b32 s91, s0, s37
	s_cselect_b32 s90, s1, s3
	s_cselect_b32 s89, s17, s35
	s_cselect_b32 s88, s27, s33
	s_add_i32 m0, s19, 0xc000
	ds_read_b128 v[184:187], v155
	ds_read_b128 v[188:191], v155 offset:1024
	ds_read_b128 v[192:195], v155 offset:2048
	ds_read_b128 v[196:199], v155 offset:3072
	ds_read_b128 v[200:203], v155 offset:4096
	ds_read_b128 v[204:207], v155 offset:5120
	ds_read_b128 v[208:211], v155 offset:6144
	ds_read_b128 v[212:215], v155 offset:7168
	global_load_lds_dwordx4 v136, s[86:87]
	s_add_i32 m0, s19, 0xe000
	s_nop 0
	global_load_lds_dwordx4 v138, s[86:87]
	s_waitcnt vmcnt(8)
	s_waitcnt lgkmcnt(0)
	s_barrier
	v_mfma_f32_16x16x32_bf16 v[124:127], v[144:147], v[184:187], v[124:127]
	v_mfma_f32_16x16x32_bf16 v[120:123], v[160:163], v[184:187], v[120:123]
	v_mfma_f32_16x16x32_bf16 v[108:111], v[144:147], v[192:195], v[108:111]
	v_mfma_f32_16x16x32_bf16 v[104:107], v[160:163], v[192:195], v[104:107]
	v_mfma_f32_16x16x32_bf16 v[92:95], v[144:147], v[200:203], v[92:95]
	v_mfma_f32_16x16x32_bf16 v[88:91], v[160:163], v[200:203], v[88:91]
	v_mfma_f32_16x16x32_bf16 v[76:79], v[144:147], v[208:211], v[76:79]
	v_mfma_f32_16x16x32_bf16 v[72:75], v[160:163], v[208:211], v[72:75]
	v_mfma_f32_16x16x32_bf16 v[124:127], v[156:159], v[188:191], v[124:127]
	v_mfma_f32_16x16x32_bf16 v[120:123], v[164:167], v[188:191], v[120:123]
	v_mfma_f32_16x16x32_bf16 v[108:111], v[156:159], v[196:199], v[108:111]
	v_mfma_f32_16x16x32_bf16 v[104:107], v[164:167], v[196:199], v[104:107]
	v_mfma_f32_16x16x32_bf16 v[92:95], v[156:159], v[204:207], v[92:95]
	v_mfma_f32_16x16x32_bf16 v[88:91], v[164:167], v[204:207], v[88:91]
	v_mfma_f32_16x16x32_bf16 v[76:79], v[156:159], v[212:215], v[76:79]
	v_mfma_f32_16x16x32_bf16 v[72:75], v[164:167], v[212:215], v[72:75]
	v_mfma_f32_16x16x32_bf16 v[116:119], v[168:171], v[184:187], v[116:119]
	v_mfma_f32_16x16x32_bf16 v[112:115], v[176:179], v[184:187], v[112:115]
	v_mfma_f32_16x16x32_bf16 v[100:103], v[168:171], v[192:195], v[100:103]
	v_mfma_f32_16x16x32_bf16 v[96:99], v[176:179], v[192:195], v[96:99]
	v_mfma_f32_16x16x32_bf16 v[84:87], v[168:171], v[200:203], v[84:87]
	v_mfma_f32_16x16x32_bf16 v[80:83], v[176:179], v[200:203], v[80:83]
	v_mfma_f32_16x16x32_bf16 v[68:71], v[168:171], v[208:211], v[68:71]
	v_mfma_f32_16x16x32_bf16 v[64:67], v[176:179], v[208:211], v[64:67]
	v_mfma_f32_16x16x32_bf16 v[116:119], v[172:175], v[188:191], v[116:119]
	v_mfma_f32_16x16x32_bf16 v[112:115], v[180:183], v[188:191], v[112:115]
	v_mfma_f32_16x16x32_bf16 v[100:103], v[172:175], v[196:199], v[100:103]
	v_mfma_f32_16x16x32_bf16 v[96:99], v[180:183], v[196:199], v[96:99]
	v_mfma_f32_16x16x32_bf16 v[84:87], v[172:175], v[204:207], v[84:87]
	v_mfma_f32_16x16x32_bf16 v[80:83], v[180:183], v[204:207], v[80:83]
	v_mfma_f32_16x16x32_bf16 v[68:71], v[172:175], v[212:215], v[68:71]
	v_mfma_f32_16x16x32_bf16 v[64:67], v[180:183], v[212:215], v[64:67]
	s_barrier
	s_add_i32 s3, s57, s18
	s_mov_b32 m0, s3
	ds_read_b128 v[184:187], v155 offset:16384
	ds_read_b128 v[188:191], v155 offset:17408
	ds_read_b128 v[192:195], v155 offset:18432
	ds_read_b128 v[196:199], v155 offset:19456
	ds_read_b128 v[200:203], v155 offset:20480
	ds_read_b128 v[204:207], v155 offset:21504
	ds_read_b128 v[208:211], v155 offset:22528
	ds_read_b128 v[212:215], v155 offset:23552
	global_load_lds_dwordx4 v130, s[88:89]
	s_add_i32 m0, s3, 0x2000
	s_add_u32 s42, s88, 0x40000
	s_addc_u32 s43, s89, 0
	s_add_i32 s3, s58, s18
	global_load_lds_dwordx4 v134, s[88:89]
	s_mov_b32 m0, s3
	s_nop 0
	global_load_lds_dwordx4 v130, s[42:43]
	s_add_i32 m0, s3, 0x2000
	s_nop 0
	global_load_lds_dwordx4 v134, s[42:43]
	s_mov_b32 m0, s19
	s_nop 0
	global_load_lds_dwordx4 v128, s[90:91]
	s_mov_b32 m0, s25
	s_nop 0
	global_load_lds_dwordx4 v132, s[90:91]
	s_waitcnt vmcnt(8)
	s_waitcnt lgkmcnt(0)
	s_barrier
	v_mfma_f32_16x16x32_bf16 v[60:63], v[144:147], v[184:187], v[60:63]
	v_mfma_f32_16x16x32_bf16 v[56:59], v[160:163], v[184:187], v[56:59]
	v_mfma_f32_16x16x32_bf16 v[44:47], v[144:147], v[192:195], v[44:47]
	v_mfma_f32_16x16x32_bf16 v[40:43], v[160:163], v[192:195], v[40:43]
	v_mfma_f32_16x16x32_bf16 v[28:31], v[144:147], v[200:203], v[28:31]
	v_mfma_f32_16x16x32_bf16 v[24:27], v[160:163], v[200:203], v[24:27]
	v_mfma_f32_16x16x32_bf16 v[12:15], v[144:147], v[208:211], v[12:15]
	v_mfma_f32_16x16x32_bf16 v[8:11], v[160:163], v[208:211], v[8:11]
	v_mfma_f32_16x16x32_bf16 v[60:63], v[156:159], v[188:191], v[60:63]
	v_mfma_f32_16x16x32_bf16 v[56:59], v[164:167], v[188:191], v[56:59]
	v_mfma_f32_16x16x32_bf16 v[44:47], v[156:159], v[196:199], v[44:47]
	v_mfma_f32_16x16x32_bf16 v[40:43], v[164:167], v[196:199], v[40:43]
	v_mfma_f32_16x16x32_bf16 v[28:31], v[156:159], v[204:207], v[28:31]
	v_mfma_f32_16x16x32_bf16 v[24:27], v[164:167], v[204:207], v[24:27]
	v_mfma_f32_16x16x32_bf16 v[12:15], v[156:159], v[212:215], v[12:15]
	v_mfma_f32_16x16x32_bf16 v[8:11], v[164:167], v[212:215], v[8:11]
	v_mfma_f32_16x16x32_bf16 v[52:55], v[168:171], v[184:187], v[52:55]
	v_mfma_f32_16x16x32_bf16 v[48:51], v[176:179], v[184:187], v[48:51]
	v_mfma_f32_16x16x32_bf16 v[36:39], v[168:171], v[192:195], v[36:39]
	v_mfma_f32_16x16x32_bf16 v[32:35], v[176:179], v[192:195], v[32:35]
	v_mfma_f32_16x16x32_bf16 v[20:23], v[168:171], v[200:203], v[20:23]
	v_mfma_f32_16x16x32_bf16 v[16:19], v[176:179], v[200:203], v[16:19]
	v_mfma_f32_16x16x32_bf16 v[4:7], v[168:171], v[208:211], v[4:7]
	v_mfma_f32_16x16x32_bf16 v[0:3], v[176:179], v[208:211], v[0:3]
	v_mfma_f32_16x16x32_bf16 v[52:55], v[172:175], v[188:191], v[52:55]
	v_mfma_f32_16x16x32_bf16 v[48:51], v[180:183], v[188:191], v[48:51]
	v_mfma_f32_16x16x32_bf16 v[36:39], v[172:175], v[196:199], v[36:39]
	v_mfma_f32_16x16x32_bf16 v[32:35], v[180:183], v[196:199], v[32:35]
	v_mfma_f32_16x16x32_bf16 v[20:23], v[172:175], v[204:207], v[20:23]
	v_mfma_f32_16x16x32_bf16 v[16:19], v[180:183], v[204:207], v[16:19]
	v_mfma_f32_16x16x32_bf16 v[4:7], v[172:175], v[212:215], v[4:7]
	v_mfma_f32_16x16x32_bf16 v[0:3], v[180:183], v[212:215], v[0:3]
	s_barrier
	s_add_i32 s3, 0, 0x18000
	s_add_i32 s37, 0, 0x1c000
	v_add_u32_e32 v164, s3, v151
	v_add_u32_e32 v180, s37, v151
	ds_read_b128 v[144:147], v164
	ds_read_b128 v[156:159], v164 offset:1024
	ds_read_b128 v[160:163], v164 offset:2048
	ds_read_b128 v[164:167], v164 offset:3072
	ds_read_b128 v[168:171], v180
	ds_read_b128 v[172:175], v180 offset:1024
	ds_read_b128 v[176:179], v180 offset:2048
	ds_read_b128 v[180:183], v180 offset:3072
	s_add_u32 s42, s90, 0x40000
	s_addc_u32 s43, s91, 0
	s_mov_b32 m0, s30
	ds_read_b128 v[184:187], v155 offset:32768
	ds_read_b128 v[188:191], v155 offset:33792
	ds_read_b128 v[192:195], v155 offset:34816
	ds_read_b128 v[196:199], v155 offset:35840
	ds_read_b128 v[200:203], v155 offset:36864
	ds_read_b128 v[204:207], v155 offset:37888
	ds_read_b128 v[208:211], v155 offset:38912
	ds_read_b128 v[212:215], v155 offset:39936
	global_load_lds_dwordx4 v128, s[42:43]
	v_lshl_add_u64 v[222:223], s[42:43], 0, v[132:133]
	s_mov_b32 m0, s31
	s_nop 0
	global_load_lds_dwordx4 v[222:223], off
	s_waitcnt vmcnt(8)
	s_waitcnt lgkmcnt(0)
	s_barrier
	v_mfma_f32_16x16x32_bf16 v[124:127], v[144:147], v[184:187], v[124:127]
	v_mfma_f32_16x16x32_bf16 v[120:123], v[160:163], v[184:187], v[120:123]
	v_mfma_f32_16x16x32_bf16 v[108:111], v[144:147], v[192:195], v[108:111]
	v_mfma_f32_16x16x32_bf16 v[104:107], v[160:163], v[192:195], v[104:107]
	v_mfma_f32_16x16x32_bf16 v[92:95], v[144:147], v[200:203], v[92:95]
	v_mfma_f32_16x16x32_bf16 v[88:91], v[160:163], v[200:203], v[88:91]
	v_mfma_f32_16x16x32_bf16 v[76:79], v[144:147], v[208:211], v[76:79]
	v_mfma_f32_16x16x32_bf16 v[72:75], v[160:163], v[208:211], v[72:75]
	v_mfma_f32_16x16x32_bf16 v[124:127], v[156:159], v[188:191], v[124:127]
	v_mfma_f32_16x16x32_bf16 v[120:123], v[164:167], v[188:191], v[120:123]
	v_mfma_f32_16x16x32_bf16 v[108:111], v[156:159], v[196:199], v[108:111]
	v_mfma_f32_16x16x32_bf16 v[104:107], v[164:167], v[196:199], v[104:107]
	v_mfma_f32_16x16x32_bf16 v[92:95], v[156:159], v[204:207], v[92:95]
	v_mfma_f32_16x16x32_bf16 v[88:91], v[164:167], v[204:207], v[88:91]
	v_mfma_f32_16x16x32_bf16 v[76:79], v[156:159], v[212:215], v[76:79]
	v_mfma_f32_16x16x32_bf16 v[72:75], v[164:167], v[212:215], v[72:75]
	v_mfma_f32_16x16x32_bf16 v[116:119], v[168:171], v[184:187], v[116:119]
	v_mfma_f32_16x16x32_bf16 v[112:115], v[176:179], v[184:187], v[112:115]
	v_mfma_f32_16x16x32_bf16 v[100:103], v[168:171], v[192:195], v[100:103]
	v_mfma_f32_16x16x32_bf16 v[96:99], v[176:179], v[192:195], v[96:99]
	v_mfma_f32_16x16x32_bf16 v[84:87], v[168:171], v[200:203], v[84:87]
	v_mfma_f32_16x16x32_bf16 v[80:83], v[176:179], v[200:203], v[80:83]
	v_mfma_f32_16x16x32_bf16 v[68:71], v[168:171], v[208:211], v[68:71]
	v_mfma_f32_16x16x32_bf16 v[64:67], v[176:179], v[208:211], v[64:67]
	v_mfma_f32_16x16x32_bf16 v[116:119], v[172:175], v[188:191], v[116:119]
	v_mfma_f32_16x16x32_bf16 v[112:115], v[180:183], v[188:191], v[112:115]
	v_mfma_f32_16x16x32_bf16 v[100:103], v[172:175], v[196:199], v[100:103]
	v_mfma_f32_16x16x32_bf16 v[96:99], v[180:183], v[196:199], v[96:99]
	v_mfma_f32_16x16x32_bf16 v[84:87], v[172:175], v[204:207], v[84:87]
	v_mfma_f32_16x16x32_bf16 v[80:83], v[180:183], v[204:207], v[80:83]
	v_mfma_f32_16x16x32_bf16 v[68:71], v[172:175], v[212:215], v[68:71]
	v_mfma_f32_16x16x32_bf16 v[64:67], v[180:183], v[212:215], v[64:67]
	s_barrier
	s_add_i32 s3, s3, s18
	s_add_u32 s42, s88, 0x80
	s_addc_u32 s43, s89, 0
	s_mov_b32 m0, s3
	ds_read_b128 v[184:187], v155 offset:49152
	ds_read_b128 v[188:191], v155 offset:50176
	ds_read_b128 v[192:195], v155 offset:51200
	ds_read_b128 v[196:199], v155 offset:52224
	ds_read_b128 v[200:203], v155 offset:53248
	ds_read_b128 v[204:207], v155 offset:54272
	ds_read_b128 v[208:211], v155 offset:55296
	ds_read_b128 v[212:215], v155 offset:56320
	global_load_lds_dwordx4 v130, s[42:43]
	s_add_i32 m0, s3, 0x2000
	s_add_i32 s3, s37, s18
	global_load_lds_dwordx4 v134, s[42:43]
	s_add_u32 s42, s42, 0x40000
	s_addc_u32 s43, s43, 0
	s_mov_b32 m0, s3
	s_nop 0
	global_load_lds_dwordx4 v130, s[42:43]
	s_add_i32 m0, s3, 0x2000
	s_nop 0
	global_load_lds_dwordx4 v134, s[42:43]
	s_add_u32 s90, s90, 0x80
	s_addc_u32 s91, s91, 0
	s_mov_b32 m0, s49
	s_nop 0
	global_load_lds_dwordx4 v128, s[90:91]
	s_mov_b32 m0, s56
	s_nop 0
	global_load_lds_dwordx4 v132, s[90:91]
	s_waitcnt vmcnt(8)
	s_waitcnt lgkmcnt(0)
	s_barrier
	v_mfma_f32_16x16x32_bf16 v[60:63], v[144:147], v[184:187], v[60:63]
	v_mfma_f32_16x16x32_bf16 v[56:59], v[160:163], v[184:187], v[56:59]
	v_mfma_f32_16x16x32_bf16 v[44:47], v[144:147], v[192:195], v[44:47]
	v_mfma_f32_16x16x32_bf16 v[40:43], v[160:163], v[192:195], v[40:43]
	v_mfma_f32_16x16x32_bf16 v[28:31], v[144:147], v[200:203], v[28:31]
	v_mfma_f32_16x16x32_bf16 v[24:27], v[160:163], v[200:203], v[24:27]
	v_mfma_f32_16x16x32_bf16 v[12:15], v[144:147], v[208:211], v[12:15]
	v_mfma_f32_16x16x32_bf16 v[8:11], v[160:163], v[208:211], v[8:11]
	v_mfma_f32_16x16x32_bf16 v[60:63], v[156:159], v[188:191], v[60:63]
	v_mfma_f32_16x16x32_bf16 v[56:59], v[164:167], v[188:191], v[56:59]
	v_mfma_f32_16x16x32_bf16 v[44:47], v[156:159], v[196:199], v[44:47]
	v_mfma_f32_16x16x32_bf16 v[40:43], v[164:167], v[196:199], v[40:43]
	v_mfma_f32_16x16x32_bf16 v[28:31], v[156:159], v[204:207], v[28:31]
	v_mfma_f32_16x16x32_bf16 v[24:27], v[164:167], v[204:207], v[24:27]
	v_mfma_f32_16x16x32_bf16 v[12:15], v[156:159], v[212:215], v[12:15]
	v_mfma_f32_16x16x32_bf16 v[8:11], v[164:167], v[212:215], v[8:11]
	v_mfma_f32_16x16x32_bf16 v[52:55], v[168:171], v[184:187], v[52:55]
	v_mfma_f32_16x16x32_bf16 v[48:51], v[176:179], v[184:187], v[48:51]
	v_mfma_f32_16x16x32_bf16 v[36:39], v[168:171], v[192:195], v[36:39]
	v_mfma_f32_16x16x32_bf16 v[32:35], v[176:179], v[192:195], v[32:35]
	v_mfma_f32_16x16x32_bf16 v[20:23], v[168:171], v[200:203], v[20:23]
	v_mfma_f32_16x16x32_bf16 v[16:19], v[176:179], v[200:203], v[16:19]
	v_mfma_f32_16x16x32_bf16 v[4:7], v[168:171], v[208:211], v[4:7]
	v_mfma_f32_16x16x32_bf16 v[0:3], v[176:179], v[208:211], v[0:3]
	v_mfma_f32_16x16x32_bf16 v[52:55], v[172:175], v[188:191], v[52:55]
	v_mfma_f32_16x16x32_bf16 v[48:51], v[180:183], v[188:191], v[48:51]
	v_mfma_f32_16x16x32_bf16 v[36:39], v[172:175], v[196:199], v[36:39]
	v_mfma_f32_16x16x32_bf16 v[32:35], v[180:183], v[196:199], v[32:35]
	v_mfma_f32_16x16x32_bf16 v[20:23], v[172:175], v[204:207], v[20:23]
	v_mfma_f32_16x16x32_bf16 v[16:19], v[180:183], v[204:207], v[16:19]
	v_mfma_f32_16x16x32_bf16 v[4:7], v[172:175], v[212:215], v[4:7]
	v_mfma_f32_16x16x32_bf16 v[0:3], v[180:183], v[212:215], v[0:3]
	s_barrier
	s_add_i32 s36, s36, 2
	s_add_u32 s86, s86, 0x100
	s_addc_u32 s87, s87, 0
	s_add_u32 s33, s33, 0x100
	s_addc_u32 s35, s35, 0
	s_cmp_gt_u32 s36, 13
	s_cbranch_scc0 .LBB0_539
	s_and_b64 vcc, exec, s[12:13]
	s_cbranch_vccz .LBB0_542
	s_barrier

.LBB0_563:
	ds_read_b128 v[144:147], v157
	ds_read_b128 v[148:151], v157 offset:1024
	ds_read_b128 v[160:163], v157 offset:2048
	ds_read_b128 v[164:167], v157 offset:3072
	ds_read_b128 v[168:171], v158
	ds_read_b128 v[172:175], v158 offset:1024
	ds_read_b128 v[176:179], v158 offset:2048
	ds_read_b128 v[180:183], v158 offset:3072
	s_add_u32 s3, s34, 0xfffe0080
	s_addc_u32 s42, s35, -1
	s_cmp_eq_u32 s37, 4
	s_cselect_b32 s91, s0, s42
	s_cselect_b32 s90, s1, s3
	s_cselect_b32 s89, s24, s36
	s_cselect_b32 s88, s27, s33
	s_add_i32 m0, s19, 0xc000
	ds_read_b128 v[184:187], v159
	ds_read_b128 v[188:191], v159 offset:1024
	ds_read_b128 v[192:195], v159 offset:2048
	ds_read_b128 v[196:199], v159 offset:3072
	ds_read_b128 v[200:203], v159 offset:4096
	ds_read_b128 v[204:207], v159 offset:5120
	ds_read_b128 v[208:211], v159 offset:6144
	ds_read_b128 v[212:215], v159 offset:7168
	global_load_lds_dwordx4 v136, s[34:35]
	s_add_i32 m0, s19, 0xe000
	s_nop 0
	global_load_lds_dwordx4 v138, s[34:35]
	s_waitcnt vmcnt(8)
	s_waitcnt lgkmcnt(0)
	s_barrier
	v_mfma_f32_16x16x32_bf16 v[124:127], v[144:147], v[184:187], v[124:127]
	v_mfma_f32_16x16x32_bf16 v[120:123], v[160:163], v[184:187], v[120:123]
	v_mfma_f32_16x16x32_bf16 v[108:111], v[144:147], v[192:195], v[108:111]
	v_mfma_f32_16x16x32_bf16 v[104:107], v[160:163], v[192:195], v[104:107]
	v_mfma_f32_16x16x32_bf16 v[92:95], v[144:147], v[200:203], v[92:95]
	v_mfma_f32_16x16x32_bf16 v[88:91], v[160:163], v[200:203], v[88:91]
	v_mfma_f32_16x16x32_bf16 v[76:79], v[144:147], v[208:211], v[76:79]
	v_mfma_f32_16x16x32_bf16 v[72:75], v[160:163], v[208:211], v[72:75]
	v_mfma_f32_16x16x32_bf16 v[124:127], v[148:151], v[188:191], v[124:127]
	v_mfma_f32_16x16x32_bf16 v[120:123], v[164:167], v[188:191], v[120:123]
	v_mfma_f32_16x16x32_bf16 v[108:111], v[148:151], v[196:199], v[108:111]
	v_mfma_f32_16x16x32_bf16 v[104:107], v[164:167], v[196:199], v[104:107]
	v_mfma_f32_16x16x32_bf16 v[92:95], v[148:151], v[204:207], v[92:95]
	v_mfma_f32_16x16x32_bf16 v[88:91], v[164:167], v[204:207], v[88:91]
	v_mfma_f32_16x16x32_bf16 v[76:79], v[148:151], v[212:215], v[76:79]
	v_mfma_f32_16x16x32_bf16 v[72:75], v[164:167], v[212:215], v[72:75]
	v_mfma_f32_16x16x32_bf16 v[116:119], v[168:171], v[184:187], v[116:119]
	v_mfma_f32_16x16x32_bf16 v[112:115], v[176:179], v[184:187], v[112:115]
	v_mfma_f32_16x16x32_bf16 v[100:103], v[168:171], v[192:195], v[100:103]
	v_mfma_f32_16x16x32_bf16 v[96:99], v[176:179], v[192:195], v[96:99]
	v_mfma_f32_16x16x32_bf16 v[84:87], v[168:171], v[200:203], v[84:87]
	v_mfma_f32_16x16x32_bf16 v[80:83], v[176:179], v[200:203], v[80:83]
	v_mfma_f32_16x16x32_bf16 v[68:71], v[168:171], v[208:211], v[68:71]
	v_mfma_f32_16x16x32_bf16 v[64:67], v[176:179], v[208:211], v[64:67]
	v_mfma_f32_16x16x32_bf16 v[116:119], v[172:175], v[188:191], v[116:119]
	v_mfma_f32_16x16x32_bf16 v[112:115], v[180:183], v[188:191], v[112:115]
	v_mfma_f32_16x16x32_bf16 v[100:103], v[172:175], v[196:199], v[100:103]
	v_mfma_f32_16x16x32_bf16 v[96:99], v[180:183], v[196:199], v[96:99]
	v_mfma_f32_16x16x32_bf16 v[84:87], v[172:175], v[204:207], v[84:87]
	v_mfma_f32_16x16x32_bf16 v[80:83], v[180:183], v[204:207], v[80:83]
	v_mfma_f32_16x16x32_bf16 v[68:71], v[172:175], v[212:215], v[68:71]
	v_mfma_f32_16x16x32_bf16 v[64:67], v[180:183], v[212:215], v[64:67]
	s_barrier
	s_add_i32 s3, s78, s18
	s_mov_b32 m0, s3
	ds_read_b128 v[184:187], v159 offset:16384
	ds_read_b128 v[188:191], v159 offset:17408
	ds_read_b128 v[192:195], v159 offset:18432
	ds_read_b128 v[196:199], v159 offset:19456
	ds_read_b128 v[200:203], v159 offset:20480
	ds_read_b128 v[204:207], v159 offset:21504
	ds_read_b128 v[208:211], v159 offset:22528
	ds_read_b128 v[212:215], v159 offset:23552
	global_load_lds_dwordx4 v130, s[88:89]
	s_add_i32 m0, s3, 0x2000
	s_add_u32 s42, s88, 0x20000
	s_addc_u32 s43, s89, 0
	s_add_i32 s3, s79, s18
	global_load_lds_dwordx4 v134, s[88:89]
	s_mov_b32 m0, s3
	s_nop 0
	global_load_lds_dwordx4 v130, s[42:43]
	s_add_i32 m0, s3, 0x2000
	s_nop 0
	global_load_lds_dwordx4 v134, s[42:43]
	s_mov_b32 m0, s19
	s_nop 0
	global_load_lds_dwordx4 v128, s[90:91]
	s_mov_b32 m0, s25
	s_nop 0
	global_load_lds_dwordx4 v132, s[90:91]
	s_waitcnt vmcnt(8)
	s_waitcnt lgkmcnt(0)
	s_barrier
	v_mfma_f32_16x16x32_bf16 v[60:63], v[144:147], v[184:187], v[60:63]
	v_mfma_f32_16x16x32_bf16 v[56:59], v[160:163], v[184:187], v[56:59]
	v_mfma_f32_16x16x32_bf16 v[44:47], v[144:147], v[192:195], v[44:47]
	v_mfma_f32_16x16x32_bf16 v[40:43], v[160:163], v[192:195], v[40:43]
	v_mfma_f32_16x16x32_bf16 v[28:31], v[144:147], v[200:203], v[28:31]
	v_mfma_f32_16x16x32_bf16 v[24:27], v[160:163], v[200:203], v[24:27]
	v_mfma_f32_16x16x32_bf16 v[12:15], v[144:147], v[208:211], v[12:15]
	v_mfma_f32_16x16x32_bf16 v[8:11], v[160:163], v[208:211], v[8:11]
	v_mfma_f32_16x16x32_bf16 v[60:63], v[148:151], v[188:191], v[60:63]
	v_mfma_f32_16x16x32_bf16 v[56:59], v[164:167], v[188:191], v[56:59]
	v_mfma_f32_16x16x32_bf16 v[44:47], v[148:151], v[196:199], v[44:47]
	v_mfma_f32_16x16x32_bf16 v[40:43], v[164:167], v[196:199], v[40:43]
	v_mfma_f32_16x16x32_bf16 v[28:31], v[148:151], v[204:207], v[28:31]
	v_mfma_f32_16x16x32_bf16 v[24:27], v[164:167], v[204:207], v[24:27]
	v_mfma_f32_16x16x32_bf16 v[12:15], v[148:151], v[212:215], v[12:15]
	v_mfma_f32_16x16x32_bf16 v[8:11], v[164:167], v[212:215], v[8:11]
	v_mfma_f32_16x16x32_bf16 v[52:55], v[168:171], v[184:187], v[52:55]
	v_mfma_f32_16x16x32_bf16 v[48:51], v[176:179], v[184:187], v[48:51]
	v_mfma_f32_16x16x32_bf16 v[36:39], v[168:171], v[192:195], v[36:39]
	v_mfma_f32_16x16x32_bf16 v[32:35], v[176:179], v[192:195], v[32:35]
	v_mfma_f32_16x16x32_bf16 v[20:23], v[168:171], v[200:203], v[20:23]
	v_mfma_f32_16x16x32_bf16 v[16:19], v[176:179], v[200:203], v[16:19]
	v_mfma_f32_16x16x32_bf16 v[4:7], v[168:171], v[208:211], v[4:7]
	v_mfma_f32_16x16x32_bf16 v[0:3], v[176:179], v[208:211], v[0:3]
	v_mfma_f32_16x16x32_bf16 v[52:55], v[172:175], v[188:191], v[52:55]
	v_mfma_f32_16x16x32_bf16 v[48:51], v[180:183], v[188:191], v[48:51]
	v_mfma_f32_16x16x32_bf16 v[36:39], v[172:175], v[196:199], v[36:39]
	v_mfma_f32_16x16x32_bf16 v[32:35], v[180:183], v[196:199], v[32:35]
	v_mfma_f32_16x16x32_bf16 v[20:23], v[172:175], v[204:207], v[20:23]
	v_mfma_f32_16x16x32_bf16 v[16:19], v[180:183], v[204:207], v[16:19]
	v_mfma_f32_16x16x32_bf16 v[4:7], v[172:175], v[212:215], v[4:7]
	v_mfma_f32_16x16x32_bf16 v[0:3], v[180:183], v[212:215], v[0:3]
	s_barrier
	s_add_i32 s3, 0, 0x18000
	s_add_i32 s44, 0, 0x1c000
	v_add_u32_e32 v164, s3, v155
	v_add_u32_e32 v180, s44, v155
	ds_read_b128 v[144:147], v164
	ds_read_b128 v[148:151], v164 offset:1024
	ds_read_b128 v[160:163], v164 offset:2048
	ds_read_b128 v[164:167], v164 offset:3072
	ds_read_b128 v[168:171], v180
	ds_read_b128 v[172:175], v180 offset:1024
	ds_read_b128 v[176:179], v180 offset:2048
	ds_read_b128 v[180:183], v180 offset:3072
	s_add_u32 s42, s90, 0x20000
	s_addc_u32 s43, s91, 0
	s_mov_b32 m0, s30
	ds_read_b128 v[184:187], v159 offset:32768
	ds_read_b128 v[188:191], v159 offset:33792
	ds_read_b128 v[192:195], v159 offset:34816
	ds_read_b128 v[196:199], v159 offset:35840
	ds_read_b128 v[200:203], v159 offset:36864
	ds_read_b128 v[204:207], v159 offset:37888
	ds_read_b128 v[208:211], v159 offset:38912
	ds_read_b128 v[212:215], v159 offset:39936
	global_load_lds_dwordx4 v128, s[42:43]
	v_lshl_add_u64 v[222:223], s[42:43], 0, v[132:133]
	s_mov_b32 m0, s31
	s_nop 0
	global_load_lds_dwordx4 v[222:223], off
	s_waitcnt vmcnt(8)
	s_waitcnt lgkmcnt(0)
	s_barrier
	v_mfma_f32_16x16x32_bf16 v[124:127], v[144:147], v[184:187], v[124:127]
	v_mfma_f32_16x16x32_bf16 v[120:123], v[160:163], v[184:187], v[120:123]
	v_mfma_f32_16x16x32_bf16 v[108:111], v[144:147], v[192:195], v[108:111]
	v_mfma_f32_16x16x32_bf16 v[104:107], v[160:163], v[192:195], v[104:107]
	v_mfma_f32_16x16x32_bf16 v[92:95], v[144:147], v[200:203], v[92:95]
	v_mfma_f32_16x16x32_bf16 v[88:91], v[160:163], v[200:203], v[88:91]
	v_mfma_f32_16x16x32_bf16 v[76:79], v[144:147], v[208:211], v[76:79]
	v_mfma_f32_16x16x32_bf16 v[72:75], v[160:163], v[208:211], v[72:75]
	v_mfma_f32_16x16x32_bf16 v[124:127], v[148:151], v[188:191], v[124:127]
	v_mfma_f32_16x16x32_bf16 v[120:123], v[164:167], v[188:191], v[120:123]
	v_mfma_f32_16x16x32_bf16 v[108:111], v[148:151], v[196:199], v[108:111]
	v_mfma_f32_16x16x32_bf16 v[104:107], v[164:167], v[196:199], v[104:107]
	v_mfma_f32_16x16x32_bf16 v[92:95], v[148:151], v[204:207], v[92:95]
	v_mfma_f32_16x16x32_bf16 v[88:91], v[164:167], v[204:207], v[88:91]
	v_mfma_f32_16x16x32_bf16 v[76:79], v[148:151], v[212:215], v[76:79]
	v_mfma_f32_16x16x32_bf16 v[72:75], v[164:167], v[212:215], v[72:75]
	v_mfma_f32_16x16x32_bf16 v[116:119], v[168:171], v[184:187], v[116:119]
	v_mfma_f32_16x16x32_bf16 v[112:115], v[176:179], v[184:187], v[112:115]
	v_mfma_f32_16x16x32_bf16 v[100:103], v[168:171], v[192:195], v[100:103]
	v_mfma_f32_16x16x32_bf16 v[96:99], v[176:179], v[192:195], v[96:99]
	v_mfma_f32_16x16x32_bf16 v[84:87], v[168:171], v[200:203], v[84:87]
	v_mfma_f32_16x16x32_bf16 v[80:83], v[176:179], v[200:203], v[80:83]
	v_mfma_f32_16x16x32_bf16 v[68:71], v[168:171], v[208:211], v[68:71]
	v_mfma_f32_16x16x32_bf16 v[64:67], v[176:179], v[208:211], v[64:67]
	v_mfma_f32_16x16x32_bf16 v[116:119], v[172:175], v[188:191], v[116:119]
	v_mfma_f32_16x16x32_bf16 v[112:115], v[180:183], v[188:191], v[112:115]
	v_mfma_f32_16x16x32_bf16 v[100:103], v[172:175], v[196:199], v[100:103]
	v_mfma_f32_16x16x32_bf16 v[96:99], v[180:183], v[196:199], v[96:99]
	v_mfma_f32_16x16x32_bf16 v[84:87], v[172:175], v[204:207], v[84:87]
	v_mfma_f32_16x16x32_bf16 v[80:83], v[180:183], v[204:207], v[80:83]
	v_mfma_f32_16x16x32_bf16 v[68:71], v[172:175], v[212:215], v[68:71]
	v_mfma_f32_16x16x32_bf16 v[64:67], v[180:183], v[212:215], v[64:67]
	s_barrier
	s_add_i32 s3, s3, s18
	s_add_u32 s42, s88, 0x80
	s_addc_u32 s43, s89, 0
	s_mov_b32 m0, s3
	ds_read_b128 v[184:187], v159 offset:49152
	ds_read_b128 v[188:191], v159 offset:50176
	ds_read_b128 v[192:195], v159 offset:51200
	ds_read_b128 v[196:199], v159 offset:52224
	ds_read_b128 v[200:203], v159 offset:53248
	ds_read_b128 v[204:207], v159 offset:54272
	ds_read_b128 v[208:211], v159 offset:55296
	ds_read_b128 v[212:215], v159 offset:56320
	global_load_lds_dwordx4 v130, s[42:43]
	s_add_i32 m0, s3, 0x2000
	s_add_i32 s3, s44, s18
	global_load_lds_dwordx4 v134, s[42:43]
	s_add_u32 s42, s42, 0x20000
	s_addc_u32 s43, s43, 0
	s_mov_b32 m0, s3
	s_nop 0
	global_load_lds_dwordx4 v130, s[42:43]
	s_add_i32 m0, s3, 0x2000
	s_nop 0
	global_load_lds_dwordx4 v134, s[42:43]
	s_add_u32 s90, s90, 0x80
	s_addc_u32 s91, s91, 0
	s_mov_b32 m0, s58
	s_nop 0
	global_load_lds_dwordx4 v128, s[90:91]
	s_mov_b32 m0, s59
	s_nop 0
	global_load_lds_dwordx4 v132, s[90:91]
	s_waitcnt vmcnt(8)
	s_waitcnt lgkmcnt(0)
	s_barrier
	v_mfma_f32_16x16x32_bf16 v[60:63], v[144:147], v[184:187], v[60:63]
	v_mfma_f32_16x16x32_bf16 v[56:59], v[160:163], v[184:187], v[56:59]
	v_mfma_f32_16x16x32_bf16 v[44:47], v[144:147], v[192:195], v[44:47]
	v_mfma_f32_16x16x32_bf16 v[40:43], v[160:163], v[192:195], v[40:43]
	v_mfma_f32_16x16x32_bf16 v[28:31], v[144:147], v[200:203], v[28:31]
	v_mfma_f32_16x16x32_bf16 v[24:27], v[160:163], v[200:203], v[24:27]
	v_mfma_f32_16x16x32_bf16 v[12:15], v[144:147], v[208:211], v[12:15]
	v_mfma_f32_16x16x32_bf16 v[8:11], v[160:163], v[208:211], v[8:11]
	v_mfma_f32_16x16x32_bf16 v[60:63], v[148:151], v[188:191], v[60:63]
	v_mfma_f32_16x16x32_bf16 v[56:59], v[164:167], v[188:191], v[56:59]
	v_mfma_f32_16x16x32_bf16 v[44:47], v[148:151], v[196:199], v[44:47]
	v_mfma_f32_16x16x32_bf16 v[40:43], v[164:167], v[196:199], v[40:43]
	v_mfma_f32_16x16x32_bf16 v[28:31], v[148:151], v[204:207], v[28:31]
	v_mfma_f32_16x16x32_bf16 v[24:27], v[164:167], v[204:207], v[24:27]
	v_mfma_f32_16x16x32_bf16 v[12:15], v[148:151], v[212:215], v[12:15]
	v_mfma_f32_16x16x32_bf16 v[8:11], v[164:167], v[212:215], v[8:11]
	v_mfma_f32_16x16x32_bf16 v[52:55], v[168:171], v[184:187], v[52:55]
	v_mfma_f32_16x16x32_bf16 v[48:51], v[176:179], v[184:187], v[48:51]
	v_mfma_f32_16x16x32_bf16 v[36:39], v[168:171], v[192:195], v[36:39]
	v_mfma_f32_16x16x32_bf16 v[32:35], v[176:179], v[192:195], v[32:35]
	v_mfma_f32_16x16x32_bf16 v[20:23], v[168:171], v[200:203], v[20:23]
	v_mfma_f32_16x16x32_bf16 v[16:19], v[176:179], v[200:203], v[16:19]
	v_mfma_f32_16x16x32_bf16 v[4:7], v[168:171], v[208:211], v[4:7]
	v_mfma_f32_16x16x32_bf16 v[0:3], v[176:179], v[208:211], v[0:3]
	v_mfma_f32_16x16x32_bf16 v[52:55], v[172:175], v[188:191], v[52:55]
	v_mfma_f32_16x16x32_bf16 v[48:51], v[180:183], v[188:191], v[48:51]
	v_mfma_f32_16x16x32_bf16 v[36:39], v[172:175], v[196:199], v[36:39]
	v_mfma_f32_16x16x32_bf16 v[32:35], v[180:183], v[196:199], v[32:35]
	v_mfma_f32_16x16x32_bf16 v[20:23], v[172:175], v[204:207], v[20:23]
	v_mfma_f32_16x16x32_bf16 v[16:19], v[180:183], v[204:207], v[16:19]
	v_mfma_f32_16x16x32_bf16 v[4:7], v[172:175], v[212:215], v[4:7]
	v_mfma_f32_16x16x32_bf16 v[0:3], v[180:183], v[212:215], v[0:3]
	s_barrier
	s_add_i32 s37, s37, 2
	s_add_u32 s34, s34, 0x100
	s_addc_u32 s35, s35, 0
	s_add_u32 s33, s33, 0x100
	s_addc_u32 s36, s36, 0
	s_cmp_gt_u32 s37, 5
	s_cbranch_scc0 .LBB0_563
	s_and_b64 vcc, exec, s[14:15]
	s_cbranch_vccz .LBB0_566
	s_barrier

.LBB0_639:
	ds_read_b128 v[140:143], v149
	ds_read_b128 v[152:155], v149 offset:1024
	ds_read_b128 v[156:159], v149 offset:2048
	ds_read_b128 v[160:163], v149 offset:3072
	ds_read_b128 v[164:167], v150
	ds_read_b128 v[168:171], v150 offset:1024
	ds_read_b128 v[172:175], v150 offset:2048
	ds_read_b128 v[176:179], v150 offset:3072
	s_add_u32 s3, s86, 0xfff80080
	s_addc_u32 s33, s87, -1
	s_cmp_eq_u32 s27, 28
	s_cselect_b32 s91, s0, s33
	s_cselect_b32 s90, s1, s3
	s_cselect_b32 s89, s15, s24
	s_cselect_b32 s88, s17, s19
	s_add_i32 m0, s30, 0xc000
	ds_read_b128 v[180:183], v151
	ds_read_b128 v[184:187], v151 offset:1024
	ds_read_b128 v[188:191], v151 offset:2048
	ds_read_b128 v[192:195], v151 offset:3072
	ds_read_b128 v[196:199], v151 offset:4096
	ds_read_b128 v[200:203], v151 offset:5120
	ds_read_b128 v[204:207], v151 offset:6144
	ds_read_b128 v[208:211], v151 offset:7168
	global_load_lds_dwordx4 v132, s[86:87]
	s_add_i32 m0, s30, 0xe000
	s_nop 0
	global_load_lds_dwordx4 v134, s[86:87]
	s_waitcnt vmcnt(8)
	s_waitcnt lgkmcnt(0)
	s_barrier
	v_mfma_f32_16x16x32_bf16 v[124:127], v[140:143], v[180:183], v[124:127]
	v_mfma_f32_16x16x32_bf16 v[120:123], v[156:159], v[180:183], v[120:123]
	v_mfma_f32_16x16x32_bf16 v[108:111], v[140:143], v[188:191], v[108:111]
	v_mfma_f32_16x16x32_bf16 v[104:107], v[156:159], v[188:191], v[104:107]
	v_mfma_f32_16x16x32_bf16 v[92:95], v[140:143], v[196:199], v[92:95]
	v_mfma_f32_16x16x32_bf16 v[88:91], v[156:159], v[196:199], v[88:91]
	v_mfma_f32_16x16x32_bf16 v[76:79], v[140:143], v[204:207], v[76:79]
	v_mfma_f32_16x16x32_bf16 v[72:75], v[156:159], v[204:207], v[72:75]
	v_mfma_f32_16x16x32_bf16 v[124:127], v[152:155], v[184:187], v[124:127]
	v_mfma_f32_16x16x32_bf16 v[120:123], v[160:163], v[184:187], v[120:123]
	v_mfma_f32_16x16x32_bf16 v[108:111], v[152:155], v[192:195], v[108:111]
	v_mfma_f32_16x16x32_bf16 v[104:107], v[160:163], v[192:195], v[104:107]
	v_mfma_f32_16x16x32_bf16 v[92:95], v[152:155], v[200:203], v[92:95]
	v_mfma_f32_16x16x32_bf16 v[88:91], v[160:163], v[200:203], v[88:91]
	v_mfma_f32_16x16x32_bf16 v[76:79], v[152:155], v[208:211], v[76:79]
	v_mfma_f32_16x16x32_bf16 v[72:75], v[160:163], v[208:211], v[72:75]
	v_mfma_f32_16x16x32_bf16 v[116:119], v[164:167], v[180:183], v[116:119]
	v_mfma_f32_16x16x32_bf16 v[112:115], v[172:175], v[180:183], v[112:115]
	v_mfma_f32_16x16x32_bf16 v[100:103], v[164:167], v[188:191], v[100:103]
	v_mfma_f32_16x16x32_bf16 v[96:99], v[172:175], v[188:191], v[96:99]
	v_mfma_f32_16x16x32_bf16 v[84:87], v[164:167], v[196:199], v[84:87]
	v_mfma_f32_16x16x32_bf16 v[80:83], v[172:175], v[196:199], v[80:83]
	v_mfma_f32_16x16x32_bf16 v[68:71], v[164:167], v[204:207], v[68:71]
	v_mfma_f32_16x16x32_bf16 v[64:67], v[172:175], v[204:207], v[64:67]
	v_mfma_f32_16x16x32_bf16 v[116:119], v[168:171], v[184:187], v[116:119]
	v_mfma_f32_16x16x32_bf16 v[112:115], v[176:179], v[184:187], v[112:115]
	v_mfma_f32_16x16x32_bf16 v[100:103], v[168:171], v[192:195], v[100:103]
	v_mfma_f32_16x16x32_bf16 v[96:99], v[176:179], v[192:195], v[96:99]
	v_mfma_f32_16x16x32_bf16 v[84:87], v[168:171], v[200:203], v[84:87]
	v_mfma_f32_16x16x32_bf16 v[80:83], v[176:179], v[200:203], v[80:83]
	v_mfma_f32_16x16x32_bf16 v[68:71], v[168:171], v[208:211], v[68:71]
	v_mfma_f32_16x16x32_bf16 v[64:67], v[176:179], v[208:211], v[64:67]
	s_barrier
	s_add_i32 s3, s59, s25
	s_mov_b32 m0, s3
	ds_read_b128 v[180:183], v151 offset:16384
	ds_read_b128 v[184:187], v151 offset:17408
	ds_read_b128 v[188:191], v151 offset:18432
	ds_read_b128 v[192:195], v151 offset:19456
	ds_read_b128 v[196:199], v151 offset:20480
	ds_read_b128 v[200:203], v151 offset:21504
	ds_read_b128 v[204:207], v151 offset:22528
	ds_read_b128 v[208:211], v151 offset:23552
	global_load_lds_dwordx4 v128, s[88:89]
	s_add_i32 m0, s3, 0x2000
	s_add_u32 s36, s88, 0x80000
	s_addc_u32 s37, s89, 0
	s_add_i32 s3, s68, s25
	global_load_lds_dwordx4 v130, s[88:89]
	s_mov_b32 m0, s3
	s_nop 0
	global_load_lds_dwordx4 v128, s[36:37]
	s_add_i32 m0, s3, 0x2000
	s_nop 0
	global_load_lds_dwordx4 v130, s[36:37]
	s_mov_b32 m0, s30
	s_nop 0
	global_load_lds_dwordx4 v128, s[90:91]
	s_mov_b32 m0, s31
	s_nop 0
	global_load_lds_dwordx4 v130, s[90:91]
	s_waitcnt vmcnt(8)
	s_waitcnt lgkmcnt(0)
	s_barrier
	v_mfma_f32_16x16x32_bf16 v[60:63], v[140:143], v[180:183], v[60:63]
	v_mfma_f32_16x16x32_bf16 v[56:59], v[156:159], v[180:183], v[56:59]
	v_mfma_f32_16x16x32_bf16 v[44:47], v[140:143], v[188:191], v[44:47]
	v_mfma_f32_16x16x32_bf16 v[40:43], v[156:159], v[188:191], v[40:43]
	v_mfma_f32_16x16x32_bf16 v[28:31], v[140:143], v[196:199], v[28:31]
	v_mfma_f32_16x16x32_bf16 v[24:27], v[156:159], v[196:199], v[24:27]
	v_mfma_f32_16x16x32_bf16 v[12:15], v[140:143], v[204:207], v[12:15]
	v_mfma_f32_16x16x32_bf16 v[8:11], v[156:159], v[204:207], v[8:11]
	v_mfma_f32_16x16x32_bf16 v[60:63], v[152:155], v[184:187], v[60:63]
	v_mfma_f32_16x16x32_bf16 v[56:59], v[160:163], v[184:187], v[56:59]
	v_mfma_f32_16x16x32_bf16 v[44:47], v[152:155], v[192:195], v[44:47]
	v_mfma_f32_16x16x32_bf16 v[40:43], v[160:163], v[192:195], v[40:43]
	v_mfma_f32_16x16x32_bf16 v[28:31], v[152:155], v[200:203], v[28:31]
	v_mfma_f32_16x16x32_bf16 v[24:27], v[160:163], v[200:203], v[24:27]
	v_mfma_f32_16x16x32_bf16 v[12:15], v[152:155], v[208:211], v[12:15]
	v_mfma_f32_16x16x32_bf16 v[8:11], v[160:163], v[208:211], v[8:11]
	v_mfma_f32_16x16x32_bf16 v[52:55], v[164:167], v[180:183], v[52:55]
	v_mfma_f32_16x16x32_bf16 v[48:51], v[172:175], v[180:183], v[48:51]
	v_mfma_f32_16x16x32_bf16 v[36:39], v[164:167], v[188:191], v[36:39]
	v_mfma_f32_16x16x32_bf16 v[32:35], v[172:175], v[188:191], v[32:35]
	v_mfma_f32_16x16x32_bf16 v[20:23], v[164:167], v[196:199], v[20:23]
	v_mfma_f32_16x16x32_bf16 v[16:19], v[172:175], v[196:199], v[16:19]
	v_mfma_f32_16x16x32_bf16 v[4:7], v[164:167], v[204:207], v[4:7]
	v_mfma_f32_16x16x32_bf16 v[0:3], v[172:175], v[204:207], v[0:3]
	v_mfma_f32_16x16x32_bf16 v[52:55], v[168:171], v[184:187], v[52:55]
	v_mfma_f32_16x16x32_bf16 v[48:51], v[176:179], v[184:187], v[48:51]
	v_mfma_f32_16x16x32_bf16 v[36:39], v[168:171], v[192:195], v[36:39]
	v_mfma_f32_16x16x32_bf16 v[32:35], v[176:179], v[192:195], v[32:35]
	v_mfma_f32_16x16x32_bf16 v[20:23], v[168:171], v[200:203], v[20:23]
	v_mfma_f32_16x16x32_bf16 v[16:19], v[176:179], v[200:203], v[16:19]
	v_mfma_f32_16x16x32_bf16 v[4:7], v[168:171], v[208:211], v[4:7]
	v_mfma_f32_16x16x32_bf16 v[0:3], v[176:179], v[208:211], v[0:3]
	s_barrier
	s_add_i32 s3, 0, 0x18000
	s_add_i32 s33, 0, 0x1c000
	v_add_u32_e32 v160, s3, v147
	v_add_u32_e32 v176, s33, v147
	ds_read_b128 v[140:143], v160
	ds_read_b128 v[152:155], v160 offset:1024
	ds_read_b128 v[156:159], v160 offset:2048
	ds_read_b128 v[160:163], v160 offset:3072
	ds_read_b128 v[164:167], v176
	ds_read_b128 v[168:171], v176 offset:1024
	ds_read_b128 v[172:175], v176 offset:2048
	ds_read_b128 v[176:179], v176 offset:3072
	s_add_u32 s36, s90, 0x80000
	s_addc_u32 s37, s91, 0
	s_mov_b32 m0, s48
	ds_read_b128 v[180:183], v151 offset:32768
	ds_read_b128 v[184:187], v151 offset:33792
	ds_read_b128 v[188:191], v151 offset:34816
	ds_read_b128 v[192:195], v151 offset:35840
	ds_read_b128 v[196:199], v151 offset:36864
	ds_read_b128 v[200:203], v151 offset:37888
	ds_read_b128 v[204:207], v151 offset:38912
	ds_read_b128 v[208:211], v151 offset:39936
	global_load_lds_dwordx4 v128, s[36:37]
	v_lshl_add_u64 v[218:219], s[36:37], 0, v[130:131]
	s_mov_b32 m0, s49
	s_nop 0
	global_load_lds_dwordx4 v[218:219], off
	s_waitcnt vmcnt(8)
	s_waitcnt lgkmcnt(0)
	s_barrier
	v_mfma_f32_16x16x32_bf16 v[124:127], v[140:143], v[180:183], v[124:127]
	v_mfma_f32_16x16x32_bf16 v[120:123], v[156:159], v[180:183], v[120:123]
	v_mfma_f32_16x16x32_bf16 v[108:111], v[140:143], v[188:191], v[108:111]
	v_mfma_f32_16x16x32_bf16 v[104:107], v[156:159], v[188:191], v[104:107]
	v_mfma_f32_16x16x32_bf16 v[92:95], v[140:143], v[196:199], v[92:95]
	v_mfma_f32_16x16x32_bf16 v[88:91], v[156:159], v[196:199], v[88:91]
	v_mfma_f32_16x16x32_bf16 v[76:79], v[140:143], v[204:207], v[76:79]
	v_mfma_f32_16x16x32_bf16 v[72:75], v[156:159], v[204:207], v[72:75]
	v_mfma_f32_16x16x32_bf16 v[124:127], v[152:155], v[184:187], v[124:127]
	v_mfma_f32_16x16x32_bf16 v[120:123], v[160:163], v[184:187], v[120:123]
	v_mfma_f32_16x16x32_bf16 v[108:111], v[152:155], v[192:195], v[108:111]
	v_mfma_f32_16x16x32_bf16 v[104:107], v[160:163], v[192:195], v[104:107]
	v_mfma_f32_16x16x32_bf16 v[92:95], v[152:155], v[200:203], v[92:95]
	v_mfma_f32_16x16x32_bf16 v[88:91], v[160:163], v[200:203], v[88:91]
	v_mfma_f32_16x16x32_bf16 v[76:79], v[152:155], v[208:211], v[76:79]
	v_mfma_f32_16x16x32_bf16 v[72:75], v[160:163], v[208:211], v[72:75]
	v_mfma_f32_16x16x32_bf16 v[116:119], v[164:167], v[180:183], v[116:119]
	v_mfma_f32_16x16x32_bf16 v[112:115], v[172:175], v[180:183], v[112:115]
	v_mfma_f32_16x16x32_bf16 v[100:103], v[164:167], v[188:191], v[100:103]
	v_mfma_f32_16x16x32_bf16 v[96:99], v[172:175], v[188:191], v[96:99]
	v_mfma_f32_16x16x32_bf16 v[84:87], v[164:167], v[196:199], v[84:87]
	v_mfma_f32_16x16x32_bf16 v[80:83], v[172:175], v[196:199], v[80:83]
	v_mfma_f32_16x16x32_bf16 v[68:71], v[164:167], v[204:207], v[68:71]
	v_mfma_f32_16x16x32_bf16 v[64:67], v[172:175], v[204:207], v[64:67]
	v_mfma_f32_16x16x32_bf16 v[116:119], v[168:171], v[184:187], v[116:119]
	v_mfma_f32_16x16x32_bf16 v[112:115], v[176:179], v[184:187], v[112:115]
	v_mfma_f32_16x16x32_bf16 v[100:103], v[168:171], v[192:195], v[100:103]
	v_mfma_f32_16x16x32_bf16 v[96:99], v[176:179], v[192:195], v[96:99]
	v_mfma_f32_16x16x32_bf16 v[84:87], v[168:171], v[200:203], v[84:87]
	v_mfma_f32_16x16x32_bf16 v[80:83], v[176:179], v[200:203], v[80:83]
	v_mfma_f32_16x16x32_bf16 v[68:71], v[168:171], v[208:211], v[68:71]
	v_mfma_f32_16x16x32_bf16 v[64:67], v[176:179], v[208:211], v[64:67]
	s_barrier
	s_add_i32 s3, s3, s25
	s_add_u32 s36, s88, 0x80
	s_addc_u32 s37, s89, 0
	s_mov_b32 m0, s3
	ds_read_b128 v[180:183], v151 offset:49152
	ds_read_b128 v[184:187], v151 offset:50176
	ds_read_b128 v[188:191], v151 offset:51200
	ds_read_b128 v[192:195], v151 offset:52224
	ds_read_b128 v[196:199], v151 offset:53248
	ds_read_b128 v[200:203], v151 offset:54272
	ds_read_b128 v[204:207], v151 offset:55296
	ds_read_b128 v[208:211], v151 offset:56320
	global_load_lds_dwordx4 v128, s[36:37]
	s_add_i32 m0, s3, 0x2000
	s_add_i32 s3, s33, s25
	global_load_lds_dwordx4 v130, s[36:37]
	s_add_u32 s36, s36, 0x80000
	s_addc_u32 s37, s37, 0
	s_mov_b32 m0, s3
	s_nop 0
	global_load_lds_dwordx4 v128, s[36:37]
	s_add_i32 m0, s3, 0x2000
	s_nop 0
	global_load_lds_dwordx4 v130, s[36:37]
	s_add_u32 s90, s90, 0x80
	s_addc_u32 s91, s91, 0
	s_mov_b32 m0, s57
	s_nop 0
	global_load_lds_dwordx4 v128, s[90:91]
	s_mov_b32 m0, s58
	s_nop 0
	global_load_lds_dwordx4 v130, s[90:91]
	s_waitcnt vmcnt(8)
	s_waitcnt lgkmcnt(0)
	s_barrier
	v_mfma_f32_16x16x32_bf16 v[60:63], v[140:143], v[180:183], v[60:63]
	v_mfma_f32_16x16x32_bf16 v[56:59], v[156:159], v[180:183], v[56:59]
	v_mfma_f32_16x16x32_bf16 v[44:47], v[140:143], v[188:191], v[44:47]
	v_mfma_f32_16x16x32_bf16 v[40:43], v[156:159], v[188:191], v[40:43]
	v_mfma_f32_16x16x32_bf16 v[28:31], v[140:143], v[196:199], v[28:31]
	v_mfma_f32_16x16x32_bf16 v[24:27], v[156:159], v[196:199], v[24:27]
	v_mfma_f32_16x16x32_bf16 v[12:15], v[140:143], v[204:207], v[12:15]
	v_mfma_f32_16x16x32_bf16 v[8:11], v[156:159], v[204:207], v[8:11]
	v_mfma_f32_16x16x32_bf16 v[60:63], v[152:155], v[184:187], v[60:63]
	v_mfma_f32_16x16x32_bf16 v[56:59], v[160:163], v[184:187], v[56:59]
	v_mfma_f32_16x16x32_bf16 v[44:47], v[152:155], v[192:195], v[44:47]
	v_mfma_f32_16x16x32_bf16 v[40:43], v[160:163], v[192:195], v[40:43]
	v_mfma_f32_16x16x32_bf16 v[28:31], v[152:155], v[200:203], v[28:31]
	v_mfma_f32_16x16x32_bf16 v[24:27], v[160:163], v[200:203], v[24:27]
	v_mfma_f32_16x16x32_bf16 v[12:15], v[152:155], v[208:211], v[12:15]
	v_mfma_f32_16x16x32_bf16 v[8:11], v[160:163], v[208:211], v[8:11]
	v_mfma_f32_16x16x32_bf16 v[52:55], v[164:167], v[180:183], v[52:55]
	v_mfma_f32_16x16x32_bf16 v[48:51], v[172:175], v[180:183], v[48:51]
	v_mfma_f32_16x16x32_bf16 v[36:39], v[164:167], v[188:191], v[36:39]
	v_mfma_f32_16x16x32_bf16 v[32:35], v[172:175], v[188:191], v[32:35]
	v_mfma_f32_16x16x32_bf16 v[20:23], v[164:167], v[196:199], v[20:23]
	v_mfma_f32_16x16x32_bf16 v[16:19], v[172:175], v[196:199], v[16:19]
	v_mfma_f32_16x16x32_bf16 v[4:7], v[164:167], v[204:207], v[4:7]
	v_mfma_f32_16x16x32_bf16 v[0:3], v[172:175], v[204:207], v[0:3]
	v_mfma_f32_16x16x32_bf16 v[52:55], v[168:171], v[184:187], v[52:55]
	v_mfma_f32_16x16x32_bf16 v[48:51], v[176:179], v[184:187], v[48:51]
	v_mfma_f32_16x16x32_bf16 v[36:39], v[168:171], v[192:195], v[36:39]
	v_mfma_f32_16x16x32_bf16 v[32:35], v[176:179], v[192:195], v[32:35]
	v_mfma_f32_16x16x32_bf16 v[20:23], v[168:171], v[200:203], v[20:23]
	v_mfma_f32_16x16x32_bf16 v[16:19], v[176:179], v[200:203], v[16:19]
	v_mfma_f32_16x16x32_bf16 v[4:7], v[168:171], v[208:211], v[4:7]
	v_mfma_f32_16x16x32_bf16 v[0:3], v[176:179], v[208:211], v[0:3]
	s_barrier
	s_add_i32 s27, s27, 2
	s_add_u32 s86, s86, 0x100
	s_addc_u32 s87, s87, 0
	s_add_u32 s19, s19, 0x100
	s_addc_u32 s24, s24, 0
	s_cmp_gt_u32 s27, 29
	s_cbranch_scc0 .LBB0_639
	s_and_b64 vcc, exec, s[12:13]
	s_cbranch_vccz .LBB0_642
	s_barrier

.LBB0_770:
	ds_read_b128 v[154:157], v150
	ds_read_b128 v[158:161], v150 offset:1024
	ds_read_b128 v[162:165], v150 offset:2048
	ds_read_b128 v[166:169], v150 offset:3072
	ds_read_b128 v[170:173], v151
	ds_read_b128 v[174:177], v151 offset:1024
	ds_read_b128 v[178:181], v151 offset:2048
	ds_read_b128 v[182:185], v151 offset:3072
	s_add_u32 s3, s88, 0xfff80080
	s_addc_u32 s37, s89, -1
	s_cmp_eq_u32 s36, 28
	s_cselect_b32 s91, s0, s37
	s_cselect_b32 s90, s1, s3
	s_cselect_b32 s81, s17, s35
	s_cselect_b32 s80, s27, s33
	s_add_i32 m0, s19, 0xc000
	ds_read_b128 v[186:189], v152
	ds_read_b128 v[190:193], v152 offset:1024
	ds_read_b128 v[194:197], v152 offset:2048
	ds_read_b128 v[198:201], v152 offset:3072
	ds_read_b128 v[202:205], v152 offset:4096
	ds_read_b128 v[206:209], v152 offset:5120
	ds_read_b128 v[210:213], v152 offset:6144
	ds_read_b128 v[214:217], v152 offset:7168
	global_load_lds_dwordx4 v138, s[88:89]
	s_add_i32 m0, s19, 0xe000
	s_nop 0
	global_load_lds_dwordx4 v140, s[88:89]
	s_waitcnt vmcnt(8)
	s_waitcnt lgkmcnt(0)
	s_barrier
	v_mfma_f32_16x16x32_bf16 v[124:127], v[154:157], v[186:189], v[124:127]
	v_mfma_f32_16x16x32_bf16 v[120:123], v[162:165], v[186:189], v[120:123]
	v_mfma_f32_16x16x32_bf16 v[108:111], v[154:157], v[194:197], v[108:111]
	v_mfma_f32_16x16x32_bf16 v[104:107], v[162:165], v[194:197], v[104:107]
	v_mfma_f32_16x16x32_bf16 v[92:95], v[154:157], v[202:205], v[92:95]
	v_mfma_f32_16x16x32_bf16 v[88:91], v[162:165], v[202:205], v[88:91]
	v_mfma_f32_16x16x32_bf16 v[76:79], v[154:157], v[210:213], v[76:79]
	v_mfma_f32_16x16x32_bf16 v[72:75], v[162:165], v[210:213], v[72:75]
	v_mfma_f32_16x16x32_bf16 v[124:127], v[158:161], v[190:193], v[124:127]
	v_mfma_f32_16x16x32_bf16 v[120:123], v[166:169], v[190:193], v[120:123]
	v_mfma_f32_16x16x32_bf16 v[108:111], v[158:161], v[198:201], v[108:111]
	v_mfma_f32_16x16x32_bf16 v[104:107], v[166:169], v[198:201], v[104:107]
	v_mfma_f32_16x16x32_bf16 v[92:95], v[158:161], v[206:209], v[92:95]
	v_mfma_f32_16x16x32_bf16 v[88:91], v[166:169], v[206:209], v[88:91]
	v_mfma_f32_16x16x32_bf16 v[76:79], v[158:161], v[214:217], v[76:79]
	v_mfma_f32_16x16x32_bf16 v[72:75], v[166:169], v[214:217], v[72:75]
	v_mfma_f32_16x16x32_bf16 v[116:119], v[170:173], v[186:189], v[116:119]
	v_mfma_f32_16x16x32_bf16 v[112:115], v[178:181], v[186:189], v[112:115]
	v_mfma_f32_16x16x32_bf16 v[100:103], v[170:173], v[194:197], v[100:103]
	v_mfma_f32_16x16x32_bf16 v[96:99], v[178:181], v[194:197], v[96:99]
	v_mfma_f32_16x16x32_bf16 v[84:87], v[170:173], v[202:205], v[84:87]
	v_mfma_f32_16x16x32_bf16 v[80:83], v[178:181], v[202:205], v[80:83]
	v_mfma_f32_16x16x32_bf16 v[68:71], v[170:173], v[210:213], v[68:71]
	v_mfma_f32_16x16x32_bf16 v[64:67], v[178:181], v[210:213], v[64:67]
	v_mfma_f32_16x16x32_bf16 v[116:119], v[174:177], v[190:193], v[116:119]
	v_mfma_f32_16x16x32_bf16 v[112:115], v[182:185], v[190:193], v[112:115]
	v_mfma_f32_16x16x32_bf16 v[100:103], v[174:177], v[198:201], v[100:103]
	v_mfma_f32_16x16x32_bf16 v[96:99], v[182:185], v[198:201], v[96:99]
	v_mfma_f32_16x16x32_bf16 v[84:87], v[174:177], v[206:209], v[84:87]
	v_mfma_f32_16x16x32_bf16 v[80:83], v[182:185], v[206:209], v[80:83]
	v_mfma_f32_16x16x32_bf16 v[68:71], v[174:177], v[214:217], v[68:71]
	v_mfma_f32_16x16x32_bf16 v[64:67], v[182:185], v[214:217], v[64:67]
	s_barrier
	s_add_i32 s3, s56, s18
	s_mov_b32 m0, s3
	ds_read_b128 v[186:189], v152 offset:16384
	ds_read_b128 v[190:193], v152 offset:17408
	ds_read_b128 v[194:197], v152 offset:18432
	ds_read_b128 v[198:201], v152 offset:19456
	ds_read_b128 v[202:205], v152 offset:20480
	ds_read_b128 v[206:209], v152 offset:21504
	ds_read_b128 v[210:213], v152 offset:22528
	ds_read_b128 v[214:217], v152 offset:23552
	global_load_lds_dwordx4 v130, s[80:81]
	s_add_i32 m0, s3, 0x2000
	s_add_u32 s42, s80, 0x80000
	s_addc_u32 s43, s81, 0
	s_add_i32 s3, s57, s18
	global_load_lds_dwordx4 v134, s[80:81]
	s_mov_b32 m0, s3
	s_nop 0
	global_load_lds_dwordx4 v130, s[42:43]
	s_add_i32 m0, s3, 0x2000
	s_nop 0
	global_load_lds_dwordx4 v134, s[42:43]
	s_mov_b32 m0, s19
	s_nop 0
	global_load_lds_dwordx4 v128, s[90:91]
	s_mov_b32 m0, s25
	s_nop 0
	global_load_lds_dwordx4 v132, s[90:91]
	s_waitcnt vmcnt(8)
	s_waitcnt lgkmcnt(0)
	s_barrier
	v_mfma_f32_16x16x32_bf16 v[60:63], v[154:157], v[186:189], v[60:63]
	v_mfma_f32_16x16x32_bf16 v[56:59], v[162:165], v[186:189], v[56:59]
	v_mfma_f32_16x16x32_bf16 v[44:47], v[154:157], v[194:197], v[44:47]
	v_mfma_f32_16x16x32_bf16 v[40:43], v[162:165], v[194:197], v[40:43]
	v_mfma_f32_16x16x32_bf16 v[28:31], v[154:157], v[202:205], v[28:31]
	v_mfma_f32_16x16x32_bf16 v[24:27], v[162:165], v[202:205], v[24:27]
	v_mfma_f32_16x16x32_bf16 v[12:15], v[154:157], v[210:213], v[12:15]
	v_mfma_f32_16x16x32_bf16 v[8:11], v[162:165], v[210:213], v[8:11]
	v_mfma_f32_16x16x32_bf16 v[60:63], v[158:161], v[190:193], v[60:63]
	v_mfma_f32_16x16x32_bf16 v[56:59], v[166:169], v[190:193], v[56:59]
	v_mfma_f32_16x16x32_bf16 v[44:47], v[158:161], v[198:201], v[44:47]
	v_mfma_f32_16x16x32_bf16 v[40:43], v[166:169], v[198:201], v[40:43]
	v_mfma_f32_16x16x32_bf16 v[28:31], v[158:161], v[206:209], v[28:31]
	v_mfma_f32_16x16x32_bf16 v[24:27], v[166:169], v[206:209], v[24:27]
	v_mfma_f32_16x16x32_bf16 v[12:15], v[158:161], v[214:217], v[12:15]
	v_mfma_f32_16x16x32_bf16 v[8:11], v[166:169], v[214:217], v[8:11]
	v_mfma_f32_16x16x32_bf16 v[52:55], v[170:173], v[186:189], v[52:55]
	v_mfma_f32_16x16x32_bf16 v[48:51], v[178:181], v[186:189], v[48:51]
	v_mfma_f32_16x16x32_bf16 v[36:39], v[170:173], v[194:197], v[36:39]
	v_mfma_f32_16x16x32_bf16 v[32:35], v[178:181], v[194:197], v[32:35]
	v_mfma_f32_16x16x32_bf16 v[20:23], v[170:173], v[202:205], v[20:23]
	v_mfma_f32_16x16x32_bf16 v[16:19], v[178:181], v[202:205], v[16:19]
	v_mfma_f32_16x16x32_bf16 v[4:7], v[170:173], v[210:213], v[4:7]
	v_mfma_f32_16x16x32_bf16 v[0:3], v[178:181], v[210:213], v[0:3]
	v_mfma_f32_16x16x32_bf16 v[52:55], v[174:177], v[190:193], v[52:55]
	v_mfma_f32_16x16x32_bf16 v[48:51], v[182:185], v[190:193], v[48:51]
	v_mfma_f32_16x16x32_bf16 v[36:39], v[174:177], v[198:201], v[36:39]
	v_mfma_f32_16x16x32_bf16 v[32:35], v[182:185], v[198:201], v[32:35]
	v_mfma_f32_16x16x32_bf16 v[20:23], v[174:177], v[206:209], v[20:23]
	v_mfma_f32_16x16x32_bf16 v[16:19], v[182:185], v[206:209], v[16:19]
	v_mfma_f32_16x16x32_bf16 v[4:7], v[174:177], v[214:217], v[4:7]
	v_mfma_f32_16x16x32_bf16 v[0:3], v[182:185], v[214:217], v[0:3]
	s_barrier
	s_add_i32 s3, 0, 0x18000
	v_add_u32_e32 v153, s3, v149
	s_add_i32 s37, 0, 0x1c000
	ds_read_b128 v[154:157], v153
	ds_read_b128 v[158:161], v153 offset:1024
	ds_read_b128 v[162:165], v153 offset:2048
	ds_read_b128 v[166:169], v153 offset:3072
	v_add_u32_e32 v153, s37, v149
	ds_read_b128 v[170:173], v153
	ds_read_b128 v[174:177], v153 offset:1024
	ds_read_b128 v[178:181], v153 offset:2048
	ds_read_b128 v[182:185], v153 offset:3072
	s_add_u32 s42, s90, 0x80000
	s_addc_u32 s43, s91, 0
	s_mov_b32 m0, s30
	ds_read_b128 v[186:189], v152 offset:32768
	ds_read_b128 v[190:193], v152 offset:33792
	ds_read_b128 v[194:197], v152 offset:34816
	ds_read_b128 v[198:201], v152 offset:35840
	ds_read_b128 v[202:205], v152 offset:36864
	ds_read_b128 v[206:209], v152 offset:37888
	ds_read_b128 v[210:213], v152 offset:38912
	ds_read_b128 v[214:217], v152 offset:39936
	global_load_lds_dwordx4 v128, s[42:43]
	v_lshl_add_u64 v[224:225], s[42:43], 0, v[132:133]
	s_mov_b32 m0, s31
	s_nop 0
	global_load_lds_dwordx4 v[224:225], off
	s_waitcnt vmcnt(8)
	s_waitcnt lgkmcnt(0)
	s_barrier
	v_mfma_f32_16x16x32_bf16 v[124:127], v[154:157], v[186:189], v[124:127]
	v_mfma_f32_16x16x32_bf16 v[120:123], v[162:165], v[186:189], v[120:123]
	v_mfma_f32_16x16x32_bf16 v[108:111], v[154:157], v[194:197], v[108:111]
	v_mfma_f32_16x16x32_bf16 v[104:107], v[162:165], v[194:197], v[104:107]
	v_mfma_f32_16x16x32_bf16 v[92:95], v[154:157], v[202:205], v[92:95]
	v_mfma_f32_16x16x32_bf16 v[88:91], v[162:165], v[202:205], v[88:91]
	v_mfma_f32_16x16x32_bf16 v[76:79], v[154:157], v[210:213], v[76:79]
	v_mfma_f32_16x16x32_bf16 v[72:75], v[162:165], v[210:213], v[72:75]
	v_mfma_f32_16x16x32_bf16 v[124:127], v[158:161], v[190:193], v[124:127]
	v_mfma_f32_16x16x32_bf16 v[120:123], v[166:169], v[190:193], v[120:123]
	v_mfma_f32_16x16x32_bf16 v[108:111], v[158:161], v[198:201], v[108:111]
	v_mfma_f32_16x16x32_bf16 v[104:107], v[166:169], v[198:201], v[104:107]
	v_mfma_f32_16x16x32_bf16 v[92:95], v[158:161], v[206:209], v[92:95]
	v_mfma_f32_16x16x32_bf16 v[88:91], v[166:169], v[206:209], v[88:91]
	v_mfma_f32_16x16x32_bf16 v[76:79], v[158:161], v[214:217], v[76:79]
	v_mfma_f32_16x16x32_bf16 v[72:75], v[166:169], v[214:217], v[72:75]
	v_mfma_f32_16x16x32_bf16 v[116:119], v[170:173], v[186:189], v[116:119]
	v_mfma_f32_16x16x32_bf16 v[112:115], v[178:181], v[186:189], v[112:115]
	v_mfma_f32_16x16x32_bf16 v[100:103], v[170:173], v[194:197], v[100:103]
	v_mfma_f32_16x16x32_bf16 v[96:99], v[178:181], v[194:197], v[96:99]
	v_mfma_f32_16x16x32_bf16 v[84:87], v[170:173], v[202:205], v[84:87]
	v_mfma_f32_16x16x32_bf16 v[80:83], v[178:181], v[202:205], v[80:83]
	v_mfma_f32_16x16x32_bf16 v[68:71], v[170:173], v[210:213], v[68:71]
	v_mfma_f32_16x16x32_bf16 v[64:67], v[178:181], v[210:213], v[64:67]
	v_mfma_f32_16x16x32_bf16 v[116:119], v[174:177], v[190:193], v[116:119]
	v_mfma_f32_16x16x32_bf16 v[112:115], v[182:185], v[190:193], v[112:115]
	v_mfma_f32_16x16x32_bf16 v[100:103], v[174:177], v[198:201], v[100:103]
	v_mfma_f32_16x16x32_bf16 v[96:99], v[182:185], v[198:201], v[96:99]
	v_mfma_f32_16x16x32_bf16 v[84:87], v[174:177], v[206:209], v[84:87]
	v_mfma_f32_16x16x32_bf16 v[80:83], v[182:185], v[206:209], v[80:83]
	v_mfma_f32_16x16x32_bf16 v[68:71], v[174:177], v[214:217], v[68:71]
	v_mfma_f32_16x16x32_bf16 v[64:67], v[182:185], v[214:217], v[64:67]
	s_barrier
	s_add_i32 s3, s3, s18
	s_add_u32 s42, s80, 0x80
	s_addc_u32 s43, s81, 0
	s_mov_b32 m0, s3
	ds_read_b128 v[186:189], v152 offset:49152
	ds_read_b128 v[190:193], v152 offset:50176
	ds_read_b128 v[194:197], v152 offset:51200
	ds_read_b128 v[198:201], v152 offset:52224
	ds_read_b128 v[202:205], v152 offset:53248
	ds_read_b128 v[206:209], v152 offset:54272
	ds_read_b128 v[210:213], v152 offset:55296
	ds_read_b128 v[214:217], v152 offset:56320
	global_load_lds_dwordx4 v130, s[42:43]
	s_add_i32 m0, s3, 0x2000
	s_add_i32 s3, s37, s18
	global_load_lds_dwordx4 v134, s[42:43]
	s_add_u32 s42, s42, 0x80000
	s_addc_u32 s43, s43, 0
	s_mov_b32 m0, s3
	s_nop 0
	global_load_lds_dwordx4 v130, s[42:43]
	s_add_i32 m0, s3, 0x2000
	s_nop 0
	global_load_lds_dwordx4 v134, s[42:43]
	s_add_u32 s90, s90, 0x80
	s_addc_u32 s91, s91, 0
	s_mov_b32 m0, s48
	s_nop 0
	global_load_lds_dwordx4 v128, s[90:91]
	s_mov_b32 m0, s49
	s_nop 0
	global_load_lds_dwordx4 v132, s[90:91]
	s_waitcnt vmcnt(8)
	s_waitcnt lgkmcnt(0)
	s_barrier
	v_mfma_f32_16x16x32_bf16 v[60:63], v[154:157], v[186:189], v[60:63]
	v_mfma_f32_16x16x32_bf16 v[56:59], v[162:165], v[186:189], v[56:59]
	v_mfma_f32_16x16x32_bf16 v[44:47], v[154:157], v[194:197], v[44:47]
	v_mfma_f32_16x16x32_bf16 v[40:43], v[162:165], v[194:197], v[40:43]
	v_mfma_f32_16x16x32_bf16 v[28:31], v[154:157], v[202:205], v[28:31]
	v_mfma_f32_16x16x32_bf16 v[24:27], v[162:165], v[202:205], v[24:27]
	v_mfma_f32_16x16x32_bf16 v[12:15], v[154:157], v[210:213], v[12:15]
	v_mfma_f32_16x16x32_bf16 v[8:11], v[162:165], v[210:213], v[8:11]
	v_mfma_f32_16x16x32_bf16 v[60:63], v[158:161], v[190:193], v[60:63]
	v_mfma_f32_16x16x32_bf16 v[56:59], v[166:169], v[190:193], v[56:59]
	v_mfma_f32_16x16x32_bf16 v[44:47], v[158:161], v[198:201], v[44:47]
	v_mfma_f32_16x16x32_bf16 v[40:43], v[166:169], v[198:201], v[40:43]
	v_mfma_f32_16x16x32_bf16 v[28:31], v[158:161], v[206:209], v[28:31]
	v_mfma_f32_16x16x32_bf16 v[24:27], v[166:169], v[206:209], v[24:27]
	v_mfma_f32_16x16x32_bf16 v[12:15], v[158:161], v[214:217], v[12:15]
	v_mfma_f32_16x16x32_bf16 v[8:11], v[166:169], v[214:217], v[8:11]
	v_mfma_f32_16x16x32_bf16 v[52:55], v[170:173], v[186:189], v[52:55]
	v_mfma_f32_16x16x32_bf16 v[48:51], v[178:181], v[186:189], v[48:51]
	v_mfma_f32_16x16x32_bf16 v[36:39], v[170:173], v[194:197], v[36:39]
	v_mfma_f32_16x16x32_bf16 v[32:35], v[178:181], v[194:197], v[32:35]
	v_mfma_f32_16x16x32_bf16 v[20:23], v[170:173], v[202:205], v[20:23]
	v_mfma_f32_16x16x32_bf16 v[16:19], v[178:181], v[202:205], v[16:19]
	v_mfma_f32_16x16x32_bf16 v[4:7], v[170:173], v[210:213], v[4:7]
	v_mfma_f32_16x16x32_bf16 v[0:3], v[178:181], v[210:213], v[0:3]
	v_mfma_f32_16x16x32_bf16 v[52:55], v[174:177], v[190:193], v[52:55]
	v_mfma_f32_16x16x32_bf16 v[48:51], v[182:185], v[190:193], v[48:51]
	v_mfma_f32_16x16x32_bf16 v[36:39], v[174:177], v[198:201], v[36:39]
	v_mfma_f32_16x16x32_bf16 v[32:35], v[182:185], v[198:201], v[32:35]
	v_mfma_f32_16x16x32_bf16 v[20:23], v[174:177], v[206:209], v[20:23]
	v_mfma_f32_16x16x32_bf16 v[16:19], v[182:185], v[206:209], v[16:19]
	v_mfma_f32_16x16x32_bf16 v[4:7], v[174:177], v[214:217], v[4:7]
	v_mfma_f32_16x16x32_bf16 v[0:3], v[182:185], v[214:217], v[0:3]
	s_barrier
	s_add_i32 s36, s36, 2
	s_add_u32 s88, s88, 0x100
	s_addc_u32 s89, s89, 0
	s_add_u32 s33, s33, 0x100
	s_addc_u32 s35, s35, 0
	s_cmp_gt_u32 s36, 29
	s_cbranch_scc0 .LBB0_770
	s_and_b64 vcc, exec, s[14:15]
	s_cbranch_vccz .LBB0_773
	s_barrier

.LBB0_846:
	ds_read_b128 v[140:143], v149
	ds_read_b128 v[152:155], v149 offset:1024
	ds_read_b128 v[156:159], v149 offset:2048
	ds_read_b128 v[160:163], v149 offset:3072
	ds_read_b128 v[164:167], v150
	ds_read_b128 v[168:171], v150 offset:1024
	ds_read_b128 v[172:175], v150 offset:2048
	ds_read_b128 v[176:179], v150 offset:3072
	s_add_u32 s3, s84, 0xffe00080
	s_addc_u32 s37, s85, -1
	s_cmpk_eq_i32 s36, 0x7c
	s_cselect_b32 s87, s0, s37
	s_cselect_b32 s86, s1, s3
	s_cselect_b32 s81, s15, s33
	s_cselect_b32 s80, s17, s27
	s_add_i32 m0, s19, 0xc000
	ds_read_b128 v[180:183], v151
	ds_read_b128 v[184:187], v151 offset:1024
	ds_read_b128 v[188:191], v151 offset:2048
	ds_read_b128 v[192:195], v151 offset:3072
	ds_read_b128 v[196:199], v151 offset:4096
	ds_read_b128 v[200:203], v151 offset:5120
	ds_read_b128 v[204:207], v151 offset:6144
	ds_read_b128 v[208:211], v151 offset:7168
	global_load_lds_dwordx4 v132, s[84:85]
	s_add_i32 m0, s19, 0xe000
	s_nop 0
	global_load_lds_dwordx4 v134, s[84:85]
	s_waitcnt vmcnt(8)
	s_waitcnt lgkmcnt(0)
	s_barrier
	v_mfma_f32_16x16x32_bf16 v[124:127], v[140:143], v[180:183], v[124:127]
	v_mfma_f32_16x16x32_bf16 v[120:123], v[156:159], v[180:183], v[120:123]
	v_mfma_f32_16x16x32_bf16 v[112:115], v[140:143], v[188:191], v[112:115]
	v_mfma_f32_16x16x32_bf16 v[104:107], v[156:159], v[188:191], v[104:107]
	v_mfma_f32_16x16x32_bf16 v[96:99], v[140:143], v[196:199], v[96:99]
	v_mfma_f32_16x16x32_bf16 v[88:91], v[156:159], v[196:199], v[88:91]
	v_mfma_f32_16x16x32_bf16 v[80:83], v[140:143], v[204:207], v[80:83]
	v_mfma_f32_16x16x32_bf16 v[72:75], v[156:159], v[204:207], v[72:75]
	v_mfma_f32_16x16x32_bf16 v[124:127], v[152:155], v[184:187], v[124:127]
	v_mfma_f32_16x16x32_bf16 v[120:123], v[160:163], v[184:187], v[120:123]
	v_mfma_f32_16x16x32_bf16 v[112:115], v[152:155], v[192:195], v[112:115]
	v_mfma_f32_16x16x32_bf16 v[104:107], v[160:163], v[192:195], v[104:107]
	v_mfma_f32_16x16x32_bf16 v[96:99], v[152:155], v[200:203], v[96:99]
	v_mfma_f32_16x16x32_bf16 v[88:91], v[160:163], v[200:203], v[88:91]
	v_mfma_f32_16x16x32_bf16 v[80:83], v[152:155], v[208:211], v[80:83]
	v_mfma_f32_16x16x32_bf16 v[72:75], v[160:163], v[208:211], v[72:75]
	v_mfma_f32_16x16x32_bf16 v[116:119], v[164:167], v[180:183], v[116:119]
	v_mfma_f32_16x16x32_bf16 v[108:111], v[172:175], v[180:183], v[108:111]
	v_mfma_f32_16x16x32_bf16 v[100:103], v[164:167], v[188:191], v[100:103]
	v_mfma_f32_16x16x32_bf16 v[92:95], v[172:175], v[188:191], v[92:95]
	v_mfma_f32_16x16x32_bf16 v[84:87], v[164:167], v[196:199], v[84:87]
	v_mfma_f32_16x16x32_bf16 v[76:79], v[172:175], v[196:199], v[76:79]
	v_mfma_f32_16x16x32_bf16 v[68:71], v[164:167], v[204:207], v[68:71]
	v_mfma_f32_16x16x32_bf16 v[64:67], v[172:175], v[204:207], v[64:67]
	v_mfma_f32_16x16x32_bf16 v[116:119], v[168:171], v[184:187], v[116:119]
	v_mfma_f32_16x16x32_bf16 v[108:111], v[176:179], v[184:187], v[108:111]
	v_mfma_f32_16x16x32_bf16 v[100:103], v[168:171], v[192:195], v[100:103]
	v_mfma_f32_16x16x32_bf16 v[92:95], v[176:179], v[192:195], v[92:95]
	v_mfma_f32_16x16x32_bf16 v[84:87], v[168:171], v[200:203], v[84:87]
	v_mfma_f32_16x16x32_bf16 v[76:79], v[176:179], v[200:203], v[76:79]
	v_mfma_f32_16x16x32_bf16 v[68:71], v[168:171], v[208:211], v[68:71]
	v_mfma_f32_16x16x32_bf16 v[64:67], v[176:179], v[208:211], v[64:67]
	s_barrier
	s_add_i32 s3, s57, s18
	s_mov_b32 m0, s3
	ds_read_b128 v[180:183], v151 offset:16384
	ds_read_b128 v[184:187], v151 offset:17408
	ds_read_b128 v[188:191], v151 offset:18432
	ds_read_b128 v[192:195], v151 offset:19456
	ds_read_b128 v[196:199], v151 offset:20480
	ds_read_b128 v[200:203], v151 offset:21504
	ds_read_b128 v[204:207], v151 offset:22528
	ds_read_b128 v[208:211], v151 offset:23552
	global_load_lds_dwordx4 v128, s[80:81]
	s_add_i32 m0, s3, 0x2000
	s_add_u32 s42, s80, 0x200000
	s_addc_u32 s43, s81, 0
	s_add_i32 s3, s58, s18
	global_load_lds_dwordx4 v130, s[80:81]
	s_mov_b32 m0, s3
	s_nop 0
	global_load_lds_dwordx4 v128, s[42:43]
	s_add_i32 m0, s3, 0x2000
	s_nop 0
	global_load_lds_dwordx4 v130, s[42:43]
	s_mov_b32 m0, s19
	s_nop 0
	global_load_lds_dwordx4 v128, s[86:87]
	s_mov_b32 m0, s25
	s_nop 0
	global_load_lds_dwordx4 v130, s[86:87]
	s_waitcnt vmcnt(8)
	s_waitcnt lgkmcnt(0)
	s_barrier
	v_mfma_f32_16x16x32_bf16 v[60:63], v[140:143], v[180:183], v[60:63]
	v_mfma_f32_16x16x32_bf16 v[56:59], v[156:159], v[180:183], v[56:59]
	v_mfma_f32_16x16x32_bf16 v[48:51], v[140:143], v[188:191], v[48:51]
	v_mfma_f32_16x16x32_bf16 v[40:43], v[156:159], v[188:191], v[40:43]
	v_mfma_f32_16x16x32_bf16 v[32:35], v[140:143], v[196:199], v[32:35]
	v_mfma_f32_16x16x32_bf16 v[24:27], v[156:159], v[196:199], v[24:27]
	v_mfma_f32_16x16x32_bf16 v[16:19], v[140:143], v[204:207], v[16:19]
	v_mfma_f32_16x16x32_bf16 v[8:11], v[156:159], v[204:207], v[8:11]
	v_mfma_f32_16x16x32_bf16 v[60:63], v[152:155], v[184:187], v[60:63]
	v_mfma_f32_16x16x32_bf16 v[56:59], v[160:163], v[184:187], v[56:59]
	v_mfma_f32_16x16x32_bf16 v[48:51], v[152:155], v[192:195], v[48:51]
	v_mfma_f32_16x16x32_bf16 v[40:43], v[160:163], v[192:195], v[40:43]
	v_mfma_f32_16x16x32_bf16 v[32:35], v[152:155], v[200:203], v[32:35]
	v_mfma_f32_16x16x32_bf16 v[24:27], v[160:163], v[200:203], v[24:27]
	v_mfma_f32_16x16x32_bf16 v[16:19], v[152:155], v[208:211], v[16:19]
	v_mfma_f32_16x16x32_bf16 v[8:11], v[160:163], v[208:211], v[8:11]
	v_mfma_f32_16x16x32_bf16 v[52:55], v[164:167], v[180:183], v[52:55]
	v_mfma_f32_16x16x32_bf16 v[44:47], v[172:175], v[180:183], v[44:47]
	v_mfma_f32_16x16x32_bf16 v[36:39], v[164:167], v[188:191], v[36:39]
	v_mfma_f32_16x16x32_bf16 v[28:31], v[172:175], v[188:191], v[28:31]
	v_mfma_f32_16x16x32_bf16 v[20:23], v[164:167], v[196:199], v[20:23]
	v_mfma_f32_16x16x32_bf16 v[12:15], v[172:175], v[196:199], v[12:15]
	v_mfma_f32_16x16x32_bf16 v[4:7], v[164:167], v[204:207], v[4:7]
	v_mfma_f32_16x16x32_bf16 v[0:3], v[172:175], v[204:207], v[0:3]
	v_mfma_f32_16x16x32_bf16 v[52:55], v[168:171], v[184:187], v[52:55]
	v_mfma_f32_16x16x32_bf16 v[44:47], v[176:179], v[184:187], v[44:47]
	v_mfma_f32_16x16x32_bf16 v[36:39], v[168:171], v[192:195], v[36:39]
	v_mfma_f32_16x16x32_bf16 v[28:31], v[176:179], v[192:195], v[28:31]
	v_mfma_f32_16x16x32_bf16 v[20:23], v[168:171], v[200:203], v[20:23]
	v_mfma_f32_16x16x32_bf16 v[12:15], v[176:179], v[200:203], v[12:15]
	v_mfma_f32_16x16x32_bf16 v[4:7], v[168:171], v[208:211], v[4:7]
	v_mfma_f32_16x16x32_bf16 v[0:3], v[176:179], v[208:211], v[0:3]
	s_barrier
	s_add_i32 s3, 0, 0x18000
	s_add_i32 s37, 0, 0x1c000
	v_add_u32_e32 v160, s3, v147
	v_add_u32_e32 v176, s37, v147
	ds_read_b128 v[140:143], v160
	ds_read_b128 v[152:155], v160 offset:1024
	ds_read_b128 v[156:159], v160 offset:2048
	ds_read_b128 v[160:163], v160 offset:3072
	ds_read_b128 v[164:167], v176
	ds_read_b128 v[168:171], v176 offset:1024
	ds_read_b128 v[172:175], v176 offset:2048
	ds_read_b128 v[176:179], v176 offset:3072
	s_add_u32 s42, s86, 0x200000
	s_addc_u32 s43, s87, 0
	s_mov_b32 m0, s30
	ds_read_b128 v[180:183], v151 offset:32768
	ds_read_b128 v[184:187], v151 offset:33792
	ds_read_b128 v[188:191], v151 offset:34816
	ds_read_b128 v[192:195], v151 offset:35840
	ds_read_b128 v[196:199], v151 offset:36864
	ds_read_b128 v[200:203], v151 offset:37888
	ds_read_b128 v[204:207], v151 offset:38912
	ds_read_b128 v[208:211], v151 offset:39936
	global_load_lds_dwordx4 v128, s[42:43]
	v_lshl_add_u64 v[218:219], s[42:43], 0, v[130:131]
	s_mov_b32 m0, s31
	s_nop 0
	global_load_lds_dwordx4 v[218:219], off
	s_waitcnt vmcnt(8)
	s_waitcnt lgkmcnt(0)
	s_barrier
	v_mfma_f32_16x16x32_bf16 v[124:127], v[140:143], v[180:183], v[124:127]
	v_mfma_f32_16x16x32_bf16 v[120:123], v[156:159], v[180:183], v[120:123]
	v_mfma_f32_16x16x32_bf16 v[112:115], v[140:143], v[188:191], v[112:115]
	v_mfma_f32_16x16x32_bf16 v[104:107], v[156:159], v[188:191], v[104:107]
	v_mfma_f32_16x16x32_bf16 v[96:99], v[140:143], v[196:199], v[96:99]
	v_mfma_f32_16x16x32_bf16 v[88:91], v[156:159], v[196:199], v[88:91]
	v_mfma_f32_16x16x32_bf16 v[80:83], v[140:143], v[204:207], v[80:83]
	v_mfma_f32_16x16x32_bf16 v[72:75], v[156:159], v[204:207], v[72:75]
	v_mfma_f32_16x16x32_bf16 v[124:127], v[152:155], v[184:187], v[124:127]
	v_mfma_f32_16x16x32_bf16 v[120:123], v[160:163], v[184:187], v[120:123]
	v_mfma_f32_16x16x32_bf16 v[112:115], v[152:155], v[192:195], v[112:115]
	v_mfma_f32_16x16x32_bf16 v[104:107], v[160:163], v[192:195], v[104:107]
	v_mfma_f32_16x16x32_bf16 v[96:99], v[152:155], v[200:203], v[96:99]
	v_mfma_f32_16x16x32_bf16 v[88:91], v[160:163], v[200:203], v[88:91]
	v_mfma_f32_16x16x32_bf16 v[80:83], v[152:155], v[208:211], v[80:83]
	v_mfma_f32_16x16x32_bf16 v[72:75], v[160:163], v[208:211], v[72:75]
	v_mfma_f32_16x16x32_bf16 v[116:119], v[164:167], v[180:183], v[116:119]
	v_mfma_f32_16x16x32_bf16 v[108:111], v[172:175], v[180:183], v[108:111]
	v_mfma_f32_16x16x32_bf16 v[100:103], v[164:167], v[188:191], v[100:103]
	v_mfma_f32_16x16x32_bf16 v[92:95], v[172:175], v[188:191], v[92:95]
	v_mfma_f32_16x16x32_bf16 v[84:87], v[164:167], v[196:199], v[84:87]
	v_mfma_f32_16x16x32_bf16 v[76:79], v[172:175], v[196:199], v[76:79]
	v_mfma_f32_16x16x32_bf16 v[68:71], v[164:167], v[204:207], v[68:71]
	v_mfma_f32_16x16x32_bf16 v[64:67], v[172:175], v[204:207], v[64:67]
	v_mfma_f32_16x16x32_bf16 v[116:119], v[168:171], v[184:187], v[116:119]
	v_mfma_f32_16x16x32_bf16 v[108:111], v[176:179], v[184:187], v[108:111]
	v_mfma_f32_16x16x32_bf16 v[100:103], v[168:171], v[192:195], v[100:103]
	v_mfma_f32_16x16x32_bf16 v[92:95], v[176:179], v[192:195], v[92:95]
	v_mfma_f32_16x16x32_bf16 v[84:87], v[168:171], v[200:203], v[84:87]
	v_mfma_f32_16x16x32_bf16 v[76:79], v[176:179], v[200:203], v[76:79]
	v_mfma_f32_16x16x32_bf16 v[68:71], v[168:171], v[208:211], v[68:71]
	v_mfma_f32_16x16x32_bf16 v[64:67], v[176:179], v[208:211], v[64:67]
	s_barrier
	s_add_i32 s3, s3, s18
	s_add_u32 s42, s80, 0x80
	s_addc_u32 s43, s81, 0
	s_mov_b32 m0, s3
	ds_read_b128 v[180:183], v151 offset:49152
	ds_read_b128 v[184:187], v151 offset:50176
	ds_read_b128 v[188:191], v151 offset:51200
	ds_read_b128 v[192:195], v151 offset:52224
	ds_read_b128 v[196:199], v151 offset:53248
	ds_read_b128 v[200:203], v151 offset:54272
	ds_read_b128 v[204:207], v151 offset:55296
	ds_read_b128 v[208:211], v151 offset:56320
	global_load_lds_dwordx4 v128, s[42:43]
	s_add_i32 m0, s3, 0x2000
	s_add_i32 s3, s37, s18
	global_load_lds_dwordx4 v130, s[42:43]
	s_add_u32 s42, s42, 0x200000
	s_addc_u32 s43, s43, 0
	s_mov_b32 m0, s3
	s_nop 0
	global_load_lds_dwordx4 v128, s[42:43]
	s_add_i32 m0, s3, 0x2000
	s_nop 0
	global_load_lds_dwordx4 v130, s[42:43]
	s_add_u32 s86, s86, 0x80
	s_addc_u32 s87, s87, 0
	s_mov_b32 m0, s49
	s_nop 0
	global_load_lds_dwordx4 v128, s[86:87]
	s_mov_b32 m0, s56
	s_nop 0
	global_load_lds_dwordx4 v130, s[86:87]
	s_waitcnt vmcnt(8)
	s_waitcnt lgkmcnt(0)
	s_barrier
	v_mfma_f32_16x16x32_bf16 v[60:63], v[140:143], v[180:183], v[60:63]
	v_mfma_f32_16x16x32_bf16 v[56:59], v[156:159], v[180:183], v[56:59]
	v_mfma_f32_16x16x32_bf16 v[48:51], v[140:143], v[188:191], v[48:51]
	v_mfma_f32_16x16x32_bf16 v[40:43], v[156:159], v[188:191], v[40:43]
	v_mfma_f32_16x16x32_bf16 v[32:35], v[140:143], v[196:199], v[32:35]
	v_mfma_f32_16x16x32_bf16 v[24:27], v[156:159], v[196:199], v[24:27]
	v_mfma_f32_16x16x32_bf16 v[16:19], v[140:143], v[204:207], v[16:19]
	v_mfma_f32_16x16x32_bf16 v[8:11], v[156:159], v[204:207], v[8:11]
	v_mfma_f32_16x16x32_bf16 v[60:63], v[152:155], v[184:187], v[60:63]
	v_mfma_f32_16x16x32_bf16 v[56:59], v[160:163], v[184:187], v[56:59]
	v_mfma_f32_16x16x32_bf16 v[48:51], v[152:155], v[192:195], v[48:51]
	v_mfma_f32_16x16x32_bf16 v[40:43], v[160:163], v[192:195], v[40:43]
	v_mfma_f32_16x16x32_bf16 v[32:35], v[152:155], v[200:203], v[32:35]
	v_mfma_f32_16x16x32_bf16 v[24:27], v[160:163], v[200:203], v[24:27]
	v_mfma_f32_16x16x32_bf16 v[16:19], v[152:155], v[208:211], v[16:19]
	v_mfma_f32_16x16x32_bf16 v[8:11], v[160:163], v[208:211], v[8:11]
	v_mfma_f32_16x16x32_bf16 v[52:55], v[164:167], v[180:183], v[52:55]
	v_mfma_f32_16x16x32_bf16 v[44:47], v[172:175], v[180:183], v[44:47]
	v_mfma_f32_16x16x32_bf16 v[36:39], v[164:167], v[188:191], v[36:39]
	v_mfma_f32_16x16x32_bf16 v[28:31], v[172:175], v[188:191], v[28:31]
	v_mfma_f32_16x16x32_bf16 v[20:23], v[164:167], v[196:199], v[20:23]
	v_mfma_f32_16x16x32_bf16 v[12:15], v[172:175], v[196:199], v[12:15]
	v_mfma_f32_16x16x32_bf16 v[4:7], v[164:167], v[204:207], v[4:7]
	v_mfma_f32_16x16x32_bf16 v[0:3], v[172:175], v[204:207], v[0:3]
	v_mfma_f32_16x16x32_bf16 v[52:55], v[168:171], v[184:187], v[52:55]
	v_mfma_f32_16x16x32_bf16 v[44:47], v[176:179], v[184:187], v[44:47]
	v_mfma_f32_16x16x32_bf16 v[36:39], v[168:171], v[192:195], v[36:39]
	v_mfma_f32_16x16x32_bf16 v[28:31], v[176:179], v[192:195], v[28:31]
	v_mfma_f32_16x16x32_bf16 v[20:23], v[168:171], v[200:203], v[20:23]
	v_mfma_f32_16x16x32_bf16 v[12:15], v[176:179], v[200:203], v[12:15]
	v_mfma_f32_16x16x32_bf16 v[4:7], v[168:171], v[208:211], v[4:7]
	v_mfma_f32_16x16x32_bf16 v[0:3], v[176:179], v[208:211], v[0:3]
	s_barrier
	s_add_i32 s36, s36, 2
	s_add_u32 s84, s84, 0x100
	s_addc_u32 s85, s85, 0
	s_add_u32 s27, s27, 0x100
	s_addc_u32 s33, s33, 0
	s_cmpk_gt_u32 s36, 0x7d
	s_cbranch_scc0 .LBB0_846
	s_and_b64 vcc, exec, s[12:13]
	s_cbranch_vccz .LBB0_849
	s_barrier

.LBB0_919:
	ds_read_b128 v[128:131], v173
	ds_read_b128 v[132:135], v173 offset:1024
	ds_read_b128 v[158:161], v173 offset:2048
	ds_read_b128 v[178:181], v173 offset:3072
	ds_read_b128 v[182:185], v174
	ds_read_b128 v[186:189], v174 offset:1024
	ds_read_b128 v[190:193], v174 offset:2048
	ds_read_b128 v[194:197], v174 offset:3072
	s_add_u32 s3, s34, 0xfff80080
	s_addc_u32 s27, s35, -1
	s_cmp_eq_u32 s24, 28
	s_cselect_b32 vcc_hi, s0, s27
	s_cselect_b32 vcc_lo, s1, s3
	s_cselect_b32 s81, s15, s19
	s_cselect_b32 s80, s17, s18
	s_add_i32 m0, s30, 0xc000
	ds_read_b128 v[198:201], v175
	ds_read_b128 v[202:205], v175 offset:1024
	ds_read_b128 v[206:209], v175 offset:2048
	ds_read_b128 v[210:213], v175 offset:3072
	ds_read_b128 v[214:217], v175 offset:4096
	ds_read_b128 v[218:221], v175 offset:5120
	ds_read_b128 v[222:225], v175 offset:6144
	ds_read_b128 v[230:233], v175 offset:7168
	global_load_lds_dwordx4 v148, s[34:35]
	s_add_i32 m0, s30, 0xe000
	s_nop 0
	global_load_lds_dwordx4 v150, s[34:35]
	s_waitcnt vmcnt(8)
	s_waitcnt lgkmcnt(0)
	s_barrier
	v_mfma_f32_16x16x32_bf16 v[124:127], v[128:131], v[198:201], v[124:127]
	v_mfma_f32_16x16x32_bf16 v[120:123], v[158:161], v[198:201], v[120:123]
	v_mfma_f32_16x16x32_bf16 v[108:111], v[128:131], v[206:209], v[108:111]
	v_mfma_f32_16x16x32_bf16 v[104:107], v[158:161], v[206:209], v[104:107]
	v_mfma_f32_16x16x32_bf16 v[92:95], v[128:131], v[214:217], v[92:95]
	v_mfma_f32_16x16x32_bf16 v[88:91], v[158:161], v[214:217], v[88:91]
	v_mfma_f32_16x16x32_bf16 v[76:79], v[128:131], v[222:225], v[76:79]
	v_mfma_f32_16x16x32_bf16 v[72:75], v[158:161], v[222:225], v[72:75]
	v_mfma_f32_16x16x32_bf16 v[124:127], v[132:135], v[202:205], v[124:127]
	v_mfma_f32_16x16x32_bf16 v[120:123], v[178:181], v[202:205], v[120:123]
	v_mfma_f32_16x16x32_bf16 v[108:111], v[132:135], v[210:213], v[108:111]
	v_mfma_f32_16x16x32_bf16 v[104:107], v[178:181], v[210:213], v[104:107]
	v_mfma_f32_16x16x32_bf16 v[92:95], v[132:135], v[218:221], v[92:95]
	v_mfma_f32_16x16x32_bf16 v[88:91], v[178:181], v[218:221], v[88:91]
	v_mfma_f32_16x16x32_bf16 v[76:79], v[132:135], v[230:233], v[76:79]
	v_mfma_f32_16x16x32_bf16 v[72:75], v[178:181], v[230:233], v[72:75]
	v_mfma_f32_16x16x32_bf16 v[116:119], v[182:185], v[198:201], v[116:119]
	v_mfma_f32_16x16x32_bf16 v[112:115], v[190:193], v[198:201], v[112:115]
	v_mfma_f32_16x16x32_bf16 v[100:103], v[182:185], v[206:209], v[100:103]
	v_mfma_f32_16x16x32_bf16 v[96:99], v[190:193], v[206:209], v[96:99]
	v_mfma_f32_16x16x32_bf16 v[84:87], v[182:185], v[214:217], v[84:87]
	v_mfma_f32_16x16x32_bf16 v[80:83], v[190:193], v[214:217], v[80:83]
	v_mfma_f32_16x16x32_bf16 v[68:71], v[182:185], v[222:225], v[68:71]
	v_mfma_f32_16x16x32_bf16 v[64:67], v[190:193], v[222:225], v[64:67]
	v_mfma_f32_16x16x32_bf16 v[116:119], v[186:189], v[202:205], v[116:119]
	v_mfma_f32_16x16x32_bf16 v[112:115], v[194:197], v[202:205], v[112:115]
	v_mfma_f32_16x16x32_bf16 v[100:103], v[186:189], v[210:213], v[100:103]
	v_mfma_f32_16x16x32_bf16 v[96:99], v[194:197], v[210:213], v[96:99]
	v_mfma_f32_16x16x32_bf16 v[84:87], v[186:189], v[218:221], v[84:87]
	v_mfma_f32_16x16x32_bf16 v[80:83], v[194:197], v[218:221], v[80:83]
	v_mfma_f32_16x16x32_bf16 v[68:71], v[186:189], v[230:233], v[68:71]
	v_mfma_f32_16x16x32_bf16 v[64:67], v[194:197], v[230:233], v[64:67]
	s_barrier
	s_add_i32 s3, s57, s25
	s_mov_b32 m0, s3
	ds_read_b128 v[198:201], v175 offset:16384
	ds_read_b128 v[202:205], v175 offset:17408
	ds_read_b128 v[206:209], v175 offset:18432
	ds_read_b128 v[210:213], v175 offset:19456
	ds_read_b128 v[214:217], v175 offset:20480
	ds_read_b128 v[218:221], v175 offset:21504
	ds_read_b128 v[222:225], v175 offset:22528
	ds_read_b128 v[230:233], v175 offset:23552
	global_load_lds_dwordx4 v138, s[80:81]
	s_add_i32 m0, s3, 0x2000
	s_add_u32 s36, s80, 0x80000
	s_addc_u32 s37, s81, 0
	s_add_i32 s3, s76, s25
	global_load_lds_dwordx4 v142, s[80:81]
	s_mov_b32 m0, s3
	s_nop 0
	global_load_lds_dwordx4 v138, s[36:37]
	s_add_i32 m0, s3, 0x2000
	s_nop 0
	global_load_lds_dwordx4 v142, s[36:37]
	s_mov_b32 m0, s30
	s_nop 0
	global_load_lds_dwordx4 v136, vcc
	s_mov_b32 m0, s31
	s_nop 0
	global_load_lds_dwordx4 v140, vcc
	s_waitcnt vmcnt(8)
	s_waitcnt lgkmcnt(0)
	s_barrier
	v_mfma_f32_16x16x32_bf16 v[60:63], v[128:131], v[198:201], v[60:63]
	v_mfma_f32_16x16x32_bf16 v[56:59], v[158:161], v[198:201], v[56:59]
	v_mfma_f32_16x16x32_bf16 v[44:47], v[128:131], v[206:209], v[44:47]
	v_mfma_f32_16x16x32_bf16 v[40:43], v[158:161], v[206:209], v[40:43]
	v_mfma_f32_16x16x32_bf16 v[28:31], v[128:131], v[214:217], v[28:31]
	v_mfma_f32_16x16x32_bf16 v[24:27], v[158:161], v[214:217], v[24:27]
	v_mfma_f32_16x16x32_bf16 v[12:15], v[128:131], v[222:225], v[12:15]
	v_mfma_f32_16x16x32_bf16 v[8:11], v[158:161], v[222:225], v[8:11]
	v_mfma_f32_16x16x32_bf16 v[60:63], v[132:135], v[202:205], v[60:63]
	v_mfma_f32_16x16x32_bf16 v[56:59], v[178:181], v[202:205], v[56:59]
	v_mfma_f32_16x16x32_bf16 v[44:47], v[132:135], v[210:213], v[44:47]
	v_mfma_f32_16x16x32_bf16 v[40:43], v[178:181], v[210:213], v[40:43]
	v_mfma_f32_16x16x32_bf16 v[28:31], v[132:135], v[218:221], v[28:31]
	v_mfma_f32_16x16x32_bf16 v[24:27], v[178:181], v[218:221], v[24:27]
	v_mfma_f32_16x16x32_bf16 v[12:15], v[132:135], v[230:233], v[12:15]
	v_mfma_f32_16x16x32_bf16 v[8:11], v[178:181], v[230:233], v[8:11]
	v_mfma_f32_16x16x32_bf16 v[52:55], v[182:185], v[198:201], v[52:55]
	v_mfma_f32_16x16x32_bf16 v[48:51], v[190:193], v[198:201], v[48:51]
	v_mfma_f32_16x16x32_bf16 v[36:39], v[182:185], v[206:209], v[36:39]
	v_mfma_f32_16x16x32_bf16 v[32:35], v[190:193], v[206:209], v[32:35]
	v_mfma_f32_16x16x32_bf16 v[20:23], v[182:185], v[214:217], v[20:23]
	v_mfma_f32_16x16x32_bf16 v[16:19], v[190:193], v[214:217], v[16:19]
	v_mfma_f32_16x16x32_bf16 v[4:7], v[182:185], v[222:225], v[4:7]
	v_mfma_f32_16x16x32_bf16 v[0:3], v[190:193], v[222:225], v[0:3]
	v_mfma_f32_16x16x32_bf16 v[52:55], v[186:189], v[202:205], v[52:55]
	v_mfma_f32_16x16x32_bf16 v[48:51], v[194:197], v[202:205], v[48:51]
	v_mfma_f32_16x16x32_bf16 v[36:39], v[186:189], v[210:213], v[36:39]
	v_mfma_f32_16x16x32_bf16 v[32:35], v[194:197], v[210:213], v[32:35]
	v_mfma_f32_16x16x32_bf16 v[20:23], v[186:189], v[218:221], v[20:23]
	v_mfma_f32_16x16x32_bf16 v[16:19], v[194:197], v[218:221], v[16:19]
	v_mfma_f32_16x16x32_bf16 v[4:7], v[186:189], v[230:233], v[4:7]
	v_mfma_f32_16x16x32_bf16 v[0:3], v[194:197], v[230:233], v[0:3]
	s_barrier
	s_add_i32 s3, 0, 0x18000
	v_add_u32_e32 v144, s3, v165
	s_add_i32 s27, 0, 0x1c000
	ds_read_b128 v[128:131], v144
	ds_read_b128 v[132:135], v144 offset:1024
	ds_read_b128 v[158:161], v144 offset:2048
	ds_read_b128 v[178:181], v144 offset:3072
	v_add_u32_e32 v144, s27, v165
	ds_read_b128 v[182:185], v144
	ds_read_b128 v[186:189], v144 offset:1024
	ds_read_b128 v[190:193], v144 offset:2048
	ds_read_b128 v[194:197], v144 offset:3072
	s_add_u32 s36, vcc_lo, 0x80000
	s_addc_u32 s37, vcc_hi, 0
	s_mov_b32 m0, s58
	ds_read_b128 v[198:201], v175 offset:32768
	ds_read_b128 v[202:205], v175 offset:33792
	ds_read_b128 v[206:209], v175 offset:34816
	ds_read_b128 v[210:213], v175 offset:35840
	ds_read_b128 v[214:217], v175 offset:36864
	ds_read_b128 v[218:221], v175 offset:37888
	ds_read_b128 v[222:225], v175 offset:38912
	ds_read_b128 v[230:233], v175 offset:39936
	global_load_lds_dwordx4 v136, s[36:37]
	s_mov_b32 m0, s59
	s_nop 0
	global_load_lds_dwordx4 v140, s[36:37]
	s_waitcnt vmcnt(8)
	s_waitcnt lgkmcnt(0)
	s_barrier
	v_mfma_f32_16x16x32_bf16 v[124:127], v[128:131], v[198:201], v[124:127]
	v_mfma_f32_16x16x32_bf16 v[120:123], v[158:161], v[198:201], v[120:123]
	v_mfma_f32_16x16x32_bf16 v[108:111], v[128:131], v[206:209], v[108:111]
	v_mfma_f32_16x16x32_bf16 v[104:107], v[158:161], v[206:209], v[104:107]
	v_mfma_f32_16x16x32_bf16 v[92:95], v[128:131], v[214:217], v[92:95]
	v_mfma_f32_16x16x32_bf16 v[88:91], v[158:161], v[214:217], v[88:91]
	v_mfma_f32_16x16x32_bf16 v[76:79], v[128:131], v[222:225], v[76:79]
	v_mfma_f32_16x16x32_bf16 v[72:75], v[158:161], v[222:225], v[72:75]
	v_mfma_f32_16x16x32_bf16 v[124:127], v[132:135], v[202:205], v[124:127]
	v_mfma_f32_16x16x32_bf16 v[120:123], v[178:181], v[202:205], v[120:123]
	v_mfma_f32_16x16x32_bf16 v[108:111], v[132:135], v[210:213], v[108:111]
	v_mfma_f32_16x16x32_bf16 v[104:107], v[178:181], v[210:213], v[104:107]
	v_mfma_f32_16x16x32_bf16 v[92:95], v[132:135], v[218:221], v[92:95]
	v_mfma_f32_16x16x32_bf16 v[88:91], v[178:181], v[218:221], v[88:91]
	v_mfma_f32_16x16x32_bf16 v[76:79], v[132:135], v[230:233], v[76:79]
	v_mfma_f32_16x16x32_bf16 v[72:75], v[178:181], v[230:233], v[72:75]
	v_mfma_f32_16x16x32_bf16 v[116:119], v[182:185], v[198:201], v[116:119]
	v_mfma_f32_16x16x32_bf16 v[112:115], v[190:193], v[198:201], v[112:115]
	v_mfma_f32_16x16x32_bf16 v[100:103], v[182:185], v[206:209], v[100:103]
	v_mfma_f32_16x16x32_bf16 v[96:99], v[190:193], v[206:209], v[96:99]
	v_mfma_f32_16x16x32_bf16 v[84:87], v[182:185], v[214:217], v[84:87]
	v_mfma_f32_16x16x32_bf16 v[80:83], v[190:193], v[214:217], v[80:83]
	v_mfma_f32_16x16x32_bf16 v[68:71], v[182:185], v[222:225], v[68:71]
	v_mfma_f32_16x16x32_bf16 v[64:67], v[190:193], v[222:225], v[64:67]
	v_mfma_f32_16x16x32_bf16 v[116:119], v[186:189], v[202:205], v[116:119]
	v_mfma_f32_16x16x32_bf16 v[112:115], v[194:197], v[202:205], v[112:115]
	v_mfma_f32_16x16x32_bf16 v[100:103], v[186:189], v[210:213], v[100:103]
	v_mfma_f32_16x16x32_bf16 v[96:99], v[194:197], v[210:213], v[96:99]
	v_mfma_f32_16x16x32_bf16 v[84:87], v[186:189], v[218:221], v[84:87]
	v_mfma_f32_16x16x32_bf16 v[80:83], v[194:197], v[218:221], v[80:83]
	v_mfma_f32_16x16x32_bf16 v[68:71], v[186:189], v[230:233], v[68:71]
	v_mfma_f32_16x16x32_bf16 v[64:67], v[194:197], v[230:233], v[64:67]
	s_barrier
	s_add_i32 s3, s3, s25
	s_add_u32 s36, s80, 0x80
	s_addc_u32 s37, s81, 0
	s_mov_b32 m0, s3
	ds_read_b128 v[198:201], v175 offset:49152
	ds_read_b128 v[202:205], v175 offset:50176
	ds_read_b128 v[206:209], v175 offset:51200
	ds_read_b128 v[210:213], v175 offset:52224
	ds_read_b128 v[214:217], v175 offset:53248
	ds_read_b128 v[218:221], v175 offset:54272
	ds_read_b128 v[222:225], v175 offset:55296
	ds_read_b128 v[230:233], v175 offset:56320
	global_load_lds_dwordx4 v138, s[36:37]
	s_add_i32 m0, s3, 0x2000
	s_add_i32 s3, s27, s25
	global_load_lds_dwordx4 v142, s[36:37]
	s_add_u32 s36, s36, 0x80000
	s_addc_u32 s37, s37, 0
	s_mov_b32 m0, s3
	s_nop 0
	global_load_lds_dwordx4 v138, s[36:37]
	s_add_i32 m0, s3, 0x2000
	s_nop 0
	global_load_lds_dwordx4 v142, s[36:37]
	s_add_u32 vcc_lo, vcc_lo, 0x80
	s_addc_u32 vcc_hi, vcc_hi, 0
	s_mov_b32 m0, s78
	s_nop 0
	global_load_lds_dwordx4 v136, vcc
	s_mov_b32 m0, s56
	s_nop 0
	global_load_lds_dwordx4 v140, vcc
	s_waitcnt vmcnt(8)
	s_waitcnt lgkmcnt(0)
	s_barrier
	v_mfma_f32_16x16x32_bf16 v[60:63], v[128:131], v[198:201], v[60:63]
	v_mfma_f32_16x16x32_bf16 v[56:59], v[158:161], v[198:201], v[56:59]
	v_mfma_f32_16x16x32_bf16 v[44:47], v[128:131], v[206:209], v[44:47]
	v_mfma_f32_16x16x32_bf16 v[40:43], v[158:161], v[206:209], v[40:43]
	v_mfma_f32_16x16x32_bf16 v[28:31], v[128:131], v[214:217], v[28:31]
	v_mfma_f32_16x16x32_bf16 v[24:27], v[158:161], v[214:217], v[24:27]
	v_mfma_f32_16x16x32_bf16 v[12:15], v[128:131], v[222:225], v[12:15]
	v_mfma_f32_16x16x32_bf16 v[8:11], v[158:161], v[222:225], v[8:11]
	v_mfma_f32_16x16x32_bf16 v[60:63], v[132:135], v[202:205], v[60:63]
	v_mfma_f32_16x16x32_bf16 v[56:59], v[178:181], v[202:205], v[56:59]
	v_mfma_f32_16x16x32_bf16 v[44:47], v[132:135], v[210:213], v[44:47]
	v_mfma_f32_16x16x32_bf16 v[40:43], v[178:181], v[210:213], v[40:43]
	v_mfma_f32_16x16x32_bf16 v[28:31], v[132:135], v[218:221], v[28:31]
	v_mfma_f32_16x16x32_bf16 v[24:27], v[178:181], v[218:221], v[24:27]
	v_mfma_f32_16x16x32_bf16 v[12:15], v[132:135], v[230:233], v[12:15]
	v_mfma_f32_16x16x32_bf16 v[8:11], v[178:181], v[230:233], v[8:11]
	v_mfma_f32_16x16x32_bf16 v[52:55], v[182:185], v[198:201], v[52:55]
	v_mfma_f32_16x16x32_bf16 v[48:51], v[190:193], v[198:201], v[48:51]
	v_mfma_f32_16x16x32_bf16 v[36:39], v[182:185], v[206:209], v[36:39]
	v_mfma_f32_16x16x32_bf16 v[32:35], v[190:193], v[206:209], v[32:35]
	v_mfma_f32_16x16x32_bf16 v[20:23], v[182:185], v[214:217], v[20:23]
	v_mfma_f32_16x16x32_bf16 v[16:19], v[190:193], v[214:217], v[16:19]
	v_mfma_f32_16x16x32_bf16 v[4:7], v[182:185], v[222:225], v[4:7]
	v_mfma_f32_16x16x32_bf16 v[0:3], v[190:193], v[222:225], v[0:3]
	v_mfma_f32_16x16x32_bf16 v[52:55], v[186:189], v[202:205], v[52:55]
	v_mfma_f32_16x16x32_bf16 v[48:51], v[194:197], v[202:205], v[48:51]
	v_mfma_f32_16x16x32_bf16 v[36:39], v[186:189], v[210:213], v[36:39]
	v_mfma_f32_16x16x32_bf16 v[32:35], v[194:197], v[210:213], v[32:35]
	v_mfma_f32_16x16x32_bf16 v[20:23], v[186:189], v[218:221], v[20:23]
	v_mfma_f32_16x16x32_bf16 v[16:19], v[194:197], v[218:221], v[16:19]
	v_mfma_f32_16x16x32_bf16 v[4:7], v[186:189], v[230:233], v[4:7]
	v_mfma_f32_16x16x32_bf16 v[0:3], v[194:197], v[230:233], v[0:3]
	s_barrier
	s_add_i32 s24, s24, 2
	s_add_u32 s34, s34, 0x100
	s_addc_u32 s35, s35, 0
	s_add_u32 s18, s18, 0x100
	s_addc_u32 s19, s19, 0
	s_cmp_gt_u32 s24, 29
	s_cbranch_scc0 .LBB0_919
	s_and_b64 vcc, exec, s[86:87]
	s_cbranch_vccz .LBB0_922
	s_barrier

.LBB0_1393:
	ds_read_b128 v[144:147], v153
	ds_read_b128 v[156:159], v153 offset:1024
	ds_read_b128 v[160:163], v153 offset:2048
	ds_read_b128 v[164:167], v153 offset:3072
	ds_read_b128 v[168:171], v154
	ds_read_b128 v[172:175], v154 offset:1024
	ds_read_b128 v[176:179], v154 offset:2048
	ds_read_b128 v[180:183], v154 offset:3072
	s_add_u32 s3, s88, 0xfffc0080
	s_addc_u32 s37, s89, -1
	s_cmp_eq_u32 s36, 12
	s_cselect_b32 s91, s0, s37
	s_cselect_b32 s90, s1, s3
	s_cselect_b32 s81, s17, s35
	s_cselect_b32 s80, s27, s33
	s_add_i32 m0, s19, 0xc000
	ds_read_b128 v[184:187], v155
	ds_read_b128 v[188:191], v155 offset:1024
	ds_read_b128 v[192:195], v155 offset:2048
	ds_read_b128 v[196:199], v155 offset:3072
	ds_read_b128 v[200:203], v155 offset:4096
	ds_read_b128 v[204:207], v155 offset:5120
	ds_read_b128 v[208:211], v155 offset:6144
	ds_read_b128 v[212:215], v155 offset:7168
	global_load_lds_dwordx4 v136, s[88:89]
	s_add_i32 m0, s19, 0xe000
	s_nop 0
	global_load_lds_dwordx4 v138, s[88:89]
	s_waitcnt vmcnt(8)
	s_waitcnt lgkmcnt(0)
	s_barrier
	v_mfma_f32_16x16x32_bf16 v[124:127], v[144:147], v[184:187], v[124:127]
	v_mfma_f32_16x16x32_bf16 v[120:123], v[160:163], v[184:187], v[120:123]
	v_mfma_f32_16x16x32_bf16 v[108:111], v[144:147], v[192:195], v[108:111]
	v_mfma_f32_16x16x32_bf16 v[104:107], v[160:163], v[192:195], v[104:107]
	v_mfma_f32_16x16x32_bf16 v[92:95], v[144:147], v[200:203], v[92:95]
	v_mfma_f32_16x16x32_bf16 v[88:91], v[160:163], v[200:203], v[88:91]
	v_mfma_f32_16x16x32_bf16 v[76:79], v[144:147], v[208:211], v[76:79]
	v_mfma_f32_16x16x32_bf16 v[72:75], v[160:163], v[208:211], v[72:75]
	v_mfma_f32_16x16x32_bf16 v[124:127], v[156:159], v[188:191], v[124:127]
	v_mfma_f32_16x16x32_bf16 v[120:123], v[164:167], v[188:191], v[120:123]
	v_mfma_f32_16x16x32_bf16 v[108:111], v[156:159], v[196:199], v[108:111]
	v_mfma_f32_16x16x32_bf16 v[104:107], v[164:167], v[196:199], v[104:107]
	v_mfma_f32_16x16x32_bf16 v[92:95], v[156:159], v[204:207], v[92:95]
	v_mfma_f32_16x16x32_bf16 v[88:91], v[164:167], v[204:207], v[88:91]
	v_mfma_f32_16x16x32_bf16 v[76:79], v[156:159], v[212:215], v[76:79]
	v_mfma_f32_16x16x32_bf16 v[72:75], v[164:167], v[212:215], v[72:75]
	v_mfma_f32_16x16x32_bf16 v[116:119], v[168:171], v[184:187], v[116:119]
	v_mfma_f32_16x16x32_bf16 v[112:115], v[176:179], v[184:187], v[112:115]
	v_mfma_f32_16x16x32_bf16 v[100:103], v[168:171], v[192:195], v[100:103]
	v_mfma_f32_16x16x32_bf16 v[96:99], v[176:179], v[192:195], v[96:99]
	v_mfma_f32_16x16x32_bf16 v[84:87], v[168:171], v[200:203], v[84:87]
	v_mfma_f32_16x16x32_bf16 v[80:83], v[176:179], v[200:203], v[80:83]
	v_mfma_f32_16x16x32_bf16 v[68:71], v[168:171], v[208:211], v[68:71]
	v_mfma_f32_16x16x32_bf16 v[64:67], v[176:179], v[208:211], v[64:67]
	v_mfma_f32_16x16x32_bf16 v[116:119], v[172:175], v[188:191], v[116:119]
	v_mfma_f32_16x16x32_bf16 v[112:115], v[180:183], v[188:191], v[112:115]
	v_mfma_f32_16x16x32_bf16 v[100:103], v[172:175], v[196:199], v[100:103]
	v_mfma_f32_16x16x32_bf16 v[96:99], v[180:183], v[196:199], v[96:99]
	v_mfma_f32_16x16x32_bf16 v[84:87], v[172:175], v[204:207], v[84:87]
	v_mfma_f32_16x16x32_bf16 v[80:83], v[180:183], v[204:207], v[80:83]
	v_mfma_f32_16x16x32_bf16 v[68:71], v[172:175], v[212:215], v[68:71]
	v_mfma_f32_16x16x32_bf16 v[64:67], v[180:183], v[212:215], v[64:67]
	s_barrier
	s_add_i32 s3, s57, s18
	s_mov_b32 m0, s3
	ds_read_b128 v[184:187], v155 offset:16384
	ds_read_b128 v[188:191], v155 offset:17408
	ds_read_b128 v[192:195], v155 offset:18432
	ds_read_b128 v[196:199], v155 offset:19456
	ds_read_b128 v[200:203], v155 offset:20480
	ds_read_b128 v[204:207], v155 offset:21504
	ds_read_b128 v[208:211], v155 offset:22528
	ds_read_b128 v[212:215], v155 offset:23552
	global_load_lds_dwordx4 v130, s[80:81]
	s_add_i32 m0, s3, 0x2000
	s_add_u32 s42, s80, 0x40000
	s_addc_u32 s43, s81, 0
	s_add_i32 s3, s58, s18
	global_load_lds_dwordx4 v134, s[80:81]
	s_mov_b32 m0, s3
	s_nop 0
	global_load_lds_dwordx4 v130, s[42:43]
	s_add_i32 m0, s3, 0x2000
	s_nop 0
	global_load_lds_dwordx4 v134, s[42:43]
	s_mov_b32 m0, s19
	s_nop 0
	global_load_lds_dwordx4 v128, s[90:91]
	s_mov_b32 m0, s25
	s_nop 0
	global_load_lds_dwordx4 v132, s[90:91]
	s_waitcnt vmcnt(8)
	s_waitcnt lgkmcnt(0)
	s_barrier
	v_mfma_f32_16x16x32_bf16 v[60:63], v[144:147], v[184:187], v[60:63]
	v_mfma_f32_16x16x32_bf16 v[56:59], v[160:163], v[184:187], v[56:59]
	v_mfma_f32_16x16x32_bf16 v[44:47], v[144:147], v[192:195], v[44:47]
	v_mfma_f32_16x16x32_bf16 v[40:43], v[160:163], v[192:195], v[40:43]
	v_mfma_f32_16x16x32_bf16 v[28:31], v[144:147], v[200:203], v[28:31]
	v_mfma_f32_16x16x32_bf16 v[24:27], v[160:163], v[200:203], v[24:27]
	v_mfma_f32_16x16x32_bf16 v[12:15], v[144:147], v[208:211], v[12:15]
	v_mfma_f32_16x16x32_bf16 v[8:11], v[160:163], v[208:211], v[8:11]
	v_mfma_f32_16x16x32_bf16 v[60:63], v[156:159], v[188:191], v[60:63]
	v_mfma_f32_16x16x32_bf16 v[56:59], v[164:167], v[188:191], v[56:59]
	v_mfma_f32_16x16x32_bf16 v[44:47], v[156:159], v[196:199], v[44:47]
	v_mfma_f32_16x16x32_bf16 v[40:43], v[164:167], v[196:199], v[40:43]
	v_mfma_f32_16x16x32_bf16 v[28:31], v[156:159], v[204:207], v[28:31]
	v_mfma_f32_16x16x32_bf16 v[24:27], v[164:167], v[204:207], v[24:27]
	v_mfma_f32_16x16x32_bf16 v[12:15], v[156:159], v[212:215], v[12:15]
	v_mfma_f32_16x16x32_bf16 v[8:11], v[164:167], v[212:215], v[8:11]
	v_mfma_f32_16x16x32_bf16 v[52:55], v[168:171], v[184:187], v[52:55]
	v_mfma_f32_16x16x32_bf16 v[48:51], v[176:179], v[184:187], v[48:51]
	v_mfma_f32_16x16x32_bf16 v[36:39], v[168:171], v[192:195], v[36:39]
	v_mfma_f32_16x16x32_bf16 v[32:35], v[176:179], v[192:195], v[32:35]
	v_mfma_f32_16x16x32_bf16 v[20:23], v[168:171], v[200:203], v[20:23]
	v_mfma_f32_16x16x32_bf16 v[16:19], v[176:179], v[200:203], v[16:19]
	v_mfma_f32_16x16x32_bf16 v[4:7], v[168:171], v[208:211], v[4:7]
	v_mfma_f32_16x16x32_bf16 v[0:3], v[176:179], v[208:211], v[0:3]
	v_mfma_f32_16x16x32_bf16 v[52:55], v[172:175], v[188:191], v[52:55]
	v_mfma_f32_16x16x32_bf16 v[48:51], v[180:183], v[188:191], v[48:51]
	v_mfma_f32_16x16x32_bf16 v[36:39], v[172:175], v[196:199], v[36:39]
	v_mfma_f32_16x16x32_bf16 v[32:35], v[180:183], v[196:199], v[32:35]
	v_mfma_f32_16x16x32_bf16 v[20:23], v[172:175], v[204:207], v[20:23]
	v_mfma_f32_16x16x32_bf16 v[16:19], v[180:183], v[204:207], v[16:19]
	v_mfma_f32_16x16x32_bf16 v[4:7], v[172:175], v[212:215], v[4:7]
	v_mfma_f32_16x16x32_bf16 v[0:3], v[180:183], v[212:215], v[0:3]
	s_barrier
	s_add_i32 s3, 0, 0x18000
	s_add_i32 s37, 0, 0x1c000
	v_add_u32_e32 v164, s3, v151
	v_add_u32_e32 v180, s37, v151
	ds_read_b128 v[144:147], v164
	ds_read_b128 v[156:159], v164 offset:1024
	ds_read_b128 v[160:163], v164 offset:2048
	ds_read_b128 v[164:167], v164 offset:3072
	ds_read_b128 v[168:171], v180
	ds_read_b128 v[172:175], v180 offset:1024
	ds_read_b128 v[176:179], v180 offset:2048
	ds_read_b128 v[180:183], v180 offset:3072
	s_add_u32 s42, s90, 0x40000
	s_addc_u32 s43, s91, 0
	s_mov_b32 m0, s30
	ds_read_b128 v[184:187], v155 offset:32768
	ds_read_b128 v[188:191], v155 offset:33792
	ds_read_b128 v[192:195], v155 offset:34816
	ds_read_b128 v[196:199], v155 offset:35840
	ds_read_b128 v[200:203], v155 offset:36864
	ds_read_b128 v[204:207], v155 offset:37888
	ds_read_b128 v[208:211], v155 offset:38912
	ds_read_b128 v[212:215], v155 offset:39936
	global_load_lds_dwordx4 v128, s[42:43]
	v_lshl_add_u64 v[222:223], s[42:43], 0, v[132:133]
	s_mov_b32 m0, s31
	s_nop 0
	global_load_lds_dwordx4 v[222:223], off
	s_waitcnt vmcnt(8)
	s_waitcnt lgkmcnt(0)
	s_barrier
	v_mfma_f32_16x16x32_bf16 v[124:127], v[144:147], v[184:187], v[124:127]
	v_mfma_f32_16x16x32_bf16 v[120:123], v[160:163], v[184:187], v[120:123]
	v_mfma_f32_16x16x32_bf16 v[108:111], v[144:147], v[192:195], v[108:111]
	v_mfma_f32_16x16x32_bf16 v[104:107], v[160:163], v[192:195], v[104:107]
	v_mfma_f32_16x16x32_bf16 v[92:95], v[144:147], v[200:203], v[92:95]
	v_mfma_f32_16x16x32_bf16 v[88:91], v[160:163], v[200:203], v[88:91]
	v_mfma_f32_16x16x32_bf16 v[76:79], v[144:147], v[208:211], v[76:79]
	v_mfma_f32_16x16x32_bf16 v[72:75], v[160:163], v[208:211], v[72:75]
	v_mfma_f32_16x16x32_bf16 v[124:127], v[156:159], v[188:191], v[124:127]
	v_mfma_f32_16x16x32_bf16 v[120:123], v[164:167], v[188:191], v[120:123]
	v_mfma_f32_16x16x32_bf16 v[108:111], v[156:159], v[196:199], v[108:111]
	v_mfma_f32_16x16x32_bf16 v[104:107], v[164:167], v[196:199], v[104:107]
	v_mfma_f32_16x16x32_bf16 v[92:95], v[156:159], v[204:207], v[92:95]
	v_mfma_f32_16x16x32_bf16 v[88:91], v[164:167], v[204:207], v[88:91]
	v_mfma_f32_16x16x32_bf16 v[76:79], v[156:159], v[212:215], v[76:79]
	v_mfma_f32_16x16x32_bf16 v[72:75], v[164:167], v[212:215], v[72:75]
	v_mfma_f32_16x16x32_bf16 v[116:119], v[168:171], v[184:187], v[116:119]
	v_mfma_f32_16x16x32_bf16 v[112:115], v[176:179], v[184:187], v[112:115]
	v_mfma_f32_16x16x32_bf16 v[100:103], v[168:171], v[192:195], v[100:103]
	v_mfma_f32_16x16x32_bf16 v[96:99], v[176:179], v[192:195], v[96:99]
	v_mfma_f32_16x16x32_bf16 v[84:87], v[168:171], v[200:203], v[84:87]
	v_mfma_f32_16x16x32_bf16 v[80:83], v[176:179], v[200:203], v[80:83]
	v_mfma_f32_16x16x32_bf16 v[68:71], v[168:171], v[208:211], v[68:71]
	v_mfma_f32_16x16x32_bf16 v[64:67], v[176:179], v[208:211], v[64:67]
	v_mfma_f32_16x16x32_bf16 v[116:119], v[172:175], v[188:191], v[116:119]
	v_mfma_f32_16x16x32_bf16 v[112:115], v[180:183], v[188:191], v[112:115]
	v_mfma_f32_16x16x32_bf16 v[100:103], v[172:175], v[196:199], v[100:103]
	v_mfma_f32_16x16x32_bf16 v[96:99], v[180:183], v[196:199], v[96:99]
	v_mfma_f32_16x16x32_bf16 v[84:87], v[172:175], v[204:207], v[84:87]
	v_mfma_f32_16x16x32_bf16 v[80:83], v[180:183], v[204:207], v[80:83]
	v_mfma_f32_16x16x32_bf16 v[68:71], v[172:175], v[212:215], v[68:71]
	v_mfma_f32_16x16x32_bf16 v[64:67], v[180:183], v[212:215], v[64:67]
	s_barrier
	s_add_i32 s3, s3, s18
	s_add_u32 s42, s80, 0x80
	s_addc_u32 s43, s81, 0
	s_mov_b32 m0, s3
	ds_read_b128 v[184:187], v155 offset:49152
	ds_read_b128 v[188:191], v155 offset:50176
	ds_read_b128 v[192:195], v155 offset:51200
	ds_read_b128 v[196:199], v155 offset:52224
	ds_read_b128 v[200:203], v155 offset:53248
	ds_read_b128 v[204:207], v155 offset:54272
	ds_read_b128 v[208:211], v155 offset:55296
	ds_read_b128 v[212:215], v155 offset:56320
	global_load_lds_dwordx4 v130, s[42:43]
	s_add_i32 m0, s3, 0x2000
	s_add_i32 s3, s37, s18
	global_load_lds_dwordx4 v134, s[42:43]
	s_add_u32 s42, s42, 0x40000
	s_addc_u32 s43, s43, 0
	s_mov_b32 m0, s3
	s_nop 0
	global_load_lds_dwordx4 v130, s[42:43]
	s_add_i32 m0, s3, 0x2000
	s_nop 0
	global_load_lds_dwordx4 v134, s[42:43]
	s_add_u32 s90, s90, 0x80
	s_addc_u32 s91, s91, 0
	s_mov_b32 m0, s53
	s_nop 0
	global_load_lds_dwordx4 v128, s[90:91]
	s_mov_b32 m0, s56
	s_nop 0
	global_load_lds_dwordx4 v132, s[90:91]
	s_waitcnt vmcnt(8)
	s_waitcnt lgkmcnt(0)
	s_barrier
	v_mfma_f32_16x16x32_bf16 v[60:63], v[144:147], v[184:187], v[60:63]
	v_mfma_f32_16x16x32_bf16 v[56:59], v[160:163], v[184:187], v[56:59]
	v_mfma_f32_16x16x32_bf16 v[44:47], v[144:147], v[192:195], v[44:47]
	v_mfma_f32_16x16x32_bf16 v[40:43], v[160:163], v[192:195], v[40:43]
	v_mfma_f32_16x16x32_bf16 v[28:31], v[144:147], v[200:203], v[28:31]
	v_mfma_f32_16x16x32_bf16 v[24:27], v[160:163], v[200:203], v[24:27]
	v_mfma_f32_16x16x32_bf16 v[12:15], v[144:147], v[208:211], v[12:15]
	v_mfma_f32_16x16x32_bf16 v[8:11], v[160:163], v[208:211], v[8:11]
	v_mfma_f32_16x16x32_bf16 v[60:63], v[156:159], v[188:191], v[60:63]
	v_mfma_f32_16x16x32_bf16 v[56:59], v[164:167], v[188:191], v[56:59]
	v_mfma_f32_16x16x32_bf16 v[44:47], v[156:159], v[196:199], v[44:47]
	v_mfma_f32_16x16x32_bf16 v[40:43], v[164:167], v[196:199], v[40:43]
	v_mfma_f32_16x16x32_bf16 v[28:31], v[156:159], v[204:207], v[28:31]
	v_mfma_f32_16x16x32_bf16 v[24:27], v[164:167], v[204:207], v[24:27]
	v_mfma_f32_16x16x32_bf16 v[12:15], v[156:159], v[212:215], v[12:15]
	v_mfma_f32_16x16x32_bf16 v[8:11], v[164:167], v[212:215], v[8:11]
	v_mfma_f32_16x16x32_bf16 v[52:55], v[168:171], v[184:187], v[52:55]
	v_mfma_f32_16x16x32_bf16 v[48:51], v[176:179], v[184:187], v[48:51]
	v_mfma_f32_16x16x32_bf16 v[36:39], v[168:171], v[192:195], v[36:39]
	v_mfma_f32_16x16x32_bf16 v[32:35], v[176:179], v[192:195], v[32:35]
	v_mfma_f32_16x16x32_bf16 v[20:23], v[168:171], v[200:203], v[20:23]
	v_mfma_f32_16x16x32_bf16 v[16:19], v[176:179], v[200:203], v[16:19]
	v_mfma_f32_16x16x32_bf16 v[4:7], v[168:171], v[208:211], v[4:7]
	v_mfma_f32_16x16x32_bf16 v[0:3], v[176:179], v[208:211], v[0:3]
	v_mfma_f32_16x16x32_bf16 v[52:55], v[172:175], v[188:191], v[52:55]
	v_mfma_f32_16x16x32_bf16 v[48:51], v[180:183], v[188:191], v[48:51]
	v_mfma_f32_16x16x32_bf16 v[36:39], v[172:175], v[196:199], v[36:39]
	v_mfma_f32_16x16x32_bf16 v[32:35], v[180:183], v[196:199], v[32:35]
	v_mfma_f32_16x16x32_bf16 v[20:23], v[172:175], v[204:207], v[20:23]
	v_mfma_f32_16x16x32_bf16 v[16:19], v[180:183], v[204:207], v[16:19]
	v_mfma_f32_16x16x32_bf16 v[4:7], v[172:175], v[212:215], v[4:7]
	v_mfma_f32_16x16x32_bf16 v[0:3], v[180:183], v[212:215], v[0:3]
	s_barrier
	s_add_i32 s36, s36, 2
	s_add_u32 s88, s88, 0x100
	s_addc_u32 s89, s89, 0
	s_add_u32 s33, s33, 0x100
	s_addc_u32 s35, s35, 0
	s_cmp_gt_u32 s36, 13
	s_cbranch_scc0 .LBB0_1393
	s_and_b64 vcc, exec, s[12:13]
	s_cbranch_vccz .LBB0_1396
	s_barrier

.LBB0_1417:
	ds_read_b128 v[144:147], v157
	ds_read_b128 v[148:151], v157 offset:1024
	ds_read_b128 v[160:163], v157 offset:2048
	ds_read_b128 v[164:167], v157 offset:3072
	ds_read_b128 v[168:171], v158
	ds_read_b128 v[172:175], v158 offset:1024
	ds_read_b128 v[176:179], v158 offset:2048
	ds_read_b128 v[180:183], v158 offset:3072
	s_add_u32 s3, s34, 0xfffe0080
	s_addc_u32 s42, s35, -1
	s_cmp_eq_u32 s37, 4
	s_cselect_b32 s91, s0, s42
	s_cselect_b32 s90, s1, s3
	s_cselect_b32 s81, s24, s36
	s_cselect_b32 s80, s27, s33
	s_add_i32 m0, s19, 0xc000
	ds_read_b128 v[184:187], v159
	ds_read_b128 v[188:191], v159 offset:1024
	ds_read_b128 v[192:195], v159 offset:2048
	ds_read_b128 v[196:199], v159 offset:3072
	ds_read_b128 v[200:203], v159 offset:4096
	ds_read_b128 v[204:207], v159 offset:5120
	ds_read_b128 v[208:211], v159 offset:6144
	ds_read_b128 v[212:215], v159 offset:7168
	global_load_lds_dwordx4 v136, s[34:35]
	s_add_i32 m0, s19, 0xe000
	s_nop 0
	global_load_lds_dwordx4 v138, s[34:35]
	s_waitcnt vmcnt(8)
	s_waitcnt lgkmcnt(0)
	s_barrier
	v_mfma_f32_16x16x32_bf16 v[124:127], v[144:147], v[184:187], v[124:127]
	v_mfma_f32_16x16x32_bf16 v[120:123], v[160:163], v[184:187], v[120:123]
	v_mfma_f32_16x16x32_bf16 v[108:111], v[144:147], v[192:195], v[108:111]
	v_mfma_f32_16x16x32_bf16 v[104:107], v[160:163], v[192:195], v[104:107]
	v_mfma_f32_16x16x32_bf16 v[92:95], v[144:147], v[200:203], v[92:95]
	v_mfma_f32_16x16x32_bf16 v[88:91], v[160:163], v[200:203], v[88:91]
	v_mfma_f32_16x16x32_bf16 v[76:79], v[144:147], v[208:211], v[76:79]
	v_mfma_f32_16x16x32_bf16 v[72:75], v[160:163], v[208:211], v[72:75]
	v_mfma_f32_16x16x32_bf16 v[124:127], v[148:151], v[188:191], v[124:127]
	v_mfma_f32_16x16x32_bf16 v[120:123], v[164:167], v[188:191], v[120:123]
	v_mfma_f32_16x16x32_bf16 v[108:111], v[148:151], v[196:199], v[108:111]
	v_mfma_f32_16x16x32_bf16 v[104:107], v[164:167], v[196:199], v[104:107]
	v_mfma_f32_16x16x32_bf16 v[92:95], v[148:151], v[204:207], v[92:95]
	v_mfma_f32_16x16x32_bf16 v[88:91], v[164:167], v[204:207], v[88:91]
	v_mfma_f32_16x16x32_bf16 v[76:79], v[148:151], v[212:215], v[76:79]
	v_mfma_f32_16x16x32_bf16 v[72:75], v[164:167], v[212:215], v[72:75]
	v_mfma_f32_16x16x32_bf16 v[116:119], v[168:171], v[184:187], v[116:119]
	v_mfma_f32_16x16x32_bf16 v[112:115], v[176:179], v[184:187], v[112:115]
	v_mfma_f32_16x16x32_bf16 v[100:103], v[168:171], v[192:195], v[100:103]
	v_mfma_f32_16x16x32_bf16 v[96:99], v[176:179], v[192:195], v[96:99]
	v_mfma_f32_16x16x32_bf16 v[84:87], v[168:171], v[200:203], v[84:87]
	v_mfma_f32_16x16x32_bf16 v[80:83], v[176:179], v[200:203], v[80:83]
	v_mfma_f32_16x16x32_bf16 v[68:71], v[168:171], v[208:211], v[68:71]
	v_mfma_f32_16x16x32_bf16 v[64:67], v[176:179], v[208:211], v[64:67]
	v_mfma_f32_16x16x32_bf16 v[116:119], v[172:175], v[188:191], v[116:119]
	v_mfma_f32_16x16x32_bf16 v[112:115], v[180:183], v[188:191], v[112:115]
	v_mfma_f32_16x16x32_bf16 v[100:103], v[172:175], v[196:199], v[100:103]
	v_mfma_f32_16x16x32_bf16 v[96:99], v[180:183], v[196:199], v[96:99]
	v_mfma_f32_16x16x32_bf16 v[84:87], v[172:175], v[204:207], v[84:87]
	v_mfma_f32_16x16x32_bf16 v[80:83], v[180:183], v[204:207], v[80:83]
	v_mfma_f32_16x16x32_bf16 v[68:71], v[172:175], v[212:215], v[68:71]
	v_mfma_f32_16x16x32_bf16 v[64:67], v[180:183], v[212:215], v[64:67]
	s_barrier
	s_add_i32 s3, s78, s18
	s_mov_b32 m0, s3
	ds_read_b128 v[184:187], v159 offset:16384
	ds_read_b128 v[188:191], v159 offset:17408
	ds_read_b128 v[192:195], v159 offset:18432
	ds_read_b128 v[196:199], v159 offset:19456
	ds_read_b128 v[200:203], v159 offset:20480
	ds_read_b128 v[204:207], v159 offset:21504
	ds_read_b128 v[208:211], v159 offset:22528
	ds_read_b128 v[212:215], v159 offset:23552
	global_load_lds_dwordx4 v130, s[80:81]
	s_add_i32 m0, s3, 0x2000
	s_add_u32 s42, s80, 0x20000
	s_addc_u32 s43, s81, 0
	s_add_i32 s3, s79, s18
	global_load_lds_dwordx4 v134, s[80:81]
	s_mov_b32 m0, s3
	s_nop 0
	global_load_lds_dwordx4 v130, s[42:43]
	s_add_i32 m0, s3, 0x2000
	s_nop 0
	global_load_lds_dwordx4 v134, s[42:43]
	s_mov_b32 m0, s19
	s_nop 0
	global_load_lds_dwordx4 v128, s[90:91]
	s_mov_b32 m0, s25
	s_nop 0
	global_load_lds_dwordx4 v132, s[90:91]
	s_waitcnt vmcnt(8)
	s_waitcnt lgkmcnt(0)
	s_barrier
	v_mfma_f32_16x16x32_bf16 v[60:63], v[144:147], v[184:187], v[60:63]
	v_mfma_f32_16x16x32_bf16 v[56:59], v[160:163], v[184:187], v[56:59]
	v_mfma_f32_16x16x32_bf16 v[44:47], v[144:147], v[192:195], v[44:47]
	v_mfma_f32_16x16x32_bf16 v[40:43], v[160:163], v[192:195], v[40:43]
	v_mfma_f32_16x16x32_bf16 v[28:31], v[144:147], v[200:203], v[28:31]
	v_mfma_f32_16x16x32_bf16 v[24:27], v[160:163], v[200:203], v[24:27]
	v_mfma_f32_16x16x32_bf16 v[12:15], v[144:147], v[208:211], v[12:15]
	v_mfma_f32_16x16x32_bf16 v[8:11], v[160:163], v[208:211], v[8:11]
	v_mfma_f32_16x16x32_bf16 v[60:63], v[148:151], v[188:191], v[60:63]
	v_mfma_f32_16x16x32_bf16 v[56:59], v[164:167], v[188:191], v[56:59]
	v_mfma_f32_16x16x32_bf16 v[44:47], v[148:151], v[196:199], v[44:47]
	v_mfma_f32_16x16x32_bf16 v[40:43], v[164:167], v[196:199], v[40:43]
	v_mfma_f32_16x16x32_bf16 v[28:31], v[148:151], v[204:207], v[28:31]
	v_mfma_f32_16x16x32_bf16 v[24:27], v[164:167], v[204:207], v[24:27]
	v_mfma_f32_16x16x32_bf16 v[12:15], v[148:151], v[212:215], v[12:15]
	v_mfma_f32_16x16x32_bf16 v[8:11], v[164:167], v[212:215], v[8:11]
	v_mfma_f32_16x16x32_bf16 v[52:55], v[168:171], v[184:187], v[52:55]
	v_mfma_f32_16x16x32_bf16 v[48:51], v[176:179], v[184:187], v[48:51]
	v_mfma_f32_16x16x32_bf16 v[36:39], v[168:171], v[192:195], v[36:39]
	v_mfma_f32_16x16x32_bf16 v[32:35], v[176:179], v[192:195], v[32:35]
	v_mfma_f32_16x16x32_bf16 v[20:23], v[168:171], v[200:203], v[20:23]
	v_mfma_f32_16x16x32_bf16 v[16:19], v[176:179], v[200:203], v[16:19]
	v_mfma_f32_16x16x32_bf16 v[4:7], v[168:171], v[208:211], v[4:7]
	v_mfma_f32_16x16x32_bf16 v[0:3], v[176:179], v[208:211], v[0:3]
	v_mfma_f32_16x16x32_bf16 v[52:55], v[172:175], v[188:191], v[52:55]
	v_mfma_f32_16x16x32_bf16 v[48:51], v[180:183], v[188:191], v[48:51]
	v_mfma_f32_16x16x32_bf16 v[36:39], v[172:175], v[196:199], v[36:39]
	v_mfma_f32_16x16x32_bf16 v[32:35], v[180:183], v[196:199], v[32:35]
	v_mfma_f32_16x16x32_bf16 v[20:23], v[172:175], v[204:207], v[20:23]
	v_mfma_f32_16x16x32_bf16 v[16:19], v[180:183], v[204:207], v[16:19]
	v_mfma_f32_16x16x32_bf16 v[4:7], v[172:175], v[212:215], v[4:7]
	v_mfma_f32_16x16x32_bf16 v[0:3], v[180:183], v[212:215], v[0:3]
	s_barrier
	s_add_i32 s3, 0, 0x18000
	s_add_i32 s44, 0, 0x1c000
	v_add_u32_e32 v164, s3, v155
	v_add_u32_e32 v180, s44, v155
	ds_read_b128 v[144:147], v164
	ds_read_b128 v[148:151], v164 offset:1024
	ds_read_b128 v[160:163], v164 offset:2048
	ds_read_b128 v[164:167], v164 offset:3072
	ds_read_b128 v[168:171], v180
	ds_read_b128 v[172:175], v180 offset:1024
	ds_read_b128 v[176:179], v180 offset:2048
	ds_read_b128 v[180:183], v180 offset:3072
	s_add_u32 s42, s90, 0x20000
	s_addc_u32 s43, s91, 0
	s_mov_b32 m0, s30
	ds_read_b128 v[184:187], v159 offset:32768
	ds_read_b128 v[188:191], v159 offset:33792
	ds_read_b128 v[192:195], v159 offset:34816
	ds_read_b128 v[196:199], v159 offset:35840
	ds_read_b128 v[200:203], v159 offset:36864
	ds_read_b128 v[204:207], v159 offset:37888
	ds_read_b128 v[208:211], v159 offset:38912
	ds_read_b128 v[212:215], v159 offset:39936
	global_load_lds_dwordx4 v128, s[42:43]
	v_lshl_add_u64 v[222:223], s[42:43], 0, v[132:133]
	s_mov_b32 m0, s31
	s_nop 0
	global_load_lds_dwordx4 v[222:223], off
	s_waitcnt vmcnt(8)
	s_waitcnt lgkmcnt(0)
	s_barrier
	v_mfma_f32_16x16x32_bf16 v[124:127], v[144:147], v[184:187], v[124:127]
	v_mfma_f32_16x16x32_bf16 v[120:123], v[160:163], v[184:187], v[120:123]
	v_mfma_f32_16x16x32_bf16 v[108:111], v[144:147], v[192:195], v[108:111]
	v_mfma_f32_16x16x32_bf16 v[104:107], v[160:163], v[192:195], v[104:107]
	v_mfma_f32_16x16x32_bf16 v[92:95], v[144:147], v[200:203], v[92:95]
	v_mfma_f32_16x16x32_bf16 v[88:91], v[160:163], v[200:203], v[88:91]
	v_mfma_f32_16x16x32_bf16 v[76:79], v[144:147], v[208:211], v[76:79]
	v_mfma_f32_16x16x32_bf16 v[72:75], v[160:163], v[208:211], v[72:75]
	v_mfma_f32_16x16x32_bf16 v[124:127], v[148:151], v[188:191], v[124:127]
	v_mfma_f32_16x16x32_bf16 v[120:123], v[164:167], v[188:191], v[120:123]
	v_mfma_f32_16x16x32_bf16 v[108:111], v[148:151], v[196:199], v[108:111]
	v_mfma_f32_16x16x32_bf16 v[104:107], v[164:167], v[196:199], v[104:107]
	v_mfma_f32_16x16x32_bf16 v[92:95], v[148:151], v[204:207], v[92:95]
	v_mfma_f32_16x16x32_bf16 v[88:91], v[164:167], v[204:207], v[88:91]
	v_mfma_f32_16x16x32_bf16 v[76:79], v[148:151], v[212:215], v[76:79]
	v_mfma_f32_16x16x32_bf16 v[72:75], v[164:167], v[212:215], v[72:75]
	v_mfma_f32_16x16x32_bf16 v[116:119], v[168:171], v[184:187], v[116:119]
	v_mfma_f32_16x16x32_bf16 v[112:115], v[176:179], v[184:187], v[112:115]
	v_mfma_f32_16x16x32_bf16 v[100:103], v[168:171], v[192:195], v[100:103]
	v_mfma_f32_16x16x32_bf16 v[96:99], v[176:179], v[192:195], v[96:99]
	v_mfma_f32_16x16x32_bf16 v[84:87], v[168:171], v[200:203], v[84:87]
	v_mfma_f32_16x16x32_bf16 v[80:83], v[176:179], v[200:203], v[80:83]
	v_mfma_f32_16x16x32_bf16 v[68:71], v[168:171], v[208:211], v[68:71]
	v_mfma_f32_16x16x32_bf16 v[64:67], v[176:179], v[208:211], v[64:67]
	v_mfma_f32_16x16x32_bf16 v[116:119], v[172:175], v[188:191], v[116:119]
	v_mfma_f32_16x16x32_bf16 v[112:115], v[180:183], v[188:191], v[112:115]
	v_mfma_f32_16x16x32_bf16 v[100:103], v[172:175], v[196:199], v[100:103]
	v_mfma_f32_16x16x32_bf16 v[96:99], v[180:183], v[196:199], v[96:99]
	v_mfma_f32_16x16x32_bf16 v[84:87], v[172:175], v[204:207], v[84:87]
	v_mfma_f32_16x16x32_bf16 v[80:83], v[180:183], v[204:207], v[80:83]
	v_mfma_f32_16x16x32_bf16 v[68:71], v[172:175], v[212:215], v[68:71]
	v_mfma_f32_16x16x32_bf16 v[64:67], v[180:183], v[212:215], v[64:67]
	s_barrier
	s_add_i32 s3, s3, s18
	s_add_u32 s42, s80, 0x80
	s_addc_u32 s43, s81, 0
	s_mov_b32 m0, s3
	ds_read_b128 v[184:187], v159 offset:49152
	ds_read_b128 v[188:191], v159 offset:50176
	ds_read_b128 v[192:195], v159 offset:51200
	ds_read_b128 v[196:199], v159 offset:52224
	ds_read_b128 v[200:203], v159 offset:53248
	ds_read_b128 v[204:207], v159 offset:54272
	ds_read_b128 v[208:211], v159 offset:55296
	ds_read_b128 v[212:215], v159 offset:56320
	global_load_lds_dwordx4 v130, s[42:43]
	s_add_i32 m0, s3, 0x2000
	s_add_i32 s3, s44, s18
	global_load_lds_dwordx4 v134, s[42:43]
	s_add_u32 s42, s42, 0x20000
	s_addc_u32 s43, s43, 0
	s_mov_b32 m0, s3
	s_nop 0
	global_load_lds_dwordx4 v130, s[42:43]
	s_add_i32 m0, s3, 0x2000
	s_nop 0
	global_load_lds_dwordx4 v134, s[42:43]
	s_add_u32 s90, s90, 0x80
	s_addc_u32 s91, s91, 0
	s_mov_b32 m0, s58
	s_nop 0
	global_load_lds_dwordx4 v128, s[90:91]
	s_mov_b32 m0, s59
	s_nop 0
	global_load_lds_dwordx4 v132, s[90:91]
	s_waitcnt vmcnt(8)
	s_waitcnt lgkmcnt(0)
	s_barrier
	v_mfma_f32_16x16x32_bf16 v[60:63], v[144:147], v[184:187], v[60:63]
	v_mfma_f32_16x16x32_bf16 v[56:59], v[160:163], v[184:187], v[56:59]
	v_mfma_f32_16x16x32_bf16 v[44:47], v[144:147], v[192:195], v[44:47]
	v_mfma_f32_16x16x32_bf16 v[40:43], v[160:163], v[192:195], v[40:43]
	v_mfma_f32_16x16x32_bf16 v[28:31], v[144:147], v[200:203], v[28:31]
	v_mfma_f32_16x16x32_bf16 v[24:27], v[160:163], v[200:203], v[24:27]
	v_mfma_f32_16x16x32_bf16 v[12:15], v[144:147], v[208:211], v[12:15]
	v_mfma_f32_16x16x32_bf16 v[8:11], v[160:163], v[208:211], v[8:11]
	v_mfma_f32_16x16x32_bf16 v[60:63], v[148:151], v[188:191], v[60:63]
	v_mfma_f32_16x16x32_bf16 v[56:59], v[164:167], v[188:191], v[56:59]
	v_mfma_f32_16x16x32_bf16 v[44:47], v[148:151], v[196:199], v[44:47]
	v_mfma_f32_16x16x32_bf16 v[40:43], v[164:167], v[196:199], v[40:43]
	v_mfma_f32_16x16x32_bf16 v[28:31], v[148:151], v[204:207], v[28:31]
	v_mfma_f32_16x16x32_bf16 v[24:27], v[164:167], v[204:207], v[24:27]
	v_mfma_f32_16x16x32_bf16 v[12:15], v[148:151], v[212:215], v[12:15]
	v_mfma_f32_16x16x32_bf16 v[8:11], v[164:167], v[212:215], v[8:11]
	v_mfma_f32_16x16x32_bf16 v[52:55], v[168:171], v[184:187], v[52:55]
	v_mfma_f32_16x16x32_bf16 v[48:51], v[176:179], v[184:187], v[48:51]
	v_mfma_f32_16x16x32_bf16 v[36:39], v[168:171], v[192:195], v[36:39]
	v_mfma_f32_16x16x32_bf16 v[32:35], v[176:179], v[192:195], v[32:35]
	v_mfma_f32_16x16x32_bf16 v[20:23], v[168:171], v[200:203], v[20:23]
	v_mfma_f32_16x16x32_bf16 v[16:19], v[176:179], v[200:203], v[16:19]
	v_mfma_f32_16x16x32_bf16 v[4:7], v[168:171], v[208:211], v[4:7]
	v_mfma_f32_16x16x32_bf16 v[0:3], v[176:179], v[208:211], v[0:3]
	v_mfma_f32_16x16x32_bf16 v[52:55], v[172:175], v[188:191], v[52:55]
	v_mfma_f32_16x16x32_bf16 v[48:51], v[180:183], v[188:191], v[48:51]
	v_mfma_f32_16x16x32_bf16 v[36:39], v[172:175], v[196:199], v[36:39]
	v_mfma_f32_16x16x32_bf16 v[32:35], v[180:183], v[196:199], v[32:35]
	v_mfma_f32_16x16x32_bf16 v[20:23], v[172:175], v[204:207], v[20:23]
	v_mfma_f32_16x16x32_bf16 v[16:19], v[180:183], v[204:207], v[16:19]
	v_mfma_f32_16x16x32_bf16 v[4:7], v[172:175], v[212:215], v[4:7]
	v_mfma_f32_16x16x32_bf16 v[0:3], v[180:183], v[212:215], v[0:3]
	s_barrier
	s_add_i32 s37, s37, 2
	s_add_u32 s34, s34, 0x100
	s_addc_u32 s35, s35, 0
	s_add_u32 s33, s33, 0x100
	s_addc_u32 s36, s36, 0
	s_cmp_gt_u32 s37, 5
	s_cbranch_scc0 .LBB0_1417
	s_and_b64 vcc, exec, s[14:15]
	s_cbranch_vccz .LBB0_1420
	s_barrier

.LBB0_1493:
	ds_read_b128 v[140:143], v149
	ds_read_b128 v[152:155], v149 offset:1024
	ds_read_b128 v[156:159], v149 offset:2048
	ds_read_b128 v[160:163], v149 offset:3072
	ds_read_b128 v[164:167], v150
	ds_read_b128 v[168:171], v150 offset:1024
	ds_read_b128 v[172:175], v150 offset:2048
	ds_read_b128 v[176:179], v150 offset:3072
	s_add_u32 s3, s86, 0xfff80080
	s_addc_u32 s33, s87, -1
	s_cmp_eq_u32 s27, 28
	s_cselect_b32 s89, s0, s33
	s_cselect_b32 s88, s1, s3
	s_cselect_b32 s81, s15, s24
	s_cselect_b32 s80, s17, s19
	s_add_i32 m0, s30, 0xc000
	ds_read_b128 v[180:183], v151
	ds_read_b128 v[184:187], v151 offset:1024
	ds_read_b128 v[188:191], v151 offset:2048
	ds_read_b128 v[192:195], v151 offset:3072
	ds_read_b128 v[196:199], v151 offset:4096
	ds_read_b128 v[200:203], v151 offset:5120
	ds_read_b128 v[204:207], v151 offset:6144
	ds_read_b128 v[208:211], v151 offset:7168
	global_load_lds_dwordx4 v132, s[86:87]
	s_add_i32 m0, s30, 0xe000
	s_nop 0
	global_load_lds_dwordx4 v134, s[86:87]
	s_waitcnt vmcnt(8)
	s_waitcnt lgkmcnt(0)
	s_barrier
	v_mfma_f32_16x16x32_bf16 v[124:127], v[140:143], v[180:183], v[124:127]
	v_mfma_f32_16x16x32_bf16 v[120:123], v[156:159], v[180:183], v[120:123]
	v_mfma_f32_16x16x32_bf16 v[108:111], v[140:143], v[188:191], v[108:111]
	v_mfma_f32_16x16x32_bf16 v[104:107], v[156:159], v[188:191], v[104:107]
	v_mfma_f32_16x16x32_bf16 v[92:95], v[140:143], v[196:199], v[92:95]
	v_mfma_f32_16x16x32_bf16 v[88:91], v[156:159], v[196:199], v[88:91]
	v_mfma_f32_16x16x32_bf16 v[76:79], v[140:143], v[204:207], v[76:79]
	v_mfma_f32_16x16x32_bf16 v[72:75], v[156:159], v[204:207], v[72:75]
	v_mfma_f32_16x16x32_bf16 v[124:127], v[152:155], v[184:187], v[124:127]
	v_mfma_f32_16x16x32_bf16 v[120:123], v[160:163], v[184:187], v[120:123]
	v_mfma_f32_16x16x32_bf16 v[108:111], v[152:155], v[192:195], v[108:111]
	v_mfma_f32_16x16x32_bf16 v[104:107], v[160:163], v[192:195], v[104:107]
	v_mfma_f32_16x16x32_bf16 v[92:95], v[152:155], v[200:203], v[92:95]
	v_mfma_f32_16x16x32_bf16 v[88:91], v[160:163], v[200:203], v[88:91]
	v_mfma_f32_16x16x32_bf16 v[76:79], v[152:155], v[208:211], v[76:79]
	v_mfma_f32_16x16x32_bf16 v[72:75], v[160:163], v[208:211], v[72:75]
	v_mfma_f32_16x16x32_bf16 v[116:119], v[164:167], v[180:183], v[116:119]
	v_mfma_f32_16x16x32_bf16 v[112:115], v[172:175], v[180:183], v[112:115]
	v_mfma_f32_16x16x32_bf16 v[100:103], v[164:167], v[188:191], v[100:103]
	v_mfma_f32_16x16x32_bf16 v[96:99], v[172:175], v[188:191], v[96:99]
	v_mfma_f32_16x16x32_bf16 v[84:87], v[164:167], v[196:199], v[84:87]
	v_mfma_f32_16x16x32_bf16 v[80:83], v[172:175], v[196:199], v[80:83]
	v_mfma_f32_16x16x32_bf16 v[68:71], v[164:167], v[204:207], v[68:71]
	v_mfma_f32_16x16x32_bf16 v[64:67], v[172:175], v[204:207], v[64:67]
	v_mfma_f32_16x16x32_bf16 v[116:119], v[168:171], v[184:187], v[116:119]
	v_mfma_f32_16x16x32_bf16 v[112:115], v[176:179], v[184:187], v[112:115]
	v_mfma_f32_16x16x32_bf16 v[100:103], v[168:171], v[192:195], v[100:103]
	v_mfma_f32_16x16x32_bf16 v[96:99], v[176:179], v[192:195], v[96:99]
	v_mfma_f32_16x16x32_bf16 v[84:87], v[168:171], v[200:203], v[84:87]
	v_mfma_f32_16x16x32_bf16 v[80:83], v[176:179], v[200:203], v[80:83]
	v_mfma_f32_16x16x32_bf16 v[68:71], v[168:171], v[208:211], v[68:71]
	v_mfma_f32_16x16x32_bf16 v[64:67], v[176:179], v[208:211], v[64:67]
	s_barrier
	s_add_i32 s3, s59, s25
	s_mov_b32 m0, s3
	ds_read_b128 v[180:183], v151 offset:16384
	ds_read_b128 v[184:187], v151 offset:17408
	ds_read_b128 v[188:191], v151 offset:18432
	ds_read_b128 v[192:195], v151 offset:19456
	ds_read_b128 v[196:199], v151 offset:20480
	ds_read_b128 v[200:203], v151 offset:21504
	ds_read_b128 v[204:207], v151 offset:22528
	ds_read_b128 v[208:211], v151 offset:23552
	global_load_lds_dwordx4 v128, s[80:81]
	s_add_i32 m0, s3, 0x2000
	s_add_u32 s36, s80, 0x80000
	s_addc_u32 s37, s81, 0
	s_add_i32 s3, s68, s25
	global_load_lds_dwordx4 v130, s[80:81]
	s_mov_b32 m0, s3
	s_nop 0
	global_load_lds_dwordx4 v128, s[36:37]
	s_add_i32 m0, s3, 0x2000
	s_nop 0
	global_load_lds_dwordx4 v130, s[36:37]
	s_mov_b32 m0, s30
	s_nop 0
	global_load_lds_dwordx4 v128, s[88:89]
	s_mov_b32 m0, s31
	s_nop 0
	global_load_lds_dwordx4 v130, s[88:89]
	s_waitcnt vmcnt(8)
	s_waitcnt lgkmcnt(0)
	s_barrier
	v_mfma_f32_16x16x32_bf16 v[60:63], v[140:143], v[180:183], v[60:63]
	v_mfma_f32_16x16x32_bf16 v[56:59], v[156:159], v[180:183], v[56:59]
	v_mfma_f32_16x16x32_bf16 v[44:47], v[140:143], v[188:191], v[44:47]
	v_mfma_f32_16x16x32_bf16 v[40:43], v[156:159], v[188:191], v[40:43]
	v_mfma_f32_16x16x32_bf16 v[28:31], v[140:143], v[196:199], v[28:31]
	v_mfma_f32_16x16x32_bf16 v[24:27], v[156:159], v[196:199], v[24:27]
	v_mfma_f32_16x16x32_bf16 v[12:15], v[140:143], v[204:207], v[12:15]
	v_mfma_f32_16x16x32_bf16 v[8:11], v[156:159], v[204:207], v[8:11]
	v_mfma_f32_16x16x32_bf16 v[60:63], v[152:155], v[184:187], v[60:63]
	v_mfma_f32_16x16x32_bf16 v[56:59], v[160:163], v[184:187], v[56:59]
	v_mfma_f32_16x16x32_bf16 v[44:47], v[152:155], v[192:195], v[44:47]
	v_mfma_f32_16x16x32_bf16 v[40:43], v[160:163], v[192:195], v[40:43]
	v_mfma_f32_16x16x32_bf16 v[28:31], v[152:155], v[200:203], v[28:31]
	v_mfma_f32_16x16x32_bf16 v[24:27], v[160:163], v[200:203], v[24:27]
	v_mfma_f32_16x16x32_bf16 v[12:15], v[152:155], v[208:211], v[12:15]
	v_mfma_f32_16x16x32_bf16 v[8:11], v[160:163], v[208:211], v[8:11]
	v_mfma_f32_16x16x32_bf16 v[52:55], v[164:167], v[180:183], v[52:55]
	v_mfma_f32_16x16x32_bf16 v[48:51], v[172:175], v[180:183], v[48:51]
	v_mfma_f32_16x16x32_bf16 v[36:39], v[164:167], v[188:191], v[36:39]
	v_mfma_f32_16x16x32_bf16 v[32:35], v[172:175], v[188:191], v[32:35]
	v_mfma_f32_16x16x32_bf16 v[20:23], v[164:167], v[196:199], v[20:23]
	v_mfma_f32_16x16x32_bf16 v[16:19], v[172:175], v[196:199], v[16:19]
	v_mfma_f32_16x16x32_bf16 v[4:7], v[164:167], v[204:207], v[4:7]
	v_mfma_f32_16x16x32_bf16 v[0:3], v[172:175], v[204:207], v[0:3]
	v_mfma_f32_16x16x32_bf16 v[52:55], v[168:171], v[184:187], v[52:55]
	v_mfma_f32_16x16x32_bf16 v[48:51], v[176:179], v[184:187], v[48:51]
	v_mfma_f32_16x16x32_bf16 v[36:39], v[168:171], v[192:195], v[36:39]
	v_mfma_f32_16x16x32_bf16 v[32:35], v[176:179], v[192:195], v[32:35]
	v_mfma_f32_16x16x32_bf16 v[20:23], v[168:171], v[200:203], v[20:23]
	v_mfma_f32_16x16x32_bf16 v[16:19], v[176:179], v[200:203], v[16:19]
	v_mfma_f32_16x16x32_bf16 v[4:7], v[168:171], v[208:211], v[4:7]
	v_mfma_f32_16x16x32_bf16 v[0:3], v[176:179], v[208:211], v[0:3]
	s_barrier
	s_add_i32 s3, 0, 0x18000
	s_add_i32 s33, 0, 0x1c000
	v_add_u32_e32 v160, s3, v147
	v_add_u32_e32 v176, s33, v147
	ds_read_b128 v[140:143], v160
	ds_read_b128 v[152:155], v160 offset:1024
	ds_read_b128 v[156:159], v160 offset:2048
	ds_read_b128 v[160:163], v160 offset:3072
	ds_read_b128 v[164:167], v176
	ds_read_b128 v[168:171], v176 offset:1024
	ds_read_b128 v[172:175], v176 offset:2048
	ds_read_b128 v[176:179], v176 offset:3072
	s_add_u32 s36, s88, 0x80000
	s_addc_u32 s37, s89, 0
	s_mov_b32 m0, s52
	ds_read_b128 v[180:183], v151 offset:32768
	ds_read_b128 v[184:187], v151 offset:33792
	ds_read_b128 v[188:191], v151 offset:34816
	ds_read_b128 v[192:195], v151 offset:35840
	ds_read_b128 v[196:199], v151 offset:36864
	ds_read_b128 v[200:203], v151 offset:37888
	ds_read_b128 v[204:207], v151 offset:38912
	ds_read_b128 v[208:211], v151 offset:39936
	global_load_lds_dwordx4 v128, s[36:37]
	v_lshl_add_u64 v[218:219], s[36:37], 0, v[130:131]
	s_mov_b32 m0, s53
	s_nop 0
	global_load_lds_dwordx4 v[218:219], off
	s_waitcnt vmcnt(8)
	s_waitcnt lgkmcnt(0)
	s_barrier
	v_mfma_f32_16x16x32_bf16 v[124:127], v[140:143], v[180:183], v[124:127]
	v_mfma_f32_16x16x32_bf16 v[120:123], v[156:159], v[180:183], v[120:123]
	v_mfma_f32_16x16x32_bf16 v[108:111], v[140:143], v[188:191], v[108:111]
	v_mfma_f32_16x16x32_bf16 v[104:107], v[156:159], v[188:191], v[104:107]
	v_mfma_f32_16x16x32_bf16 v[92:95], v[140:143], v[196:199], v[92:95]
	v_mfma_f32_16x16x32_bf16 v[88:91], v[156:159], v[196:199], v[88:91]
	v_mfma_f32_16x16x32_bf16 v[76:79], v[140:143], v[204:207], v[76:79]
	v_mfma_f32_16x16x32_bf16 v[72:75], v[156:159], v[204:207], v[72:75]
	v_mfma_f32_16x16x32_bf16 v[124:127], v[152:155], v[184:187], v[124:127]
	v_mfma_f32_16x16x32_bf16 v[120:123], v[160:163], v[184:187], v[120:123]
	v_mfma_f32_16x16x32_bf16 v[108:111], v[152:155], v[192:195], v[108:111]
	v_mfma_f32_16x16x32_bf16 v[104:107], v[160:163], v[192:195], v[104:107]
	v_mfma_f32_16x16x32_bf16 v[92:95], v[152:155], v[200:203], v[92:95]
	v_mfma_f32_16x16x32_bf16 v[88:91], v[160:163], v[200:203], v[88:91]
	v_mfma_f32_16x16x32_bf16 v[76:79], v[152:155], v[208:211], v[76:79]
	v_mfma_f32_16x16x32_bf16 v[72:75], v[160:163], v[208:211], v[72:75]
	v_mfma_f32_16x16x32_bf16 v[116:119], v[164:167], v[180:183], v[116:119]
	v_mfma_f32_16x16x32_bf16 v[112:115], v[172:175], v[180:183], v[112:115]
	v_mfma_f32_16x16x32_bf16 v[100:103], v[164:167], v[188:191], v[100:103]
	v_mfma_f32_16x16x32_bf16 v[96:99], v[172:175], v[188:191], v[96:99]
	v_mfma_f32_16x16x32_bf16 v[84:87], v[164:167], v[196:199], v[84:87]
	v_mfma_f32_16x16x32_bf16 v[80:83], v[172:175], v[196:199], v[80:83]
	v_mfma_f32_16x16x32_bf16 v[68:71], v[164:167], v[204:207], v[68:71]
	v_mfma_f32_16x16x32_bf16 v[64:67], v[172:175], v[204:207], v[64:67]
	v_mfma_f32_16x16x32_bf16 v[116:119], v[168:171], v[184:187], v[116:119]
	v_mfma_f32_16x16x32_bf16 v[112:115], v[176:179], v[184:187], v[112:115]
	v_mfma_f32_16x16x32_bf16 v[100:103], v[168:171], v[192:195], v[100:103]
	v_mfma_f32_16x16x32_bf16 v[96:99], v[176:179], v[192:195], v[96:99]
	v_mfma_f32_16x16x32_bf16 v[84:87], v[168:171], v[200:203], v[84:87]
	v_mfma_f32_16x16x32_bf16 v[80:83], v[176:179], v[200:203], v[80:83]
	v_mfma_f32_16x16x32_bf16 v[68:71], v[168:171], v[208:211], v[68:71]
	v_mfma_f32_16x16x32_bf16 v[64:67], v[176:179], v[208:211], v[64:67]
	s_barrier
	s_add_i32 s3, s3, s25
	s_add_u32 s36, s80, 0x80
	s_addc_u32 s37, s81, 0
	s_mov_b32 m0, s3
	ds_read_b128 v[180:183], v151 offset:49152
	ds_read_b128 v[184:187], v151 offset:50176
	ds_read_b128 v[188:191], v151 offset:51200
	ds_read_b128 v[192:195], v151 offset:52224
	ds_read_b128 v[196:199], v151 offset:53248
	ds_read_b128 v[200:203], v151 offset:54272
	ds_read_b128 v[204:207], v151 offset:55296
	ds_read_b128 v[208:211], v151 offset:56320
	global_load_lds_dwordx4 v128, s[36:37]
	s_add_i32 m0, s3, 0x2000
	s_add_i32 s3, s33, s25
	global_load_lds_dwordx4 v130, s[36:37]
	s_add_u32 s36, s36, 0x80000
	s_addc_u32 s37, s37, 0
	s_mov_b32 m0, s3
	s_nop 0
	global_load_lds_dwordx4 v128, s[36:37]
	s_add_i32 m0, s3, 0x2000
	s_nop 0
	global_load_lds_dwordx4 v130, s[36:37]
	s_add_u32 s88, s88, 0x80
	s_addc_u32 s89, s89, 0
	s_mov_b32 m0, s57
	s_nop 0
	global_load_lds_dwordx4 v128, s[88:89]
	s_mov_b32 m0, s58
	s_nop 0
	global_load_lds_dwordx4 v130, s[88:89]
	s_waitcnt vmcnt(8)
	s_waitcnt lgkmcnt(0)
	s_barrier
	v_mfma_f32_16x16x32_bf16 v[60:63], v[140:143], v[180:183], v[60:63]
	v_mfma_f32_16x16x32_bf16 v[56:59], v[156:159], v[180:183], v[56:59]
	v_mfma_f32_16x16x32_bf16 v[44:47], v[140:143], v[188:191], v[44:47]
	v_mfma_f32_16x16x32_bf16 v[40:43], v[156:159], v[188:191], v[40:43]
	v_mfma_f32_16x16x32_bf16 v[28:31], v[140:143], v[196:199], v[28:31]
	v_mfma_f32_16x16x32_bf16 v[24:27], v[156:159], v[196:199], v[24:27]
	v_mfma_f32_16x16x32_bf16 v[12:15], v[140:143], v[204:207], v[12:15]
	v_mfma_f32_16x16x32_bf16 v[8:11], v[156:159], v[204:207], v[8:11]
	v_mfma_f32_16x16x32_bf16 v[60:63], v[152:155], v[184:187], v[60:63]
	v_mfma_f32_16x16x32_bf16 v[56:59], v[160:163], v[184:187], v[56:59]
	v_mfma_f32_16x16x32_bf16 v[44:47], v[152:155], v[192:195], v[44:47]
	v_mfma_f32_16x16x32_bf16 v[40:43], v[160:163], v[192:195], v[40:43]
	v_mfma_f32_16x16x32_bf16 v[28:31], v[152:155], v[200:203], v[28:31]
	v_mfma_f32_16x16x32_bf16 v[24:27], v[160:163], v[200:203], v[24:27]
	v_mfma_f32_16x16x32_bf16 v[12:15], v[152:155], v[208:211], v[12:15]
	v_mfma_f32_16x16x32_bf16 v[8:11], v[160:163], v[208:211], v[8:11]
	v_mfma_f32_16x16x32_bf16 v[52:55], v[164:167], v[180:183], v[52:55]
	v_mfma_f32_16x16x32_bf16 v[48:51], v[172:175], v[180:183], v[48:51]
	v_mfma_f32_16x16x32_bf16 v[36:39], v[164:167], v[188:191], v[36:39]
	v_mfma_f32_16x16x32_bf16 v[32:35], v[172:175], v[188:191], v[32:35]
	v_mfma_f32_16x16x32_bf16 v[20:23], v[164:167], v[196:199], v[20:23]
	v_mfma_f32_16x16x32_bf16 v[16:19], v[172:175], v[196:199], v[16:19]
	v_mfma_f32_16x16x32_bf16 v[4:7], v[164:167], v[204:207], v[4:7]
	v_mfma_f32_16x16x32_bf16 v[0:3], v[172:175], v[204:207], v[0:3]
	v_mfma_f32_16x16x32_bf16 v[52:55], v[168:171], v[184:187], v[52:55]
	v_mfma_f32_16x16x32_bf16 v[48:51], v[176:179], v[184:187], v[48:51]
	v_mfma_f32_16x16x32_bf16 v[36:39], v[168:171], v[192:195], v[36:39]
	v_mfma_f32_16x16x32_bf16 v[32:35], v[176:179], v[192:195], v[32:35]
	v_mfma_f32_16x16x32_bf16 v[20:23], v[168:171], v[200:203], v[20:23]
	v_mfma_f32_16x16x32_bf16 v[16:19], v[176:179], v[200:203], v[16:19]
	v_mfma_f32_16x16x32_bf16 v[4:7], v[168:171], v[208:211], v[4:7]
	v_mfma_f32_16x16x32_bf16 v[0:3], v[176:179], v[208:211], v[0:3]
	s_barrier
	s_add_i32 s27, s27, 2
	s_add_u32 s86, s86, 0x100
	s_addc_u32 s87, s87, 0
	s_add_u32 s19, s19, 0x100
	s_addc_u32 s24, s24, 0
	s_cmp_gt_u32 s27, 29
	s_cbranch_scc0 .LBB0_1493
	s_and_b64 vcc, exec, s[12:13]
	s_cbranch_vccz .LBB0_1496
	s_barrier

.LBB0_1624:
	ds_read_b128 v[154:157], v150
	ds_read_b128 v[158:161], v150 offset:1024
	ds_read_b128 v[162:165], v150 offset:2048
	ds_read_b128 v[166:169], v150 offset:3072
	ds_read_b128 v[170:173], v151
	ds_read_b128 v[174:177], v151 offset:1024
	ds_read_b128 v[178:181], v151 offset:2048
	ds_read_b128 v[182:185], v151 offset:3072
	s_add_u32 s3, s88, 0xfff80080
	s_addc_u32 s42, s89, -1
	s_cmp_eq_u32 s37, 28
	s_cselect_b32 s93, s0, s42
	s_cselect_b32 s92, s1, s3
	s_cselect_b32 s91, s27, s36
	s_cselect_b32 s90, s33, s35
	s_add_i32 m0, s9, 0xc000
	ds_read_b128 v[186:189], v152
	ds_read_b128 v[190:193], v152 offset:1024
	ds_read_b128 v[194:197], v152 offset:2048
	ds_read_b128 v[198:201], v152 offset:3072
	ds_read_b128 v[202:205], v152 offset:4096
	ds_read_b128 v[206:209], v152 offset:5120
	ds_read_b128 v[210:213], v152 offset:6144
	ds_read_b128 v[214:217], v152 offset:7168
	global_load_lds_dwordx4 v138, s[88:89]
	s_add_i32 m0, s9, 0xe000
	s_nop 0
	global_load_lds_dwordx4 v140, s[88:89]
	s_waitcnt vmcnt(8)
	s_waitcnt lgkmcnt(0)
	s_barrier
	v_mfma_f32_16x16x32_bf16 v[124:127], v[154:157], v[186:189], v[124:127]
	v_mfma_f32_16x16x32_bf16 v[120:123], v[162:165], v[186:189], v[120:123]
	v_mfma_f32_16x16x32_bf16 v[108:111], v[154:157], v[194:197], v[108:111]
	v_mfma_f32_16x16x32_bf16 v[104:107], v[162:165], v[194:197], v[104:107]
	v_mfma_f32_16x16x32_bf16 v[92:95], v[154:157], v[202:205], v[92:95]
	v_mfma_f32_16x16x32_bf16 v[88:91], v[162:165], v[202:205], v[88:91]
	v_mfma_f32_16x16x32_bf16 v[76:79], v[154:157], v[210:213], v[76:79]
	v_mfma_f32_16x16x32_bf16 v[72:75], v[162:165], v[210:213], v[72:75]
	v_mfma_f32_16x16x32_bf16 v[124:127], v[158:161], v[190:193], v[124:127]
	v_mfma_f32_16x16x32_bf16 v[120:123], v[166:169], v[190:193], v[120:123]
	v_mfma_f32_16x16x32_bf16 v[108:111], v[158:161], v[198:201], v[108:111]
	v_mfma_f32_16x16x32_bf16 v[104:107], v[166:169], v[198:201], v[104:107]
	v_mfma_f32_16x16x32_bf16 v[92:95], v[158:161], v[206:209], v[92:95]
	v_mfma_f32_16x16x32_bf16 v[88:91], v[166:169], v[206:209], v[88:91]
	v_mfma_f32_16x16x32_bf16 v[76:79], v[158:161], v[214:217], v[76:79]
	v_mfma_f32_16x16x32_bf16 v[72:75], v[166:169], v[214:217], v[72:75]
	v_mfma_f32_16x16x32_bf16 v[116:119], v[170:173], v[186:189], v[116:119]
	v_mfma_f32_16x16x32_bf16 v[112:115], v[178:181], v[186:189], v[112:115]
	v_mfma_f32_16x16x32_bf16 v[100:103], v[170:173], v[194:197], v[100:103]
	v_mfma_f32_16x16x32_bf16 v[96:99], v[178:181], v[194:197], v[96:99]
	v_mfma_f32_16x16x32_bf16 v[84:87], v[170:173], v[202:205], v[84:87]
	v_mfma_f32_16x16x32_bf16 v[80:83], v[178:181], v[202:205], v[80:83]
	v_mfma_f32_16x16x32_bf16 v[68:71], v[170:173], v[210:213], v[68:71]
	v_mfma_f32_16x16x32_bf16 v[64:67], v[178:181], v[210:213], v[64:67]
	v_mfma_f32_16x16x32_bf16 v[116:119], v[174:177], v[190:193], v[116:119]
	v_mfma_f32_16x16x32_bf16 v[112:115], v[182:185], v[190:193], v[112:115]
	v_mfma_f32_16x16x32_bf16 v[100:103], v[174:177], v[198:201], v[100:103]
	v_mfma_f32_16x16x32_bf16 v[96:99], v[182:185], v[198:201], v[96:99]
	v_mfma_f32_16x16x32_bf16 v[84:87], v[174:177], v[206:209], v[84:87]
	v_mfma_f32_16x16x32_bf16 v[80:83], v[182:185], v[206:209], v[80:83]
	v_mfma_f32_16x16x32_bf16 v[68:71], v[174:177], v[214:217], v[68:71]
	v_mfma_f32_16x16x32_bf16 v[64:67], v[182:185], v[214:217], v[64:67]
	s_barrier
	s_add_i32 s3, s48, s8
	s_mov_b32 m0, s3
	ds_read_b128 v[186:189], v152 offset:16384
	ds_read_b128 v[190:193], v152 offset:17408
	ds_read_b128 v[194:197], v152 offset:18432
	ds_read_b128 v[198:201], v152 offset:19456
	ds_read_b128 v[202:205], v152 offset:20480
	ds_read_b128 v[206:209], v152 offset:21504
	ds_read_b128 v[210:213], v152 offset:22528
	ds_read_b128 v[214:217], v152 offset:23552
	global_load_lds_dwordx4 v130, s[90:91]
	s_add_i32 m0, s3, 0x2000
	s_add_u32 s42, s90, 0x80000
	s_addc_u32 s43, s91, 0
	s_add_i32 s3, s49, s8
	global_load_lds_dwordx4 v134, s[90:91]
	s_mov_b32 m0, s3
	s_nop 0
	global_load_lds_dwordx4 v130, s[42:43]
	s_add_i32 m0, s3, 0x2000
	s_nop 0
	global_load_lds_dwordx4 v134, s[42:43]
	s_mov_b32 m0, s9
	s_nop 0
	global_load_lds_dwordx4 v128, s[92:93]
	s_mov_b32 m0, s18
	s_nop 0
	global_load_lds_dwordx4 v132, s[92:93]
	s_waitcnt vmcnt(8)
	s_waitcnt lgkmcnt(0)
	s_barrier
	v_mfma_f32_16x16x32_bf16 v[60:63], v[154:157], v[186:189], v[60:63]
	v_mfma_f32_16x16x32_bf16 v[56:59], v[162:165], v[186:189], v[56:59]
	v_mfma_f32_16x16x32_bf16 v[44:47], v[154:157], v[194:197], v[44:47]
	v_mfma_f32_16x16x32_bf16 v[40:43], v[162:165], v[194:197], v[40:43]
	v_mfma_f32_16x16x32_bf16 v[28:31], v[154:157], v[202:205], v[28:31]
	v_mfma_f32_16x16x32_bf16 v[24:27], v[162:165], v[202:205], v[24:27]
	v_mfma_f32_16x16x32_bf16 v[12:15], v[154:157], v[210:213], v[12:15]
	v_mfma_f32_16x16x32_bf16 v[8:11], v[162:165], v[210:213], v[8:11]
	v_mfma_f32_16x16x32_bf16 v[60:63], v[158:161], v[190:193], v[60:63]
	v_mfma_f32_16x16x32_bf16 v[56:59], v[166:169], v[190:193], v[56:59]
	v_mfma_f32_16x16x32_bf16 v[44:47], v[158:161], v[198:201], v[44:47]
	v_mfma_f32_16x16x32_bf16 v[40:43], v[166:169], v[198:201], v[40:43]
	v_mfma_f32_16x16x32_bf16 v[28:31], v[158:161], v[206:209], v[28:31]
	v_mfma_f32_16x16x32_bf16 v[24:27], v[166:169], v[206:209], v[24:27]
	v_mfma_f32_16x16x32_bf16 v[12:15], v[158:161], v[214:217], v[12:15]
	v_mfma_f32_16x16x32_bf16 v[8:11], v[166:169], v[214:217], v[8:11]
	v_mfma_f32_16x16x32_bf16 v[52:55], v[170:173], v[186:189], v[52:55]
	v_mfma_f32_16x16x32_bf16 v[48:51], v[178:181], v[186:189], v[48:51]
	v_mfma_f32_16x16x32_bf16 v[36:39], v[170:173], v[194:197], v[36:39]
	v_mfma_f32_16x16x32_bf16 v[32:35], v[178:181], v[194:197], v[32:35]
	v_mfma_f32_16x16x32_bf16 v[20:23], v[170:173], v[202:205], v[20:23]
	v_mfma_f32_16x16x32_bf16 v[16:19], v[178:181], v[202:205], v[16:19]
	v_mfma_f32_16x16x32_bf16 v[4:7], v[170:173], v[210:213], v[4:7]
	v_mfma_f32_16x16x32_bf16 v[0:3], v[178:181], v[210:213], v[0:3]
	v_mfma_f32_16x16x32_bf16 v[52:55], v[174:177], v[190:193], v[52:55]
	v_mfma_f32_16x16x32_bf16 v[48:51], v[182:185], v[190:193], v[48:51]
	v_mfma_f32_16x16x32_bf16 v[36:39], v[174:177], v[198:201], v[36:39]
	v_mfma_f32_16x16x32_bf16 v[32:35], v[182:185], v[198:201], v[32:35]
	v_mfma_f32_16x16x32_bf16 v[20:23], v[174:177], v[206:209], v[20:23]
	v_mfma_f32_16x16x32_bf16 v[16:19], v[182:185], v[206:209], v[16:19]
	v_mfma_f32_16x16x32_bf16 v[4:7], v[174:177], v[214:217], v[4:7]
	v_mfma_f32_16x16x32_bf16 v[0:3], v[182:185], v[214:217], v[0:3]
	s_barrier
	s_add_i32 s3, 0, 0x18000
	v_add_u32_e32 v153, s3, v149
	s_add_i32 s44, 0, 0x1c000
	ds_read_b128 v[154:157], v153
	ds_read_b128 v[158:161], v153 offset:1024
	ds_read_b128 v[162:165], v153 offset:2048
	ds_read_b128 v[166:169], v153 offset:3072
	v_add_u32_e32 v153, s44, v149
	ds_read_b128 v[170:173], v153
	ds_read_b128 v[174:177], v153 offset:1024
	ds_read_b128 v[178:181], v153 offset:2048
	ds_read_b128 v[182:185], v153 offset:3072
	s_add_u32 s42, s92, 0x80000
	s_addc_u32 s43, s93, 0
	s_mov_b32 m0, s19
	ds_read_b128 v[186:189], v152 offset:32768
	ds_read_b128 v[190:193], v152 offset:33792
	ds_read_b128 v[194:197], v152 offset:34816
	ds_read_b128 v[198:201], v152 offset:35840
	ds_read_b128 v[202:205], v152 offset:36864
	ds_read_b128 v[206:209], v152 offset:37888
	ds_read_b128 v[210:213], v152 offset:38912
	ds_read_b128 v[214:217], v152 offset:39936
	global_load_lds_dwordx4 v128, s[42:43]
	v_lshl_add_u64 v[224:225], s[42:43], 0, v[132:133]
	s_mov_b32 m0, s25
	s_nop 0
	global_load_lds_dwordx4 v[224:225], off
	s_waitcnt vmcnt(8)
	s_waitcnt lgkmcnt(0)
	s_barrier
	v_mfma_f32_16x16x32_bf16 v[124:127], v[154:157], v[186:189], v[124:127]
	v_mfma_f32_16x16x32_bf16 v[120:123], v[162:165], v[186:189], v[120:123]
	v_mfma_f32_16x16x32_bf16 v[108:111], v[154:157], v[194:197], v[108:111]
	v_mfma_f32_16x16x32_bf16 v[104:107], v[162:165], v[194:197], v[104:107]
	v_mfma_f32_16x16x32_bf16 v[92:95], v[154:157], v[202:205], v[92:95]
	v_mfma_f32_16x16x32_bf16 v[88:91], v[162:165], v[202:205], v[88:91]
	v_mfma_f32_16x16x32_bf16 v[76:79], v[154:157], v[210:213], v[76:79]
	v_mfma_f32_16x16x32_bf16 v[72:75], v[162:165], v[210:213], v[72:75]
	v_mfma_f32_16x16x32_bf16 v[124:127], v[158:161], v[190:193], v[124:127]
	v_mfma_f32_16x16x32_bf16 v[120:123], v[166:169], v[190:193], v[120:123]
	v_mfma_f32_16x16x32_bf16 v[108:111], v[158:161], v[198:201], v[108:111]
	v_mfma_f32_16x16x32_bf16 v[104:107], v[166:169], v[198:201], v[104:107]
	v_mfma_f32_16x16x32_bf16 v[92:95], v[158:161], v[206:209], v[92:95]
	v_mfma_f32_16x16x32_bf16 v[88:91], v[166:169], v[206:209], v[88:91]
	v_mfma_f32_16x16x32_bf16 v[76:79], v[158:161], v[214:217], v[76:79]
	v_mfma_f32_16x16x32_bf16 v[72:75], v[166:169], v[214:217], v[72:75]
	v_mfma_f32_16x16x32_bf16 v[116:119], v[170:173], v[186:189], v[116:119]
	v_mfma_f32_16x16x32_bf16 v[112:115], v[178:181], v[186:189], v[112:115]
	v_mfma_f32_16x16x32_bf16 v[100:103], v[170:173], v[194:197], v[100:103]
	v_mfma_f32_16x16x32_bf16 v[96:99], v[178:181], v[194:197], v[96:99]
	v_mfma_f32_16x16x32_bf16 v[84:87], v[170:173], v[202:205], v[84:87]
	v_mfma_f32_16x16x32_bf16 v[80:83], v[178:181], v[202:205], v[80:83]
	v_mfma_f32_16x16x32_bf16 v[68:71], v[170:173], v[210:213], v[68:71]
	v_mfma_f32_16x16x32_bf16 v[64:67], v[178:181], v[210:213], v[64:67]
	v_mfma_f32_16x16x32_bf16 v[116:119], v[174:177], v[190:193], v[116:119]
	v_mfma_f32_16x16x32_bf16 v[112:115], v[182:185], v[190:193], v[112:115]
	v_mfma_f32_16x16x32_bf16 v[100:103], v[174:177], v[198:201], v[100:103]
	v_mfma_f32_16x16x32_bf16 v[96:99], v[182:185], v[198:201], v[96:99]
	v_mfma_f32_16x16x32_bf16 v[84:87], v[174:177], v[206:209], v[84:87]
	v_mfma_f32_16x16x32_bf16 v[80:83], v[182:185], v[206:209], v[80:83]
	v_mfma_f32_16x16x32_bf16 v[68:71], v[174:177], v[214:217], v[68:71]
	v_mfma_f32_16x16x32_bf16 v[64:67], v[182:185], v[214:217], v[64:67]
	s_barrier
	s_add_i32 s3, s3, s8
	s_add_u32 s42, s90, 0x80
	s_addc_u32 s43, s91, 0
	s_mov_b32 m0, s3
	ds_read_b128 v[186:189], v152 offset:49152
	ds_read_b128 v[190:193], v152 offset:50176
	ds_read_b128 v[194:197], v152 offset:51200
	ds_read_b128 v[198:201], v152 offset:52224
	ds_read_b128 v[202:205], v152 offset:53248
	ds_read_b128 v[206:209], v152 offset:54272
	ds_read_b128 v[210:213], v152 offset:55296
	ds_read_b128 v[214:217], v152 offset:56320
	global_load_lds_dwordx4 v130, s[42:43]
	s_add_i32 m0, s3, 0x2000
	s_add_i32 s3, s44, s8
	global_load_lds_dwordx4 v134, s[42:43]
	s_add_u32 s42, s42, 0x80000
	s_addc_u32 s43, s43, 0
	s_mov_b32 m0, s3
	s_nop 0
	global_load_lds_dwordx4 v130, s[42:43]
	s_add_i32 m0, s3, 0x2000
	s_nop 0
	global_load_lds_dwordx4 v134, s[42:43]
	s_add_u32 s92, s92, 0x80
	s_addc_u32 s93, s93, 0
	s_mov_b32 m0, s30
	s_nop 0
	global_load_lds_dwordx4 v128, s[92:93]
	s_mov_b32 m0, s31
	s_nop 0
	global_load_lds_dwordx4 v132, s[92:93]
	s_waitcnt vmcnt(8)
	s_waitcnt lgkmcnt(0)
	s_barrier
	v_mfma_f32_16x16x32_bf16 v[60:63], v[154:157], v[186:189], v[60:63]
	v_mfma_f32_16x16x32_bf16 v[56:59], v[162:165], v[186:189], v[56:59]
	v_mfma_f32_16x16x32_bf16 v[44:47], v[154:157], v[194:197], v[44:47]
	v_mfma_f32_16x16x32_bf16 v[40:43], v[162:165], v[194:197], v[40:43]
	v_mfma_f32_16x16x32_bf16 v[28:31], v[154:157], v[202:205], v[28:31]
	v_mfma_f32_16x16x32_bf16 v[24:27], v[162:165], v[202:205], v[24:27]
	v_mfma_f32_16x16x32_bf16 v[12:15], v[154:157], v[210:213], v[12:15]
	v_mfma_f32_16x16x32_bf16 v[8:11], v[162:165], v[210:213], v[8:11]
	v_mfma_f32_16x16x32_bf16 v[60:63], v[158:161], v[190:193], v[60:63]
	v_mfma_f32_16x16x32_bf16 v[56:59], v[166:169], v[190:193], v[56:59]
	v_mfma_f32_16x16x32_bf16 v[44:47], v[158:161], v[198:201], v[44:47]
	v_mfma_f32_16x16x32_bf16 v[40:43], v[166:169], v[198:201], v[40:43]
	v_mfma_f32_16x16x32_bf16 v[28:31], v[158:161], v[206:209], v[28:31]
	v_mfma_f32_16x16x32_bf16 v[24:27], v[166:169], v[206:209], v[24:27]
	v_mfma_f32_16x16x32_bf16 v[12:15], v[158:161], v[214:217], v[12:15]
	v_mfma_f32_16x16x32_bf16 v[8:11], v[166:169], v[214:217], v[8:11]
	v_mfma_f32_16x16x32_bf16 v[52:55], v[170:173], v[186:189], v[52:55]
	v_mfma_f32_16x16x32_bf16 v[48:51], v[178:181], v[186:189], v[48:51]
	v_mfma_f32_16x16x32_bf16 v[36:39], v[170:173], v[194:197], v[36:39]
	v_mfma_f32_16x16x32_bf16 v[32:35], v[178:181], v[194:197], v[32:35]
	v_mfma_f32_16x16x32_bf16 v[20:23], v[170:173], v[202:205], v[20:23]
	v_mfma_f32_16x16x32_bf16 v[16:19], v[178:181], v[202:205], v[16:19]
	v_mfma_f32_16x16x32_bf16 v[4:7], v[170:173], v[210:213], v[4:7]
	v_mfma_f32_16x16x32_bf16 v[0:3], v[178:181], v[210:213], v[0:3]
	v_mfma_f32_16x16x32_bf16 v[52:55], v[174:177], v[190:193], v[52:55]
	v_mfma_f32_16x16x32_bf16 v[48:51], v[182:185], v[190:193], v[48:51]
	v_mfma_f32_16x16x32_bf16 v[36:39], v[174:177], v[198:201], v[36:39]
	v_mfma_f32_16x16x32_bf16 v[32:35], v[182:185], v[198:201], v[32:35]
	v_mfma_f32_16x16x32_bf16 v[20:23], v[174:177], v[206:209], v[20:23]
	v_mfma_f32_16x16x32_bf16 v[16:19], v[182:185], v[206:209], v[16:19]
	v_mfma_f32_16x16x32_bf16 v[4:7], v[174:177], v[214:217], v[4:7]
	v_mfma_f32_16x16x32_bf16 v[0:3], v[182:185], v[214:217], v[0:3]
	s_barrier
	s_add_i32 s37, s37, 2
	s_add_u32 s88, s88, 0x100
	s_addc_u32 s89, s89, 0
	s_add_u32 s35, s35, 0x100
	s_addc_u32 s36, s36, 0
	s_cmp_gt_u32 s37, 29
	s_cbranch_scc0 .LBB0_1624
	s_and_b64 vcc, exec, s[16:17]
	s_cbranch_vccz .LBB0_1627
	s_barrier

.LBB0_1700:
	ds_read_b128 v[140:143], v149
	ds_read_b128 v[152:155], v149 offset:1024
	ds_read_b128 v[156:159], v149 offset:2048
	ds_read_b128 v[160:163], v149 offset:3072
	ds_read_b128 v[164:167], v150
	ds_read_b128 v[168:171], v150 offset:1024
	ds_read_b128 v[172:175], v150 offset:2048
	ds_read_b128 v[176:179], v150 offset:3072
	s_add_u32 s3, s86, 0xffe00080
	s_addc_u32 s37, s87, -1
	s_cmpk_eq_i32 s36, 0x7c
	s_cselect_b32 s91, s0, s37
	s_cselect_b32 s90, s1, s3
	s_cselect_b32 s89, s17, s35
	s_cselect_b32 s88, s27, s33
	s_add_i32 m0, s18, 0xc000
	ds_read_b128 v[180:183], v151
	ds_read_b128 v[184:187], v151 offset:1024
	ds_read_b128 v[188:191], v151 offset:2048
	ds_read_b128 v[192:195], v151 offset:3072
	ds_read_b128 v[196:199], v151 offset:4096
	ds_read_b128 v[200:203], v151 offset:5120
	ds_read_b128 v[204:207], v151 offset:6144
	ds_read_b128 v[208:211], v151 offset:7168
	global_load_lds_dwordx4 v132, s[86:87]
	s_add_i32 m0, s18, 0xe000
	s_nop 0
	global_load_lds_dwordx4 v134, s[86:87]
	s_waitcnt vmcnt(8)
	s_waitcnt lgkmcnt(0)
	s_barrier
	v_mfma_f32_16x16x32_bf16 v[124:127], v[140:143], v[180:183], v[124:127]
	v_mfma_f32_16x16x32_bf16 v[120:123], v[156:159], v[180:183], v[120:123]
	v_mfma_f32_16x16x32_bf16 v[112:115], v[140:143], v[188:191], v[112:115]
	v_mfma_f32_16x16x32_bf16 v[104:107], v[156:159], v[188:191], v[104:107]
	v_mfma_f32_16x16x32_bf16 v[96:99], v[140:143], v[196:199], v[96:99]
	v_mfma_f32_16x16x32_bf16 v[88:91], v[156:159], v[196:199], v[88:91]
	v_mfma_f32_16x16x32_bf16 v[80:83], v[140:143], v[204:207], v[80:83]
	v_mfma_f32_16x16x32_bf16 v[72:75], v[156:159], v[204:207], v[72:75]
	v_mfma_f32_16x16x32_bf16 v[124:127], v[152:155], v[184:187], v[124:127]
	v_mfma_f32_16x16x32_bf16 v[120:123], v[160:163], v[184:187], v[120:123]
	v_mfma_f32_16x16x32_bf16 v[112:115], v[152:155], v[192:195], v[112:115]
	v_mfma_f32_16x16x32_bf16 v[104:107], v[160:163], v[192:195], v[104:107]
	v_mfma_f32_16x16x32_bf16 v[96:99], v[152:155], v[200:203], v[96:99]
	v_mfma_f32_16x16x32_bf16 v[88:91], v[160:163], v[200:203], v[88:91]
	v_mfma_f32_16x16x32_bf16 v[80:83], v[152:155], v[208:211], v[80:83]
	v_mfma_f32_16x16x32_bf16 v[72:75], v[160:163], v[208:211], v[72:75]
	v_mfma_f32_16x16x32_bf16 v[116:119], v[164:167], v[180:183], v[116:119]
	v_mfma_f32_16x16x32_bf16 v[108:111], v[172:175], v[180:183], v[108:111]
	v_mfma_f32_16x16x32_bf16 v[100:103], v[164:167], v[188:191], v[100:103]
	v_mfma_f32_16x16x32_bf16 v[92:95], v[172:175], v[188:191], v[92:95]
	v_mfma_f32_16x16x32_bf16 v[84:87], v[164:167], v[196:199], v[84:87]
	v_mfma_f32_16x16x32_bf16 v[76:79], v[172:175], v[196:199], v[76:79]
	v_mfma_f32_16x16x32_bf16 v[68:71], v[164:167], v[204:207], v[68:71]
	v_mfma_f32_16x16x32_bf16 v[64:67], v[172:175], v[204:207], v[64:67]
	v_mfma_f32_16x16x32_bf16 v[116:119], v[168:171], v[184:187], v[116:119]
	v_mfma_f32_16x16x32_bf16 v[108:111], v[176:179], v[184:187], v[108:111]
	v_mfma_f32_16x16x32_bf16 v[100:103], v[168:171], v[192:195], v[100:103]
	v_mfma_f32_16x16x32_bf16 v[92:95], v[176:179], v[192:195], v[92:95]
	v_mfma_f32_16x16x32_bf16 v[84:87], v[168:171], v[200:203], v[84:87]
	v_mfma_f32_16x16x32_bf16 v[76:79], v[176:179], v[200:203], v[76:79]
	v_mfma_f32_16x16x32_bf16 v[68:71], v[168:171], v[208:211], v[68:71]
	v_mfma_f32_16x16x32_bf16 v[64:67], v[176:179], v[208:211], v[64:67]
	s_barrier
	s_add_i32 s3, s49, s9
	s_mov_b32 m0, s3
	ds_read_b128 v[180:183], v151 offset:16384
	ds_read_b128 v[184:187], v151 offset:17408
	ds_read_b128 v[188:191], v151 offset:18432
	ds_read_b128 v[192:195], v151 offset:19456
	ds_read_b128 v[196:199], v151 offset:20480
	ds_read_b128 v[200:203], v151 offset:21504
	ds_read_b128 v[204:207], v151 offset:22528
	ds_read_b128 v[208:211], v151 offset:23552
	global_load_lds_dwordx4 v128, s[88:89]
	s_add_i32 m0, s3, 0x2000
	s_add_u32 s42, s88, 0x200000
	s_addc_u32 s43, s89, 0
	s_add_i32 s3, s52, s9
	global_load_lds_dwordx4 v130, s[88:89]
	s_mov_b32 m0, s3
	s_nop 0
	global_load_lds_dwordx4 v128, s[42:43]
	s_add_i32 m0, s3, 0x2000
	s_nop 0
	global_load_lds_dwordx4 v130, s[42:43]
	s_mov_b32 m0, s18
	s_nop 0
	global_load_lds_dwordx4 v128, s[90:91]
	s_mov_b32 m0, s19
	s_nop 0
	global_load_lds_dwordx4 v130, s[90:91]
	s_waitcnt vmcnt(8)
	s_waitcnt lgkmcnt(0)
	s_barrier
	v_mfma_f32_16x16x32_bf16 v[60:63], v[140:143], v[180:183], v[60:63]
	v_mfma_f32_16x16x32_bf16 v[56:59], v[156:159], v[180:183], v[56:59]
	v_mfma_f32_16x16x32_bf16 v[48:51], v[140:143], v[188:191], v[48:51]
	v_mfma_f32_16x16x32_bf16 v[40:43], v[156:159], v[188:191], v[40:43]
	v_mfma_f32_16x16x32_bf16 v[32:35], v[140:143], v[196:199], v[32:35]
	v_mfma_f32_16x16x32_bf16 v[24:27], v[156:159], v[196:199], v[24:27]
	v_mfma_f32_16x16x32_bf16 v[16:19], v[140:143], v[204:207], v[16:19]
	v_mfma_f32_16x16x32_bf16 v[8:11], v[156:159], v[204:207], v[8:11]
	v_mfma_f32_16x16x32_bf16 v[60:63], v[152:155], v[184:187], v[60:63]
	v_mfma_f32_16x16x32_bf16 v[56:59], v[160:163], v[184:187], v[56:59]
	v_mfma_f32_16x16x32_bf16 v[48:51], v[152:155], v[192:195], v[48:51]
	v_mfma_f32_16x16x32_bf16 v[40:43], v[160:163], v[192:195], v[40:43]
	v_mfma_f32_16x16x32_bf16 v[32:35], v[152:155], v[200:203], v[32:35]
	v_mfma_f32_16x16x32_bf16 v[24:27], v[160:163], v[200:203], v[24:27]
	v_mfma_f32_16x16x32_bf16 v[16:19], v[152:155], v[208:211], v[16:19]
	v_mfma_f32_16x16x32_bf16 v[8:11], v[160:163], v[208:211], v[8:11]
	v_mfma_f32_16x16x32_bf16 v[52:55], v[164:167], v[180:183], v[52:55]
	v_mfma_f32_16x16x32_bf16 v[44:47], v[172:175], v[180:183], v[44:47]
	v_mfma_f32_16x16x32_bf16 v[36:39], v[164:167], v[188:191], v[36:39]
	v_mfma_f32_16x16x32_bf16 v[28:31], v[172:175], v[188:191], v[28:31]
	v_mfma_f32_16x16x32_bf16 v[20:23], v[164:167], v[196:199], v[20:23]
	v_mfma_f32_16x16x32_bf16 v[12:15], v[172:175], v[196:199], v[12:15]
	v_mfma_f32_16x16x32_bf16 v[4:7], v[164:167], v[204:207], v[4:7]
	v_mfma_f32_16x16x32_bf16 v[0:3], v[172:175], v[204:207], v[0:3]
	v_mfma_f32_16x16x32_bf16 v[52:55], v[168:171], v[184:187], v[52:55]
	v_mfma_f32_16x16x32_bf16 v[44:47], v[176:179], v[184:187], v[44:47]
	v_mfma_f32_16x16x32_bf16 v[36:39], v[168:171], v[192:195], v[36:39]
	v_mfma_f32_16x16x32_bf16 v[28:31], v[176:179], v[192:195], v[28:31]
	v_mfma_f32_16x16x32_bf16 v[20:23], v[168:171], v[200:203], v[20:23]
	v_mfma_f32_16x16x32_bf16 v[12:15], v[176:179], v[200:203], v[12:15]
	v_mfma_f32_16x16x32_bf16 v[4:7], v[168:171], v[208:211], v[4:7]
	v_mfma_f32_16x16x32_bf16 v[0:3], v[176:179], v[208:211], v[0:3]
	s_barrier
	s_add_i32 s3, 0, 0x18000
	s_add_i32 s37, 0, 0x1c000
	v_add_u32_e32 v160, s3, v147
	v_add_u32_e32 v176, s37, v147
	ds_read_b128 v[140:143], v160
	ds_read_b128 v[152:155], v160 offset:1024
	ds_read_b128 v[156:159], v160 offset:2048
	ds_read_b128 v[160:163], v160 offset:3072
	ds_read_b128 v[164:167], v176
	ds_read_b128 v[168:171], v176 offset:1024
	ds_read_b128 v[172:175], v176 offset:2048
	ds_read_b128 v[176:179], v176 offset:3072
	s_add_u32 s42, s90, 0x200000
	s_addc_u32 s43, s91, 0
	s_mov_b32 m0, s25
	ds_read_b128 v[180:183], v151 offset:32768
	ds_read_b128 v[184:187], v151 offset:33792
	ds_read_b128 v[188:191], v151 offset:34816
	ds_read_b128 v[192:195], v151 offset:35840
	ds_read_b128 v[196:199], v151 offset:36864
	ds_read_b128 v[200:203], v151 offset:37888
	ds_read_b128 v[204:207], v151 offset:38912
	ds_read_b128 v[208:211], v151 offset:39936
	global_load_lds_dwordx4 v128, s[42:43]
	v_lshl_add_u64 v[218:219], s[42:43], 0, v[130:131]
	s_mov_b32 m0, s30
	s_nop 0
	global_load_lds_dwordx4 v[218:219], off
	s_waitcnt vmcnt(8)
	s_waitcnt lgkmcnt(0)
	s_barrier
	v_mfma_f32_16x16x32_bf16 v[124:127], v[140:143], v[180:183], v[124:127]
	v_mfma_f32_16x16x32_bf16 v[120:123], v[156:159], v[180:183], v[120:123]
	v_mfma_f32_16x16x32_bf16 v[112:115], v[140:143], v[188:191], v[112:115]
	v_mfma_f32_16x16x32_bf16 v[104:107], v[156:159], v[188:191], v[104:107]
	v_mfma_f32_16x16x32_bf16 v[96:99], v[140:143], v[196:199], v[96:99]
	v_mfma_f32_16x16x32_bf16 v[88:91], v[156:159], v[196:199], v[88:91]
	v_mfma_f32_16x16x32_bf16 v[80:83], v[140:143], v[204:207], v[80:83]
	v_mfma_f32_16x16x32_bf16 v[72:75], v[156:159], v[204:207], v[72:75]
	v_mfma_f32_16x16x32_bf16 v[124:127], v[152:155], v[184:187], v[124:127]
	v_mfma_f32_16x16x32_bf16 v[120:123], v[160:163], v[184:187], v[120:123]
	v_mfma_f32_16x16x32_bf16 v[112:115], v[152:155], v[192:195], v[112:115]
	v_mfma_f32_16x16x32_bf16 v[104:107], v[160:163], v[192:195], v[104:107]
	v_mfma_f32_16x16x32_bf16 v[96:99], v[152:155], v[200:203], v[96:99]
	v_mfma_f32_16x16x32_bf16 v[88:91], v[160:163], v[200:203], v[88:91]
	v_mfma_f32_16x16x32_bf16 v[80:83], v[152:155], v[208:211], v[80:83]
	v_mfma_f32_16x16x32_bf16 v[72:75], v[160:163], v[208:211], v[72:75]
	v_mfma_f32_16x16x32_bf16 v[116:119], v[164:167], v[180:183], v[116:119]
	v_mfma_f32_16x16x32_bf16 v[108:111], v[172:175], v[180:183], v[108:111]
	v_mfma_f32_16x16x32_bf16 v[100:103], v[164:167], v[188:191], v[100:103]
	v_mfma_f32_16x16x32_bf16 v[92:95], v[172:175], v[188:191], v[92:95]
	v_mfma_f32_16x16x32_bf16 v[84:87], v[164:167], v[196:199], v[84:87]
	v_mfma_f32_16x16x32_bf16 v[76:79], v[172:175], v[196:199], v[76:79]
	v_mfma_f32_16x16x32_bf16 v[68:71], v[164:167], v[204:207], v[68:71]
	v_mfma_f32_16x16x32_bf16 v[64:67], v[172:175], v[204:207], v[64:67]
	v_mfma_f32_16x16x32_bf16 v[116:119], v[168:171], v[184:187], v[116:119]
	v_mfma_f32_16x16x32_bf16 v[108:111], v[176:179], v[184:187], v[108:111]
	v_mfma_f32_16x16x32_bf16 v[100:103], v[168:171], v[192:195], v[100:103]
	v_mfma_f32_16x16x32_bf16 v[92:95], v[176:179], v[192:195], v[92:95]
	v_mfma_f32_16x16x32_bf16 v[84:87], v[168:171], v[200:203], v[84:87]
	v_mfma_f32_16x16x32_bf16 v[76:79], v[176:179], v[200:203], v[76:79]
	v_mfma_f32_16x16x32_bf16 v[68:71], v[168:171], v[208:211], v[68:71]
	v_mfma_f32_16x16x32_bf16 v[64:67], v[176:179], v[208:211], v[64:67]
	s_barrier
	s_add_i32 s3, s3, s9
	s_add_u32 s42, s88, 0x80
	s_addc_u32 s43, s89, 0
	s_mov_b32 m0, s3
	ds_read_b128 v[180:183], v151 offset:49152
	ds_read_b128 v[184:187], v151 offset:50176
	ds_read_b128 v[188:191], v151 offset:51200
	ds_read_b128 v[192:195], v151 offset:52224
	ds_read_b128 v[196:199], v151 offset:53248
	ds_read_b128 v[200:203], v151 offset:54272
	ds_read_b128 v[204:207], v151 offset:55296
	ds_read_b128 v[208:211], v151 offset:56320
	global_load_lds_dwordx4 v128, s[42:43]
	s_add_i32 m0, s3, 0x2000
	s_add_i32 s3, s37, s9
	global_load_lds_dwordx4 v130, s[42:43]
	s_add_u32 s42, s42, 0x200000
	s_addc_u32 s43, s43, 0
	s_mov_b32 m0, s3
	s_nop 0
	global_load_lds_dwordx4 v128, s[42:43]
	s_add_i32 m0, s3, 0x2000
	s_nop 0
	global_load_lds_dwordx4 v130, s[42:43]
	s_add_u32 s90, s90, 0x80
	s_addc_u32 s91, s91, 0
	s_mov_b32 m0, s8
	s_nop 0
	global_load_lds_dwordx4 v128, s[90:91]
	s_mov_b32 m0, s48
	s_nop 0
	global_load_lds_dwordx4 v130, s[90:91]
	s_waitcnt vmcnt(8)
	s_waitcnt lgkmcnt(0)
	s_barrier
	v_mfma_f32_16x16x32_bf16 v[60:63], v[140:143], v[180:183], v[60:63]
	v_mfma_f32_16x16x32_bf16 v[56:59], v[156:159], v[180:183], v[56:59]
	v_mfma_f32_16x16x32_bf16 v[48:51], v[140:143], v[188:191], v[48:51]
	v_mfma_f32_16x16x32_bf16 v[40:43], v[156:159], v[188:191], v[40:43]
	v_mfma_f32_16x16x32_bf16 v[32:35], v[140:143], v[196:199], v[32:35]
	v_mfma_f32_16x16x32_bf16 v[24:27], v[156:159], v[196:199], v[24:27]
	v_mfma_f32_16x16x32_bf16 v[16:19], v[140:143], v[204:207], v[16:19]
	v_mfma_f32_16x16x32_bf16 v[8:11], v[156:159], v[204:207], v[8:11]
	v_mfma_f32_16x16x32_bf16 v[60:63], v[152:155], v[184:187], v[60:63]
	v_mfma_f32_16x16x32_bf16 v[56:59], v[160:163], v[184:187], v[56:59]
	v_mfma_f32_16x16x32_bf16 v[48:51], v[152:155], v[192:195], v[48:51]
	v_mfma_f32_16x16x32_bf16 v[40:43], v[160:163], v[192:195], v[40:43]
	v_mfma_f32_16x16x32_bf16 v[32:35], v[152:155], v[200:203], v[32:35]
	v_mfma_f32_16x16x32_bf16 v[24:27], v[160:163], v[200:203], v[24:27]
	v_mfma_f32_16x16x32_bf16 v[16:19], v[152:155], v[208:211], v[16:19]
	v_mfma_f32_16x16x32_bf16 v[8:11], v[160:163], v[208:211], v[8:11]
	v_mfma_f32_16x16x32_bf16 v[52:55], v[164:167], v[180:183], v[52:55]
	v_mfma_f32_16x16x32_bf16 v[44:47], v[172:175], v[180:183], v[44:47]
	v_mfma_f32_16x16x32_bf16 v[36:39], v[164:167], v[188:191], v[36:39]
	v_mfma_f32_16x16x32_bf16 v[28:31], v[172:175], v[188:191], v[28:31]
	v_mfma_f32_16x16x32_bf16 v[20:23], v[164:167], v[196:199], v[20:23]
	v_mfma_f32_16x16x32_bf16 v[12:15], v[172:175], v[196:199], v[12:15]
	v_mfma_f32_16x16x32_bf16 v[4:7], v[164:167], v[204:207], v[4:7]
	v_mfma_f32_16x16x32_bf16 v[0:3], v[172:175], v[204:207], v[0:3]
	v_mfma_f32_16x16x32_bf16 v[52:55], v[168:171], v[184:187], v[52:55]
	v_mfma_f32_16x16x32_bf16 v[44:47], v[176:179], v[184:187], v[44:47]
	v_mfma_f32_16x16x32_bf16 v[36:39], v[168:171], v[192:195], v[36:39]
	v_mfma_f32_16x16x32_bf16 v[28:31], v[176:179], v[192:195], v[28:31]
	v_mfma_f32_16x16x32_bf16 v[20:23], v[168:171], v[200:203], v[20:23]
	v_mfma_f32_16x16x32_bf16 v[12:15], v[176:179], v[200:203], v[12:15]
	v_mfma_f32_16x16x32_bf16 v[4:7], v[168:171], v[208:211], v[4:7]
	v_mfma_f32_16x16x32_bf16 v[0:3], v[176:179], v[208:211], v[0:3]
	s_barrier
	s_add_i32 s36, s36, 2
	s_add_u32 s86, s86, 0x100
	s_addc_u32 s87, s87, 0
	s_add_u32 s33, s33, 0x100
	s_addc_u32 s35, s35, 0
	s_cmpk_gt_u32 s36, 0x7d
	s_cbranch_scc0 .LBB0_1700
	s_and_b64 vcc, exec, s[14:15]
	s_cbranch_vccz .LBB0_1703
	s_barrier

.LBB0_1773:
	ds_read_b128 v[128:131], v173
	ds_read_b128 v[132:135], v173 offset:1024
	ds_read_b128 v[158:161], v173 offset:2048
	ds_read_b128 v[178:181], v173 offset:3072
	ds_read_b128 v[182:185], v174
	ds_read_b128 v[186:189], v174 offset:1024
	ds_read_b128 v[190:193], v174 offset:2048
	ds_read_b128 v[194:197], v174 offset:3072
	s_add_u32 s3, s34, 0xfff80080
	s_addc_u32 s19, s35, -1
	s_cmp_eq_u32 s18, 28
	s_cselect_b32 vcc_hi, s0, s19
	s_cselect_b32 vcc_lo, s1, s3
	s_cselect_b32 s97, s8, s17
	s_cselect_b32 s96, s9, s15
	s_add_i32 m0, s48, 0xc000
	ds_read_b128 v[198:201], v175
	ds_read_b128 v[202:205], v175 offset:1024
	ds_read_b128 v[206:209], v175 offset:2048
	ds_read_b128 v[210:213], v175 offset:3072
	ds_read_b128 v[214:217], v175 offset:4096
	ds_read_b128 v[218:221], v175 offset:5120
	ds_read_b128 v[222:225], v175 offset:6144
	ds_read_b128 v[230:233], v175 offset:7168
	global_load_lds_dwordx4 v148, s[34:35]
	s_add_i32 m0, s48, 0xe000
	s_nop 0
	global_load_lds_dwordx4 v150, s[34:35]
	s_waitcnt vmcnt(8)
	s_waitcnt lgkmcnt(0)
	s_barrier
	v_mfma_f32_16x16x32_bf16 v[124:127], v[128:131], v[198:201], v[124:127]
	v_mfma_f32_16x16x32_bf16 v[120:123], v[158:161], v[198:201], v[120:123]
	v_mfma_f32_16x16x32_bf16 v[108:111], v[128:131], v[206:209], v[108:111]
	v_mfma_f32_16x16x32_bf16 v[104:107], v[158:161], v[206:209], v[104:107]
	v_mfma_f32_16x16x32_bf16 v[92:95], v[128:131], v[214:217], v[92:95]
	v_mfma_f32_16x16x32_bf16 v[88:91], v[158:161], v[214:217], v[88:91]
	v_mfma_f32_16x16x32_bf16 v[76:79], v[128:131], v[222:225], v[76:79]
	v_mfma_f32_16x16x32_bf16 v[72:75], v[158:161], v[222:225], v[72:75]
	v_mfma_f32_16x16x32_bf16 v[124:127], v[132:135], v[202:205], v[124:127]
	v_mfma_f32_16x16x32_bf16 v[120:123], v[178:181], v[202:205], v[120:123]
	v_mfma_f32_16x16x32_bf16 v[108:111], v[132:135], v[210:213], v[108:111]
	v_mfma_f32_16x16x32_bf16 v[104:107], v[178:181], v[210:213], v[104:107]
	v_mfma_f32_16x16x32_bf16 v[92:95], v[132:135], v[218:221], v[92:95]
	v_mfma_f32_16x16x32_bf16 v[88:91], v[178:181], v[218:221], v[88:91]
	v_mfma_f32_16x16x32_bf16 v[76:79], v[132:135], v[230:233], v[76:79]
	v_mfma_f32_16x16x32_bf16 v[72:75], v[178:181], v[230:233], v[72:75]
	v_mfma_f32_16x16x32_bf16 v[116:119], v[182:185], v[198:201], v[116:119]
	v_mfma_f32_16x16x32_bf16 v[112:115], v[190:193], v[198:201], v[112:115]
	v_mfma_f32_16x16x32_bf16 v[100:103], v[182:185], v[206:209], v[100:103]
	v_mfma_f32_16x16x32_bf16 v[96:99], v[190:193], v[206:209], v[96:99]
	v_mfma_f32_16x16x32_bf16 v[84:87], v[182:185], v[214:217], v[84:87]
	v_mfma_f32_16x16x32_bf16 v[80:83], v[190:193], v[214:217], v[80:83]
	v_mfma_f32_16x16x32_bf16 v[68:71], v[182:185], v[222:225], v[68:71]
	v_mfma_f32_16x16x32_bf16 v[64:67], v[190:193], v[222:225], v[64:67]
	v_mfma_f32_16x16x32_bf16 v[116:119], v[186:189], v[202:205], v[116:119]
	v_mfma_f32_16x16x32_bf16 v[112:115], v[194:197], v[202:205], v[112:115]
	v_mfma_f32_16x16x32_bf16 v[100:103], v[186:189], v[210:213], v[100:103]
	v_mfma_f32_16x16x32_bf16 v[96:99], v[194:197], v[210:213], v[96:99]
	v_mfma_f32_16x16x32_bf16 v[84:87], v[186:189], v[218:221], v[84:87]
	v_mfma_f32_16x16x32_bf16 v[80:83], v[194:197], v[218:221], v[80:83]
	v_mfma_f32_16x16x32_bf16 v[68:71], v[186:189], v[230:233], v[68:71]
	v_mfma_f32_16x16x32_bf16 v[64:67], v[194:197], v[230:233], v[64:67]
	s_barrier
	s_add_i32 s3, s76, s25
	s_mov_b32 m0, s3
	ds_read_b128 v[198:201], v175 offset:16384
	ds_read_b128 v[202:205], v175 offset:17408
	ds_read_b128 v[206:209], v175 offset:18432
	ds_read_b128 v[210:213], v175 offset:19456
	ds_read_b128 v[214:217], v175 offset:20480
	ds_read_b128 v[218:221], v175 offset:21504
	ds_read_b128 v[222:225], v175 offset:22528
	ds_read_b128 v[230:233], v175 offset:23552
	global_load_lds_dwordx4 v138, s[96:97]
	s_add_i32 m0, s3, 0x2000
	s_add_u32 s36, s96, 0x80000
	s_addc_u32 s37, s97, 0
	s_add_i32 s3, s77, s25
	global_load_lds_dwordx4 v142, s[96:97]
	s_mov_b32 m0, s3
	s_nop 0
	global_load_lds_dwordx4 v138, s[36:37]
	s_add_i32 m0, s3, 0x2000
	s_nop 0
	global_load_lds_dwordx4 v142, s[36:37]
	s_mov_b32 m0, s48
	s_nop 0
	global_load_lds_dwordx4 v136, vcc
	s_mov_b32 m0, s49
	s_nop 0
	global_load_lds_dwordx4 v140, vcc
	s_waitcnt vmcnt(8)
	s_waitcnt lgkmcnt(0)
	s_barrier
	v_mfma_f32_16x16x32_bf16 v[60:63], v[128:131], v[198:201], v[60:63]
	v_mfma_f32_16x16x32_bf16 v[56:59], v[158:161], v[198:201], v[56:59]
	v_mfma_f32_16x16x32_bf16 v[44:47], v[128:131], v[206:209], v[44:47]
	v_mfma_f32_16x16x32_bf16 v[40:43], v[158:161], v[206:209], v[40:43]
	v_mfma_f32_16x16x32_bf16 v[28:31], v[128:131], v[214:217], v[28:31]
	v_mfma_f32_16x16x32_bf16 v[24:27], v[158:161], v[214:217], v[24:27]
	v_mfma_f32_16x16x32_bf16 v[12:15], v[128:131], v[222:225], v[12:15]
	v_mfma_f32_16x16x32_bf16 v[8:11], v[158:161], v[222:225], v[8:11]
	v_mfma_f32_16x16x32_bf16 v[60:63], v[132:135], v[202:205], v[60:63]
	v_mfma_f32_16x16x32_bf16 v[56:59], v[178:181], v[202:205], v[56:59]
	v_mfma_f32_16x16x32_bf16 v[44:47], v[132:135], v[210:213], v[44:47]
	v_mfma_f32_16x16x32_bf16 v[40:43], v[178:181], v[210:213], v[40:43]
	v_mfma_f32_16x16x32_bf16 v[28:31], v[132:135], v[218:221], v[28:31]
	v_mfma_f32_16x16x32_bf16 v[24:27], v[178:181], v[218:221], v[24:27]
	v_mfma_f32_16x16x32_bf16 v[12:15], v[132:135], v[230:233], v[12:15]
	v_mfma_f32_16x16x32_bf16 v[8:11], v[178:181], v[230:233], v[8:11]
	v_mfma_f32_16x16x32_bf16 v[52:55], v[182:185], v[198:201], v[52:55]
	v_mfma_f32_16x16x32_bf16 v[48:51], v[190:193], v[198:201], v[48:51]
	v_mfma_f32_16x16x32_bf16 v[36:39], v[182:185], v[206:209], v[36:39]
	v_mfma_f32_16x16x32_bf16 v[32:35], v[190:193], v[206:209], v[32:35]
	v_mfma_f32_16x16x32_bf16 v[20:23], v[182:185], v[214:217], v[20:23]
	v_mfma_f32_16x16x32_bf16 v[16:19], v[190:193], v[214:217], v[16:19]
	v_mfma_f32_16x16x32_bf16 v[4:7], v[182:185], v[222:225], v[4:7]
	v_mfma_f32_16x16x32_bf16 v[0:3], v[190:193], v[222:225], v[0:3]
	v_mfma_f32_16x16x32_bf16 v[52:55], v[186:189], v[202:205], v[52:55]
	v_mfma_f32_16x16x32_bf16 v[48:51], v[194:197], v[202:205], v[48:51]
	v_mfma_f32_16x16x32_bf16 v[36:39], v[186:189], v[210:213], v[36:39]
	v_mfma_f32_16x16x32_bf16 v[32:35], v[194:197], v[210:213], v[32:35]
	v_mfma_f32_16x16x32_bf16 v[20:23], v[186:189], v[218:221], v[20:23]
	v_mfma_f32_16x16x32_bf16 v[16:19], v[194:197], v[218:221], v[16:19]
	v_mfma_f32_16x16x32_bf16 v[4:7], v[186:189], v[230:233], v[4:7]
	v_mfma_f32_16x16x32_bf16 v[0:3], v[194:197], v[230:233], v[0:3]
	s_barrier
	s_add_i32 s3, 0, 0x18000
	v_add_u32_e32 v144, s3, v165
	s_add_i32 s19, 0, 0x1c000
	ds_read_b128 v[128:131], v144
	ds_read_b128 v[132:135], v144 offset:1024
	ds_read_b128 v[158:161], v144 offset:2048
	ds_read_b128 v[178:181], v144 offset:3072
	v_add_u32_e32 v144, s19, v165
	ds_read_b128 v[182:185], v144
	ds_read_b128 v[186:189], v144 offset:1024
	ds_read_b128 v[190:193], v144 offset:2048
	ds_read_b128 v[194:197], v144 offset:3072
	s_add_u32 s36, vcc_lo, 0x80000
	s_addc_u32 s37, vcc_hi, 0
	s_mov_b32 m0, s52
	ds_read_b128 v[198:201], v175 offset:32768
	ds_read_b128 v[202:205], v175 offset:33792
	ds_read_b128 v[206:209], v175 offset:34816
	ds_read_b128 v[210:213], v175 offset:35840
	ds_read_b128 v[214:217], v175 offset:36864
	ds_read_b128 v[218:221], v175 offset:37888
	ds_read_b128 v[222:225], v175 offset:38912
	ds_read_b128 v[230:233], v175 offset:39936
	global_load_lds_dwordx4 v136, s[36:37]
	s_mov_b32 m0, s53
	s_nop 0
	global_load_lds_dwordx4 v140, s[36:37]
	s_waitcnt vmcnt(8)
	s_waitcnt lgkmcnt(0)
	s_barrier
	v_mfma_f32_16x16x32_bf16 v[124:127], v[128:131], v[198:201], v[124:127]
	v_mfma_f32_16x16x32_bf16 v[120:123], v[158:161], v[198:201], v[120:123]
	v_mfma_f32_16x16x32_bf16 v[108:111], v[128:131], v[206:209], v[108:111]
	v_mfma_f32_16x16x32_bf16 v[104:107], v[158:161], v[206:209], v[104:107]
	v_mfma_f32_16x16x32_bf16 v[92:95], v[128:131], v[214:217], v[92:95]
	v_mfma_f32_16x16x32_bf16 v[88:91], v[158:161], v[214:217], v[88:91]
	v_mfma_f32_16x16x32_bf16 v[76:79], v[128:131], v[222:225], v[76:79]
	v_mfma_f32_16x16x32_bf16 v[72:75], v[158:161], v[222:225], v[72:75]
	v_mfma_f32_16x16x32_bf16 v[124:127], v[132:135], v[202:205], v[124:127]
	v_mfma_f32_16x16x32_bf16 v[120:123], v[178:181], v[202:205], v[120:123]
	v_mfma_f32_16x16x32_bf16 v[108:111], v[132:135], v[210:213], v[108:111]
	v_mfma_f32_16x16x32_bf16 v[104:107], v[178:181], v[210:213], v[104:107]
	v_mfma_f32_16x16x32_bf16 v[92:95], v[132:135], v[218:221], v[92:95]
	v_mfma_f32_16x16x32_bf16 v[88:91], v[178:181], v[218:221], v[88:91]
	v_mfma_f32_16x16x32_bf16 v[76:79], v[132:135], v[230:233], v[76:79]
	v_mfma_f32_16x16x32_bf16 v[72:75], v[178:181], v[230:233], v[72:75]
	v_mfma_f32_16x16x32_bf16 v[116:119], v[182:185], v[198:201], v[116:119]
	v_mfma_f32_16x16x32_bf16 v[112:115], v[190:193], v[198:201], v[112:115]
	v_mfma_f32_16x16x32_bf16 v[100:103], v[182:185], v[206:209], v[100:103]
	v_mfma_f32_16x16x32_bf16 v[96:99], v[190:193], v[206:209], v[96:99]
	v_mfma_f32_16x16x32_bf16 v[84:87], v[182:185], v[214:217], v[84:87]
	v_mfma_f32_16x16x32_bf16 v[80:83], v[190:193], v[214:217], v[80:83]
	v_mfma_f32_16x16x32_bf16 v[68:71], v[182:185], v[222:225], v[68:71]
	v_mfma_f32_16x16x32_bf16 v[64:67], v[190:193], v[222:225], v[64:67]
	v_mfma_f32_16x16x32_bf16 v[116:119], v[186:189], v[202:205], v[116:119]
	v_mfma_f32_16x16x32_bf16 v[112:115], v[194:197], v[202:205], v[112:115]
	v_mfma_f32_16x16x32_bf16 v[100:103], v[186:189], v[210:213], v[100:103]
	v_mfma_f32_16x16x32_bf16 v[96:99], v[194:197], v[210:213], v[96:99]
	v_mfma_f32_16x16x32_bf16 v[84:87], v[186:189], v[218:221], v[84:87]
	v_mfma_f32_16x16x32_bf16 v[80:83], v[194:197], v[218:221], v[80:83]
	v_mfma_f32_16x16x32_bf16 v[68:71], v[186:189], v[230:233], v[68:71]
	v_mfma_f32_16x16x32_bf16 v[64:67], v[194:197], v[230:233], v[64:67]
	s_barrier
	s_add_i32 s3, s3, s25
	s_add_u32 s36, s96, 0x80
	s_addc_u32 s37, s97, 0
	s_mov_b32 m0, s3
	ds_read_b128 v[198:201], v175 offset:49152
	ds_read_b128 v[202:205], v175 offset:50176
	ds_read_b128 v[206:209], v175 offset:51200
	ds_read_b128 v[210:213], v175 offset:52224
	ds_read_b128 v[214:217], v175 offset:53248
	ds_read_b128 v[218:221], v175 offset:54272
	ds_read_b128 v[222:225], v175 offset:55296
	ds_read_b128 v[230:233], v175 offset:56320
	global_load_lds_dwordx4 v138, s[36:37]
	s_add_i32 m0, s3, 0x2000
	s_add_i32 s3, s19, s25
	global_load_lds_dwordx4 v142, s[36:37]
	s_add_u32 s36, s36, 0x80000
	s_addc_u32 s37, s37, 0
	s_mov_b32 m0, s3
	s_nop 0
	global_load_lds_dwordx4 v138, s[36:37]
	s_add_i32 m0, s3, 0x2000
	s_nop 0
	global_load_lds_dwordx4 v142, s[36:37]
	s_add_u32 vcc_lo, vcc_lo, 0x80
	s_addc_u32 vcc_hi, vcc_hi, 0
	s_mov_b32 m0, s56
	s_nop 0
	global_load_lds_dwordx4 v136, vcc
	s_mov_b32 m0, s57
	s_nop 0
	global_load_lds_dwordx4 v140, vcc
	s_waitcnt vmcnt(8)
	s_waitcnt lgkmcnt(0)
	s_barrier
	v_mfma_f32_16x16x32_bf16 v[60:63], v[128:131], v[198:201], v[60:63]
	v_mfma_f32_16x16x32_bf16 v[56:59], v[158:161], v[198:201], v[56:59]
	v_mfma_f32_16x16x32_bf16 v[44:47], v[128:131], v[206:209], v[44:47]
	v_mfma_f32_16x16x32_bf16 v[40:43], v[158:161], v[206:209], v[40:43]
	v_mfma_f32_16x16x32_bf16 v[28:31], v[128:131], v[214:217], v[28:31]
	v_mfma_f32_16x16x32_bf16 v[24:27], v[158:161], v[214:217], v[24:27]
	v_mfma_f32_16x16x32_bf16 v[12:15], v[128:131], v[222:225], v[12:15]
	v_mfma_f32_16x16x32_bf16 v[8:11], v[158:161], v[222:225], v[8:11]
	v_mfma_f32_16x16x32_bf16 v[60:63], v[132:135], v[202:205], v[60:63]
	v_mfma_f32_16x16x32_bf16 v[56:59], v[178:181], v[202:205], v[56:59]
	v_mfma_f32_16x16x32_bf16 v[44:47], v[132:135], v[210:213], v[44:47]
	v_mfma_f32_16x16x32_bf16 v[40:43], v[178:181], v[210:213], v[40:43]
	v_mfma_f32_16x16x32_bf16 v[28:31], v[132:135], v[218:221], v[28:31]
	v_mfma_f32_16x16x32_bf16 v[24:27], v[178:181], v[218:221], v[24:27]
	v_mfma_f32_16x16x32_bf16 v[12:15], v[132:135], v[230:233], v[12:15]
	v_mfma_f32_16x16x32_bf16 v[8:11], v[178:181], v[230:233], v[8:11]
	v_mfma_f32_16x16x32_bf16 v[52:55], v[182:185], v[198:201], v[52:55]
	v_mfma_f32_16x16x32_bf16 v[48:51], v[190:193], v[198:201], v[48:51]
	v_mfma_f32_16x16x32_bf16 v[36:39], v[182:185], v[206:209], v[36:39]
	v_mfma_f32_16x16x32_bf16 v[32:35], v[190:193], v[206:209], v[32:35]
	v_mfma_f32_16x16x32_bf16 v[20:23], v[182:185], v[214:217], v[20:23]
	v_mfma_f32_16x16x32_bf16 v[16:19], v[190:193], v[214:217], v[16:19]
	v_mfma_f32_16x16x32_bf16 v[4:7], v[182:185], v[222:225], v[4:7]
	v_mfma_f32_16x16x32_bf16 v[0:3], v[190:193], v[222:225], v[0:3]
	v_mfma_f32_16x16x32_bf16 v[52:55], v[186:189], v[202:205], v[52:55]
	v_mfma_f32_16x16x32_bf16 v[48:51], v[194:197], v[202:205], v[48:51]
	v_mfma_f32_16x16x32_bf16 v[36:39], v[186:189], v[210:213], v[36:39]
	v_mfma_f32_16x16x32_bf16 v[32:35], v[194:197], v[210:213], v[32:35]
	v_mfma_f32_16x16x32_bf16 v[20:23], v[186:189], v[218:221], v[20:23]
	v_mfma_f32_16x16x32_bf16 v[16:19], v[194:197], v[218:221], v[16:19]
	v_mfma_f32_16x16x32_bf16 v[4:7], v[186:189], v[230:233], v[4:7]
	v_mfma_f32_16x16x32_bf16 v[0:3], v[194:197], v[230:233], v[0:3]
	s_barrier
	s_add_i32 s18, s18, 2
	s_add_u32 s34, s34, 0x100
	s_addc_u32 s35, s35, 0
	s_add_u32 s15, s15, 0x100
	s_addc_u32 s17, s17, 0
	s_cmp_gt_u32 s18, 29
	s_cbranch_scc0 .LBB0_1773
	s_and_b64 vcc, exec, s[84:85]
	s_cbranch_vccz .LBB0_1776
	s_barrier

.LBB0_2248:
	ds_read_b128 v[144:147], v153
	ds_read_b128 v[156:159], v153 offset:1024
	ds_read_b128 v[160:163], v153 offset:2048
	ds_read_b128 v[164:167], v153 offset:3072
	ds_read_b128 v[168:171], v154
	ds_read_b128 v[172:175], v154 offset:1024
	ds_read_b128 v[176:179], v154 offset:2048
	ds_read_b128 v[180:183], v154 offset:3072
	s_add_u32 s3, s52, 0xfffc0080
	s_addc_u32 s45, s53, -1
	s_cmp_eq_u32 s44, 12
	s_cselect_b32 s59, s0, s45
	s_cselect_b32 s58, s1, s3
	s_cselect_b32 s57, s17, s35
	s_cselect_b32 s56, s27, s33
	s_add_i32 m0, s9, 0xc000
	ds_read_b128 v[184:187], v155
	ds_read_b128 v[188:191], v155 offset:1024
	ds_read_b128 v[192:195], v155 offset:2048
	ds_read_b128 v[196:199], v155 offset:3072
	ds_read_b128 v[200:203], v155 offset:4096
	ds_read_b128 v[204:207], v155 offset:5120
	ds_read_b128 v[208:211], v155 offset:6144
	ds_read_b128 v[212:215], v155 offset:7168
	global_load_lds_dwordx4 v136, s[52:53]
	s_add_i32 m0, s9, 0xe000
	s_nop 0
	global_load_lds_dwordx4 v138, s[52:53]
	s_waitcnt vmcnt(8)
	s_waitcnt lgkmcnt(0)
	s_barrier
	v_mfma_f32_16x16x32_bf16 v[124:127], v[144:147], v[184:187], v[124:127]
	v_mfma_f32_16x16x32_bf16 v[120:123], v[160:163], v[184:187], v[120:123]
	v_mfma_f32_16x16x32_bf16 v[108:111], v[144:147], v[192:195], v[108:111]
	v_mfma_f32_16x16x32_bf16 v[104:107], v[160:163], v[192:195], v[104:107]
	v_mfma_f32_16x16x32_bf16 v[92:95], v[144:147], v[200:203], v[92:95]
	v_mfma_f32_16x16x32_bf16 v[88:91], v[160:163], v[200:203], v[88:91]
	v_mfma_f32_16x16x32_bf16 v[76:79], v[144:147], v[208:211], v[76:79]
	v_mfma_f32_16x16x32_bf16 v[72:75], v[160:163], v[208:211], v[72:75]
	v_mfma_f32_16x16x32_bf16 v[124:127], v[156:159], v[188:191], v[124:127]
	v_mfma_f32_16x16x32_bf16 v[120:123], v[164:167], v[188:191], v[120:123]
	v_mfma_f32_16x16x32_bf16 v[108:111], v[156:159], v[196:199], v[108:111]
	v_mfma_f32_16x16x32_bf16 v[104:107], v[164:167], v[196:199], v[104:107]
	v_mfma_f32_16x16x32_bf16 v[92:95], v[156:159], v[204:207], v[92:95]
	v_mfma_f32_16x16x32_bf16 v[88:91], v[164:167], v[204:207], v[88:91]
	v_mfma_f32_16x16x32_bf16 v[76:79], v[156:159], v[212:215], v[76:79]
	v_mfma_f32_16x16x32_bf16 v[72:75], v[164:167], v[212:215], v[72:75]
	v_mfma_f32_16x16x32_bf16 v[116:119], v[168:171], v[184:187], v[116:119]
	v_mfma_f32_16x16x32_bf16 v[112:115], v[176:179], v[184:187], v[112:115]
	v_mfma_f32_16x16x32_bf16 v[100:103], v[168:171], v[192:195], v[100:103]
	v_mfma_f32_16x16x32_bf16 v[96:99], v[176:179], v[192:195], v[96:99]
	v_mfma_f32_16x16x32_bf16 v[84:87], v[168:171], v[200:203], v[84:87]
	v_mfma_f32_16x16x32_bf16 v[80:83], v[176:179], v[200:203], v[80:83]
	v_mfma_f32_16x16x32_bf16 v[68:71], v[168:171], v[208:211], v[68:71]
	v_mfma_f32_16x16x32_bf16 v[64:67], v[176:179], v[208:211], v[64:67]
	v_mfma_f32_16x16x32_bf16 v[116:119], v[172:175], v[188:191], v[116:119]
	v_mfma_f32_16x16x32_bf16 v[112:115], v[180:183], v[188:191], v[112:115]
	v_mfma_f32_16x16x32_bf16 v[100:103], v[172:175], v[196:199], v[100:103]
	v_mfma_f32_16x16x32_bf16 v[96:99], v[180:183], v[196:199], v[96:99]
	v_mfma_f32_16x16x32_bf16 v[84:87], v[172:175], v[204:207], v[84:87]
	v_mfma_f32_16x16x32_bf16 v[80:83], v[180:183], v[204:207], v[80:83]
	v_mfma_f32_16x16x32_bf16 v[68:71], v[172:175], v[212:215], v[68:71]
	v_mfma_f32_16x16x32_bf16 v[64:67], v[180:183], v[212:215], v[64:67]
	s_barrier
	s_add_i32 s3, s62, s8
	s_mov_b32 m0, s3
	ds_read_b128 v[184:187], v155 offset:16384
	ds_read_b128 v[188:191], v155 offset:17408
	ds_read_b128 v[192:195], v155 offset:18432
	ds_read_b128 v[196:199], v155 offset:19456
	ds_read_b128 v[200:203], v155 offset:20480
	ds_read_b128 v[204:207], v155 offset:21504
	ds_read_b128 v[208:211], v155 offset:22528
	ds_read_b128 v[212:215], v155 offset:23552
	global_load_lds_dwordx4 v130, s[56:57]
	s_add_i32 m0, s3, 0x2000
	s_add_u32 s50, s56, 0x40000
	s_addc_u32 s51, s57, 0
	s_add_i32 s3, s63, s8
	global_load_lds_dwordx4 v134, s[56:57]
	s_mov_b32 m0, s3
	s_nop 0
	global_load_lds_dwordx4 v130, s[50:51]
	s_add_i32 m0, s3, 0x2000
	s_nop 0
	global_load_lds_dwordx4 v134, s[50:51]
	s_mov_b32 m0, s9
	s_nop 0
	global_load_lds_dwordx4 v128, s[58:59]
	s_mov_b32 m0, s18
	s_nop 0
	global_load_lds_dwordx4 v132, s[58:59]
	s_waitcnt vmcnt(8)
	s_waitcnt lgkmcnt(0)
	s_barrier
	v_mfma_f32_16x16x32_bf16 v[60:63], v[144:147], v[184:187], v[60:63]
	v_mfma_f32_16x16x32_bf16 v[56:59], v[160:163], v[184:187], v[56:59]
	v_mfma_f32_16x16x32_bf16 v[44:47], v[144:147], v[192:195], v[44:47]
	v_mfma_f32_16x16x32_bf16 v[40:43], v[160:163], v[192:195], v[40:43]
	v_mfma_f32_16x16x32_bf16 v[28:31], v[144:147], v[200:203], v[28:31]
	v_mfma_f32_16x16x32_bf16 v[24:27], v[160:163], v[200:203], v[24:27]
	v_mfma_f32_16x16x32_bf16 v[12:15], v[144:147], v[208:211], v[12:15]
	v_mfma_f32_16x16x32_bf16 v[8:11], v[160:163], v[208:211], v[8:11]
	v_mfma_f32_16x16x32_bf16 v[60:63], v[156:159], v[188:191], v[60:63]
	v_mfma_f32_16x16x32_bf16 v[56:59], v[164:167], v[188:191], v[56:59]
	v_mfma_f32_16x16x32_bf16 v[44:47], v[156:159], v[196:199], v[44:47]
	v_mfma_f32_16x16x32_bf16 v[40:43], v[164:167], v[196:199], v[40:43]
	v_mfma_f32_16x16x32_bf16 v[28:31], v[156:159], v[204:207], v[28:31]
	v_mfma_f32_16x16x32_bf16 v[24:27], v[164:167], v[204:207], v[24:27]
	v_mfma_f32_16x16x32_bf16 v[12:15], v[156:159], v[212:215], v[12:15]
	v_mfma_f32_16x16x32_bf16 v[8:11], v[164:167], v[212:215], v[8:11]
	v_mfma_f32_16x16x32_bf16 v[52:55], v[168:171], v[184:187], v[52:55]
	v_mfma_f32_16x16x32_bf16 v[48:51], v[176:179], v[184:187], v[48:51]
	v_mfma_f32_16x16x32_bf16 v[36:39], v[168:171], v[192:195], v[36:39]
	v_mfma_f32_16x16x32_bf16 v[32:35], v[176:179], v[192:195], v[32:35]
	v_mfma_f32_16x16x32_bf16 v[20:23], v[168:171], v[200:203], v[20:23]
	v_mfma_f32_16x16x32_bf16 v[16:19], v[176:179], v[200:203], v[16:19]
	v_mfma_f32_16x16x32_bf16 v[4:7], v[168:171], v[208:211], v[4:7]
	v_mfma_f32_16x16x32_bf16 v[0:3], v[176:179], v[208:211], v[0:3]
	v_mfma_f32_16x16x32_bf16 v[52:55], v[172:175], v[188:191], v[52:55]
	v_mfma_f32_16x16x32_bf16 v[48:51], v[180:183], v[188:191], v[48:51]
	v_mfma_f32_16x16x32_bf16 v[36:39], v[172:175], v[196:199], v[36:39]
	v_mfma_f32_16x16x32_bf16 v[32:35], v[180:183], v[196:199], v[32:35]
	v_mfma_f32_16x16x32_bf16 v[20:23], v[172:175], v[204:207], v[20:23]
	v_mfma_f32_16x16x32_bf16 v[16:19], v[180:183], v[204:207], v[16:19]
	v_mfma_f32_16x16x32_bf16 v[4:7], v[172:175], v[212:215], v[4:7]
	v_mfma_f32_16x16x32_bf16 v[0:3], v[180:183], v[212:215], v[0:3]
	s_barrier
	s_add_i32 s3, 0, 0x18000
	s_add_i32 s45, 0, 0x1c000
	v_add_u32_e32 v164, s3, v151
	v_add_u32_e32 v180, s45, v151
	ds_read_b128 v[144:147], v164
	ds_read_b128 v[156:159], v164 offset:1024
	ds_read_b128 v[160:163], v164 offset:2048
	ds_read_b128 v[164:167], v164 offset:3072
	ds_read_b128 v[168:171], v180
	ds_read_b128 v[172:175], v180 offset:1024
	ds_read_b128 v[176:179], v180 offset:2048
	ds_read_b128 v[180:183], v180 offset:3072
	s_add_u32 s50, s58, 0x40000
	s_addc_u32 s51, s59, 0
	s_mov_b32 m0, s19
	ds_read_b128 v[184:187], v155 offset:32768
	ds_read_b128 v[188:191], v155 offset:33792
	ds_read_b128 v[192:195], v155 offset:34816
	ds_read_b128 v[196:199], v155 offset:35840
	ds_read_b128 v[200:203], v155 offset:36864
	ds_read_b128 v[204:207], v155 offset:37888
	ds_read_b128 v[208:211], v155 offset:38912
	ds_read_b128 v[212:215], v155 offset:39936
	global_load_lds_dwordx4 v128, s[50:51]
	s_mov_b32 m0, s25
	s_nop 0
	global_load_lds_dwordx4 v132, s[50:51]
	s_waitcnt vmcnt(8)
	s_waitcnt lgkmcnt(0)
	s_barrier
	v_mfma_f32_16x16x32_bf16 v[124:127], v[144:147], v[184:187], v[124:127]
	v_mfma_f32_16x16x32_bf16 v[120:123], v[160:163], v[184:187], v[120:123]
	v_mfma_f32_16x16x32_bf16 v[108:111], v[144:147], v[192:195], v[108:111]
	v_mfma_f32_16x16x32_bf16 v[104:107], v[160:163], v[192:195], v[104:107]
	v_mfma_f32_16x16x32_bf16 v[92:95], v[144:147], v[200:203], v[92:95]
	v_mfma_f32_16x16x32_bf16 v[88:91], v[160:163], v[200:203], v[88:91]
	v_mfma_f32_16x16x32_bf16 v[76:79], v[144:147], v[208:211], v[76:79]
	v_mfma_f32_16x16x32_bf16 v[72:75], v[160:163], v[208:211], v[72:75]
	v_mfma_f32_16x16x32_bf16 v[124:127], v[156:159], v[188:191], v[124:127]
	v_mfma_f32_16x16x32_bf16 v[120:123], v[164:167], v[188:191], v[120:123]
	v_mfma_f32_16x16x32_bf16 v[108:111], v[156:159], v[196:199], v[108:111]
	v_mfma_f32_16x16x32_bf16 v[104:107], v[164:167], v[196:199], v[104:107]
	v_mfma_f32_16x16x32_bf16 v[92:95], v[156:159], v[204:207], v[92:95]
	v_mfma_f32_16x16x32_bf16 v[88:91], v[164:167], v[204:207], v[88:91]
	v_mfma_f32_16x16x32_bf16 v[76:79], v[156:159], v[212:215], v[76:79]
	v_mfma_f32_16x16x32_bf16 v[72:75], v[164:167], v[212:215], v[72:75]
	v_mfma_f32_16x16x32_bf16 v[116:119], v[168:171], v[184:187], v[116:119]
	v_mfma_f32_16x16x32_bf16 v[112:115], v[176:179], v[184:187], v[112:115]
	v_mfma_f32_16x16x32_bf16 v[100:103], v[168:171], v[192:195], v[100:103]
	v_mfma_f32_16x16x32_bf16 v[96:99], v[176:179], v[192:195], v[96:99]
	v_mfma_f32_16x16x32_bf16 v[84:87], v[168:171], v[200:203], v[84:87]
	v_mfma_f32_16x16x32_bf16 v[80:83], v[176:179], v[200:203], v[80:83]
	v_mfma_f32_16x16x32_bf16 v[68:71], v[168:171], v[208:211], v[68:71]
	v_mfma_f32_16x16x32_bf16 v[64:67], v[176:179], v[208:211], v[64:67]
	v_mfma_f32_16x16x32_bf16 v[116:119], v[172:175], v[188:191], v[116:119]
	v_mfma_f32_16x16x32_bf16 v[112:115], v[180:183], v[188:191], v[112:115]
	v_mfma_f32_16x16x32_bf16 v[100:103], v[172:175], v[196:199], v[100:103]
	v_mfma_f32_16x16x32_bf16 v[96:99], v[180:183], v[196:199], v[96:99]
	v_mfma_f32_16x16x32_bf16 v[84:87], v[172:175], v[204:207], v[84:87]
	v_mfma_f32_16x16x32_bf16 v[80:83], v[180:183], v[204:207], v[80:83]
	v_mfma_f32_16x16x32_bf16 v[68:71], v[172:175], v[212:215], v[68:71]
	v_mfma_f32_16x16x32_bf16 v[64:67], v[180:183], v[212:215], v[64:67]
	s_barrier
	s_add_i32 s3, s3, s8
	s_add_u32 s50, s56, 0x80
	s_addc_u32 s51, s57, 0
	s_mov_b32 m0, s3
	ds_read_b128 v[184:187], v155 offset:49152
	ds_read_b128 v[188:191], v155 offset:50176
	ds_read_b128 v[192:195], v155 offset:51200
	ds_read_b128 v[196:199], v155 offset:52224
	ds_read_b128 v[200:203], v155 offset:53248
	ds_read_b128 v[204:207], v155 offset:54272
	ds_read_b128 v[208:211], v155 offset:55296
	ds_read_b128 v[212:215], v155 offset:56320
	global_load_lds_dwordx4 v130, s[50:51]
	s_add_i32 m0, s3, 0x2000
	s_add_i32 s3, s45, s8
	global_load_lds_dwordx4 v134, s[50:51]
	s_add_u32 s50, s50, 0x40000
	s_addc_u32 s51, s51, 0
	s_mov_b32 m0, s3
	s_nop 0
	global_load_lds_dwordx4 v130, s[50:51]
	s_add_i32 m0, s3, 0x2000
	s_nop 0
	global_load_lds_dwordx4 v134, s[50:51]
	s_add_u32 s58, s58, 0x80
	s_addc_u32 s59, s59, 0
	s_mov_b32 m0, s60
	s_nop 0
	global_load_lds_dwordx4 v128, s[58:59]
	s_mov_b32 m0, s61
	s_nop 0
	global_load_lds_dwordx4 v132, s[58:59]
	s_waitcnt vmcnt(8)
	s_waitcnt lgkmcnt(0)
	s_barrier
	v_mfma_f32_16x16x32_bf16 v[60:63], v[144:147], v[184:187], v[60:63]
	v_mfma_f32_16x16x32_bf16 v[56:59], v[160:163], v[184:187], v[56:59]
	v_mfma_f32_16x16x32_bf16 v[44:47], v[144:147], v[192:195], v[44:47]
	v_mfma_f32_16x16x32_bf16 v[40:43], v[160:163], v[192:195], v[40:43]
	v_mfma_f32_16x16x32_bf16 v[28:31], v[144:147], v[200:203], v[28:31]
	v_mfma_f32_16x16x32_bf16 v[24:27], v[160:163], v[200:203], v[24:27]
	v_mfma_f32_16x16x32_bf16 v[12:15], v[144:147], v[208:211], v[12:15]
	v_mfma_f32_16x16x32_bf16 v[8:11], v[160:163], v[208:211], v[8:11]
	v_mfma_f32_16x16x32_bf16 v[60:63], v[156:159], v[188:191], v[60:63]
	v_mfma_f32_16x16x32_bf16 v[56:59], v[164:167], v[188:191], v[56:59]
	v_mfma_f32_16x16x32_bf16 v[44:47], v[156:159], v[196:199], v[44:47]
	v_mfma_f32_16x16x32_bf16 v[40:43], v[164:167], v[196:199], v[40:43]
	v_mfma_f32_16x16x32_bf16 v[28:31], v[156:159], v[204:207], v[28:31]
	v_mfma_f32_16x16x32_bf16 v[24:27], v[164:167], v[204:207], v[24:27]
	v_mfma_f32_16x16x32_bf16 v[12:15], v[156:159], v[212:215], v[12:15]
	v_mfma_f32_16x16x32_bf16 v[8:11], v[164:167], v[212:215], v[8:11]
	v_mfma_f32_16x16x32_bf16 v[52:55], v[168:171], v[184:187], v[52:55]
	v_mfma_f32_16x16x32_bf16 v[48:51], v[176:179], v[184:187], v[48:51]
	v_mfma_f32_16x16x32_bf16 v[36:39], v[168:171], v[192:195], v[36:39]
	v_mfma_f32_16x16x32_bf16 v[32:35], v[176:179], v[192:195], v[32:35]
	v_mfma_f32_16x16x32_bf16 v[20:23], v[168:171], v[200:203], v[20:23]
	v_mfma_f32_16x16x32_bf16 v[16:19], v[176:179], v[200:203], v[16:19]
	v_mfma_f32_16x16x32_bf16 v[4:7], v[168:171], v[208:211], v[4:7]
	v_mfma_f32_16x16x32_bf16 v[0:3], v[176:179], v[208:211], v[0:3]
	v_mfma_f32_16x16x32_bf16 v[52:55], v[172:175], v[188:191], v[52:55]
	v_mfma_f32_16x16x32_bf16 v[48:51], v[180:183], v[188:191], v[48:51]
	v_mfma_f32_16x16x32_bf16 v[36:39], v[172:175], v[196:199], v[36:39]
	v_mfma_f32_16x16x32_bf16 v[32:35], v[180:183], v[196:199], v[32:35]
	v_mfma_f32_16x16x32_bf16 v[20:23], v[172:175], v[204:207], v[20:23]
	v_mfma_f32_16x16x32_bf16 v[16:19], v[180:183], v[204:207], v[16:19]
	v_mfma_f32_16x16x32_bf16 v[4:7], v[172:175], v[212:215], v[4:7]
	v_mfma_f32_16x16x32_bf16 v[0:3], v[180:183], v[212:215], v[0:3]
	s_barrier
	s_add_i32 s44, s44, 2
	s_add_u32 s52, s52, 0x100
	s_addc_u32 s53, s53, 0
	s_add_u32 s33, s33, 0x100
	s_addc_u32 s35, s35, 0
	s_cmp_gt_u32 s44, 13
	s_cbranch_scc0 .LBB0_2248
	s_and_b64 vcc, exec, s[12:13]
	s_cbranch_vccz .LBB0_2251
	s_barrier

.LBB0_2272:
	ds_read_b128 v[144:147], v155
	ds_read_b128 v[148:151], v155 offset:1024
	ds_read_b128 v[158:161], v155 offset:2048
	ds_read_b128 v[162:165], v155 offset:3072
	ds_read_b128 v[166:169], v156
	ds_read_b128 v[170:173], v156 offset:1024
	ds_read_b128 v[174:177], v156 offset:2048
	ds_read_b128 v[178:181], v156 offset:3072
	s_add_u32 s3, s52, 0xfffe0080
	s_addc_u32 s51, s53, -1
	s_cmp_eq_u32 s50, 4
	s_cselect_b32 s59, s0, s51
	s_cselect_b32 s58, s1, s3
	s_cselect_b32 s57, s17, s45
	s_cselect_b32 s56, s35, s44
	s_add_i32 m0, s9, 0xc000
	ds_read_b128 v[182:185], v157
	ds_read_b128 v[186:189], v157 offset:1024
	ds_read_b128 v[190:193], v157 offset:2048
	ds_read_b128 v[194:197], v157 offset:3072
	ds_read_b128 v[198:201], v157 offset:4096
	ds_read_b128 v[202:205], v157 offset:5120
	ds_read_b128 v[206:209], v157 offset:6144
	ds_read_b128 v[210:213], v157 offset:7168
	global_load_lds_dwordx4 v136, s[52:53]
	s_add_i32 m0, s9, 0xe000
	s_nop 0
	global_load_lds_dwordx4 v138, s[52:53]
	s_waitcnt vmcnt(8)
	s_waitcnt lgkmcnt(0)
	s_barrier
	v_mfma_f32_16x16x32_bf16 v[124:127], v[144:147], v[182:185], v[124:127]
	v_mfma_f32_16x16x32_bf16 v[120:123], v[158:161], v[182:185], v[120:123]
	v_mfma_f32_16x16x32_bf16 v[108:111], v[144:147], v[190:193], v[108:111]
	v_mfma_f32_16x16x32_bf16 v[104:107], v[158:161], v[190:193], v[104:107]
	v_mfma_f32_16x16x32_bf16 v[92:95], v[144:147], v[198:201], v[92:95]
	v_mfma_f32_16x16x32_bf16 v[88:91], v[158:161], v[198:201], v[88:91]
	v_mfma_f32_16x16x32_bf16 v[76:79], v[144:147], v[206:209], v[76:79]
	v_mfma_f32_16x16x32_bf16 v[72:75], v[158:161], v[206:209], v[72:75]
	v_mfma_f32_16x16x32_bf16 v[124:127], v[148:151], v[186:189], v[124:127]
	v_mfma_f32_16x16x32_bf16 v[120:123], v[162:165], v[186:189], v[120:123]
	v_mfma_f32_16x16x32_bf16 v[108:111], v[148:151], v[194:197], v[108:111]
	v_mfma_f32_16x16x32_bf16 v[104:107], v[162:165], v[194:197], v[104:107]
	v_mfma_f32_16x16x32_bf16 v[92:95], v[148:151], v[202:205], v[92:95]
	v_mfma_f32_16x16x32_bf16 v[88:91], v[162:165], v[202:205], v[88:91]
	v_mfma_f32_16x16x32_bf16 v[76:79], v[148:151], v[210:213], v[76:79]
	v_mfma_f32_16x16x32_bf16 v[72:75], v[162:165], v[210:213], v[72:75]
	v_mfma_f32_16x16x32_bf16 v[116:119], v[166:169], v[182:185], v[116:119]
	v_mfma_f32_16x16x32_bf16 v[112:115], v[174:177], v[182:185], v[112:115]
	v_mfma_f32_16x16x32_bf16 v[100:103], v[166:169], v[190:193], v[100:103]
	v_mfma_f32_16x16x32_bf16 v[96:99], v[174:177], v[190:193], v[96:99]
	v_mfma_f32_16x16x32_bf16 v[84:87], v[166:169], v[198:201], v[84:87]
	v_mfma_f32_16x16x32_bf16 v[80:83], v[174:177], v[198:201], v[80:83]
	v_mfma_f32_16x16x32_bf16 v[68:71], v[166:169], v[206:209], v[68:71]
	v_mfma_f32_16x16x32_bf16 v[64:67], v[174:177], v[206:209], v[64:67]
	v_mfma_f32_16x16x32_bf16 v[116:119], v[170:173], v[186:189], v[116:119]
	v_mfma_f32_16x16x32_bf16 v[112:115], v[178:181], v[186:189], v[112:115]
	v_mfma_f32_16x16x32_bf16 v[100:103], v[170:173], v[194:197], v[100:103]
	v_mfma_f32_16x16x32_bf16 v[96:99], v[178:181], v[194:197], v[96:99]
	v_mfma_f32_16x16x32_bf16 v[84:87], v[170:173], v[202:205], v[84:87]
	v_mfma_f32_16x16x32_bf16 v[80:83], v[178:181], v[202:205], v[80:83]
	v_mfma_f32_16x16x32_bf16 v[68:71], v[170:173], v[210:213], v[68:71]
	v_mfma_f32_16x16x32_bf16 v[64:67], v[178:181], v[210:213], v[64:67]
	s_barrier
	s_add_i32 s3, s61, s8
	s_mov_b32 m0, s3
	ds_read_b128 v[182:185], v157 offset:16384
	ds_read_b128 v[186:189], v157 offset:17408
	ds_read_b128 v[190:193], v157 offset:18432
	ds_read_b128 v[194:197], v157 offset:19456
	ds_read_b128 v[198:201], v157 offset:20480
	ds_read_b128 v[202:205], v157 offset:21504
	ds_read_b128 v[206:209], v157 offset:22528
	ds_read_b128 v[210:213], v157 offset:23552
	global_load_lds_dwordx4 v130, s[56:57]
	s_add_i32 m0, s3, 0x2000
	s_add_u32 s64, s56, 0x20000
	s_addc_u32 s65, s57, 0
	s_add_i32 s3, s62, s8
	global_load_lds_dwordx4 v134, s[56:57]
	s_mov_b32 m0, s3
	s_nop 0
	global_load_lds_dwordx4 v130, s[64:65]
	s_add_i32 m0, s3, 0x2000
	s_nop 0
	global_load_lds_dwordx4 v134, s[64:65]
	s_mov_b32 m0, s9
	s_nop 0
	global_load_lds_dwordx4 v128, s[58:59]
	s_mov_b32 m0, s18
	s_nop 0
	global_load_lds_dwordx4 v132, s[58:59]
	s_waitcnt vmcnt(8)
	s_waitcnt lgkmcnt(0)
	s_barrier
	v_mfma_f32_16x16x32_bf16 v[60:63], v[144:147], v[182:185], v[60:63]
	v_mfma_f32_16x16x32_bf16 v[56:59], v[158:161], v[182:185], v[56:59]
	v_mfma_f32_16x16x32_bf16 v[44:47], v[144:147], v[190:193], v[44:47]
	v_mfma_f32_16x16x32_bf16 v[40:43], v[158:161], v[190:193], v[40:43]
	v_mfma_f32_16x16x32_bf16 v[28:31], v[144:147], v[198:201], v[28:31]
	v_mfma_f32_16x16x32_bf16 v[24:27], v[158:161], v[198:201], v[24:27]
	v_mfma_f32_16x16x32_bf16 v[12:15], v[144:147], v[206:209], v[12:15]
	v_mfma_f32_16x16x32_bf16 v[8:11], v[158:161], v[206:209], v[8:11]
	v_mfma_f32_16x16x32_bf16 v[60:63], v[148:151], v[186:189], v[60:63]
	v_mfma_f32_16x16x32_bf16 v[56:59], v[162:165], v[186:189], v[56:59]
	v_mfma_f32_16x16x32_bf16 v[44:47], v[148:151], v[194:197], v[44:47]
	v_mfma_f32_16x16x32_bf16 v[40:43], v[162:165], v[194:197], v[40:43]
	v_mfma_f32_16x16x32_bf16 v[28:31], v[148:151], v[202:205], v[28:31]
	v_mfma_f32_16x16x32_bf16 v[24:27], v[162:165], v[202:205], v[24:27]
	v_mfma_f32_16x16x32_bf16 v[12:15], v[148:151], v[210:213], v[12:15]
	v_mfma_f32_16x16x32_bf16 v[8:11], v[162:165], v[210:213], v[8:11]
	v_mfma_f32_16x16x32_bf16 v[52:55], v[166:169], v[182:185], v[52:55]
	v_mfma_f32_16x16x32_bf16 v[48:51], v[174:177], v[182:185], v[48:51]
	v_mfma_f32_16x16x32_bf16 v[36:39], v[166:169], v[190:193], v[36:39]
	v_mfma_f32_16x16x32_bf16 v[32:35], v[174:177], v[190:193], v[32:35]
	v_mfma_f32_16x16x32_bf16 v[20:23], v[166:169], v[198:201], v[20:23]
	v_mfma_f32_16x16x32_bf16 v[16:19], v[174:177], v[198:201], v[16:19]
	v_mfma_f32_16x16x32_bf16 v[4:7], v[166:169], v[206:209], v[4:7]
	v_mfma_f32_16x16x32_bf16 v[0:3], v[174:177], v[206:209], v[0:3]
	v_mfma_f32_16x16x32_bf16 v[52:55], v[170:173], v[186:189], v[52:55]
	v_mfma_f32_16x16x32_bf16 v[48:51], v[178:181], v[186:189], v[48:51]
	v_mfma_f32_16x16x32_bf16 v[36:39], v[170:173], v[194:197], v[36:39]
	v_mfma_f32_16x16x32_bf16 v[32:35], v[178:181], v[194:197], v[32:35]
	v_mfma_f32_16x16x32_bf16 v[20:23], v[170:173], v[202:205], v[20:23]
	v_mfma_f32_16x16x32_bf16 v[16:19], v[178:181], v[202:205], v[16:19]
	v_mfma_f32_16x16x32_bf16 v[4:7], v[170:173], v[210:213], v[4:7]
	v_mfma_f32_16x16x32_bf16 v[0:3], v[178:181], v[210:213], v[0:3]
	s_barrier
	s_add_i32 s3, 0, 0x18000
	s_add_i32 s51, 0, 0x1c000
	v_add_u32_e32 v162, s3, v153
	v_add_u32_e32 v178, s51, v153
	ds_read_b128 v[144:147], v162
	ds_read_b128 v[148:151], v162 offset:1024
	ds_read_b128 v[158:161], v162 offset:2048
	ds_read_b128 v[162:165], v162 offset:3072
	ds_read_b128 v[166:169], v178
	ds_read_b128 v[170:173], v178 offset:1024
	ds_read_b128 v[174:177], v178 offset:2048
	ds_read_b128 v[178:181], v178 offset:3072
	s_add_u32 s58, s58, 0x20000
	s_addc_u32 s59, s59, 0
	s_mov_b32 m0, s19
	ds_read_b128 v[182:185], v157 offset:32768
	ds_read_b128 v[186:189], v157 offset:33792
	ds_read_b128 v[190:193], v157 offset:34816
	ds_read_b128 v[194:197], v157 offset:35840
	ds_read_b128 v[198:201], v157 offset:36864
	ds_read_b128 v[202:205], v157 offset:37888
	ds_read_b128 v[206:209], v157 offset:38912
	ds_read_b128 v[210:213], v157 offset:39936
	global_load_lds_dwordx4 v128, s[58:59]
	s_mov_b32 m0, s25
	s_nop 0
	global_load_lds_dwordx4 v132, s[58:59]
	s_waitcnt vmcnt(8)
	s_waitcnt lgkmcnt(0)
	s_barrier
	v_mfma_f32_16x16x32_bf16 v[124:127], v[144:147], v[182:185], v[124:127]
	v_mfma_f32_16x16x32_bf16 v[120:123], v[158:161], v[182:185], v[120:123]
	v_mfma_f32_16x16x32_bf16 v[108:111], v[144:147], v[190:193], v[108:111]
	v_mfma_f32_16x16x32_bf16 v[104:107], v[158:161], v[190:193], v[104:107]
	v_mfma_f32_16x16x32_bf16 v[92:95], v[144:147], v[198:201], v[92:95]
	v_mfma_f32_16x16x32_bf16 v[88:91], v[158:161], v[198:201], v[88:91]
	v_mfma_f32_16x16x32_bf16 v[76:79], v[144:147], v[206:209], v[76:79]
	v_mfma_f32_16x16x32_bf16 v[72:75], v[158:161], v[206:209], v[72:75]
	v_mfma_f32_16x16x32_bf16 v[124:127], v[148:151], v[186:189], v[124:127]
	v_mfma_f32_16x16x32_bf16 v[120:123], v[162:165], v[186:189], v[120:123]
	v_mfma_f32_16x16x32_bf16 v[108:111], v[148:151], v[194:197], v[108:111]
	v_mfma_f32_16x16x32_bf16 v[104:107], v[162:165], v[194:197], v[104:107]
	v_mfma_f32_16x16x32_bf16 v[92:95], v[148:151], v[202:205], v[92:95]
	v_mfma_f32_16x16x32_bf16 v[88:91], v[162:165], v[202:205], v[88:91]
	v_mfma_f32_16x16x32_bf16 v[76:79], v[148:151], v[210:213], v[76:79]
	v_mfma_f32_16x16x32_bf16 v[72:75], v[162:165], v[210:213], v[72:75]
	v_mfma_f32_16x16x32_bf16 v[116:119], v[166:169], v[182:185], v[116:119]
	v_mfma_f32_16x16x32_bf16 v[112:115], v[174:177], v[182:185], v[112:115]
	v_mfma_f32_16x16x32_bf16 v[100:103], v[166:169], v[190:193], v[100:103]
	v_mfma_f32_16x16x32_bf16 v[96:99], v[174:177], v[190:193], v[96:99]
	v_mfma_f32_16x16x32_bf16 v[84:87], v[166:169], v[198:201], v[84:87]
	v_mfma_f32_16x16x32_bf16 v[80:83], v[174:177], v[198:201], v[80:83]
	v_mfma_f32_16x16x32_bf16 v[68:71], v[166:169], v[206:209], v[68:71]
	v_mfma_f32_16x16x32_bf16 v[64:67], v[174:177], v[206:209], v[64:67]
	v_mfma_f32_16x16x32_bf16 v[116:119], v[170:173], v[186:189], v[116:119]
	v_mfma_f32_16x16x32_bf16 v[112:115], v[178:181], v[186:189], v[112:115]
	v_mfma_f32_16x16x32_bf16 v[100:103], v[170:173], v[194:197], v[100:103]
	v_mfma_f32_16x16x32_bf16 v[96:99], v[178:181], v[194:197], v[96:99]
	v_mfma_f32_16x16x32_bf16 v[84:87], v[170:173], v[202:205], v[84:87]
	v_mfma_f32_16x16x32_bf16 v[80:83], v[178:181], v[202:205], v[80:83]
	v_mfma_f32_16x16x32_bf16 v[68:71], v[170:173], v[210:213], v[68:71]
	v_mfma_f32_16x16x32_bf16 v[64:67], v[178:181], v[210:213], v[64:67]
	s_barrier
	s_add_i32 s3, s3, s8
	s_add_u32 s56, s56, 0x80
	s_addc_u32 s57, s57, 0
	s_mov_b32 m0, s3
	ds_read_b128 v[182:185], v157 offset:49152
	ds_read_b128 v[186:189], v157 offset:50176
	ds_read_b128 v[190:193], v157 offset:51200
	ds_read_b128 v[194:197], v157 offset:52224
	ds_read_b128 v[198:201], v157 offset:53248
	ds_read_b128 v[202:205], v157 offset:54272
	ds_read_b128 v[206:209], v157 offset:55296
	ds_read_b128 v[210:213], v157 offset:56320
	global_load_lds_dwordx4 v130, s[56:57]
	s_add_i32 m0, s3, 0x2000
	s_add_i32 s3, s51, s8
	global_load_lds_dwordx4 v134, s[56:57]
	s_add_u32 s56, s56, 0x20000
	s_addc_u32 s57, s57, 0
	s_mov_b32 m0, s3
	s_nop 0
	global_load_lds_dwordx4 v130, s[56:57]
	s_add_i32 m0, s3, 0x2000
	s_nop 0
	global_load_lds_dwordx4 v134, s[56:57]
	s_add_u32 s58, s58, 0xfffe0080
	s_addc_u32 s59, s59, -1
	s_mov_b32 m0, s49
	s_nop 0
	global_load_lds_dwordx4 v128, s[58:59]
	s_mov_b32 m0, s60
	s_nop 0
	global_load_lds_dwordx4 v132, s[58:59]
	s_waitcnt vmcnt(8)
	s_waitcnt lgkmcnt(0)
	s_barrier
	v_mfma_f32_16x16x32_bf16 v[60:63], v[144:147], v[182:185], v[60:63]
	v_mfma_f32_16x16x32_bf16 v[56:59], v[158:161], v[182:185], v[56:59]
	v_mfma_f32_16x16x32_bf16 v[44:47], v[144:147], v[190:193], v[44:47]
	v_mfma_f32_16x16x32_bf16 v[40:43], v[158:161], v[190:193], v[40:43]
	v_mfma_f32_16x16x32_bf16 v[28:31], v[144:147], v[198:201], v[28:31]
	v_mfma_f32_16x16x32_bf16 v[24:27], v[158:161], v[198:201], v[24:27]
	v_mfma_f32_16x16x32_bf16 v[12:15], v[144:147], v[206:209], v[12:15]
	v_mfma_f32_16x16x32_bf16 v[8:11], v[158:161], v[206:209], v[8:11]
	v_mfma_f32_16x16x32_bf16 v[60:63], v[148:151], v[186:189], v[60:63]
	v_mfma_f32_16x16x32_bf16 v[56:59], v[162:165], v[186:189], v[56:59]
	v_mfma_f32_16x16x32_bf16 v[44:47], v[148:151], v[194:197], v[44:47]
	v_mfma_f32_16x16x32_bf16 v[40:43], v[162:165], v[194:197], v[40:43]
	v_mfma_f32_16x16x32_bf16 v[28:31], v[148:151], v[202:205], v[28:31]
	v_mfma_f32_16x16x32_bf16 v[24:27], v[162:165], v[202:205], v[24:27]
	v_mfma_f32_16x16x32_bf16 v[12:15], v[148:151], v[210:213], v[12:15]
	v_mfma_f32_16x16x32_bf16 v[8:11], v[162:165], v[210:213], v[8:11]
	v_mfma_f32_16x16x32_bf16 v[52:55], v[166:169], v[182:185], v[52:55]
	v_mfma_f32_16x16x32_bf16 v[48:51], v[174:177], v[182:185], v[48:51]
	v_mfma_f32_16x16x32_bf16 v[36:39], v[166:169], v[190:193], v[36:39]
	v_mfma_f32_16x16x32_bf16 v[32:35], v[174:177], v[190:193], v[32:35]
	v_mfma_f32_16x16x32_bf16 v[20:23], v[166:169], v[198:201], v[20:23]
	v_mfma_f32_16x16x32_bf16 v[16:19], v[174:177], v[198:201], v[16:19]
	v_mfma_f32_16x16x32_bf16 v[4:7], v[166:169], v[206:209], v[4:7]
	v_mfma_f32_16x16x32_bf16 v[0:3], v[174:177], v[206:209], v[0:3]
	v_mfma_f32_16x16x32_bf16 v[52:55], v[170:173], v[186:189], v[52:55]
	v_mfma_f32_16x16x32_bf16 v[48:51], v[178:181], v[186:189], v[48:51]
	v_mfma_f32_16x16x32_bf16 v[36:39], v[170:173], v[194:197], v[36:39]
	v_mfma_f32_16x16x32_bf16 v[32:35], v[178:181], v[194:197], v[32:35]
	v_mfma_f32_16x16x32_bf16 v[20:23], v[170:173], v[202:205], v[20:23]
	v_mfma_f32_16x16x32_bf16 v[16:19], v[178:181], v[202:205], v[16:19]
	v_mfma_f32_16x16x32_bf16 v[4:7], v[170:173], v[210:213], v[4:7]
	v_mfma_f32_16x16x32_bf16 v[0:3], v[178:181], v[210:213], v[0:3]
	s_barrier
	s_add_i32 s50, s50, 2
	s_add_u32 s52, s52, 0x100
	s_addc_u32 s53, s53, 0
	s_add_u32 s44, s44, 0x100
	s_addc_u32 s45, s45, 0
	s_cmp_gt_u32 s50, 5
	s_cbranch_scc0 .LBB0_2272
	s_and_b64 vcc, exec, s[12:13]
	s_cbranch_vccz .LBB0_2275
	s_barrier

.LBB0_2348:
	ds_read_b128 v[140:143], v149
	ds_read_b128 v[152:155], v149 offset:1024
	ds_read_b128 v[156:159], v149 offset:2048
	ds_read_b128 v[160:163], v149 offset:3072
	ds_read_b128 v[164:167], v150
	ds_read_b128 v[168:171], v150 offset:1024
	ds_read_b128 v[172:175], v150 offset:2048
	ds_read_b128 v[176:179], v150 offset:3072
	s_add_u32 s3, s66, 0xfff80080
	s_addc_u32 s59, s67, -1
	s_cmp_eq_u32 s57, 28
	s_cselect_b32 s75, s0, s59
	s_cselect_b32 s74, s1, s3
	s_cselect_b32 s73, s44, s51
	s_cselect_b32 s72, s45, s50
	s_add_i32 m0, s9, 0xc000
	ds_read_b128 v[180:183], v151
	ds_read_b128 v[184:187], v151 offset:1024
	ds_read_b128 v[188:191], v151 offset:2048
	ds_read_b128 v[192:195], v151 offset:3072
	ds_read_b128 v[196:199], v151 offset:4096
	ds_read_b128 v[200:203], v151 offset:5120
	ds_read_b128 v[204:207], v151 offset:6144
	ds_read_b128 v[208:211], v151 offset:7168
	global_load_lds_dwordx4 v132, s[66:67]
	s_add_i32 m0, s9, 0xe000
	s_nop 0
	global_load_lds_dwordx4 v134, s[66:67]
	s_waitcnt vmcnt(8)
	s_waitcnt lgkmcnt(0)
	s_barrier
	v_mfma_f32_16x16x32_bf16 v[124:127], v[140:143], v[180:183], v[124:127]
	v_mfma_f32_16x16x32_bf16 v[120:123], v[156:159], v[180:183], v[120:123]
	v_mfma_f32_16x16x32_bf16 v[108:111], v[140:143], v[188:191], v[108:111]
	v_mfma_f32_16x16x32_bf16 v[104:107], v[156:159], v[188:191], v[104:107]
	v_mfma_f32_16x16x32_bf16 v[92:95], v[140:143], v[196:199], v[92:95]
	v_mfma_f32_16x16x32_bf16 v[88:91], v[156:159], v[196:199], v[88:91]
	v_mfma_f32_16x16x32_bf16 v[76:79], v[140:143], v[204:207], v[76:79]
	v_mfma_f32_16x16x32_bf16 v[72:75], v[156:159], v[204:207], v[72:75]
	v_mfma_f32_16x16x32_bf16 v[124:127], v[152:155], v[184:187], v[124:127]
	v_mfma_f32_16x16x32_bf16 v[120:123], v[160:163], v[184:187], v[120:123]
	v_mfma_f32_16x16x32_bf16 v[108:111], v[152:155], v[192:195], v[108:111]
	v_mfma_f32_16x16x32_bf16 v[104:107], v[160:163], v[192:195], v[104:107]
	v_mfma_f32_16x16x32_bf16 v[92:95], v[152:155], v[200:203], v[92:95]
	v_mfma_f32_16x16x32_bf16 v[88:91], v[160:163], v[200:203], v[88:91]
	v_mfma_f32_16x16x32_bf16 v[76:79], v[152:155], v[208:211], v[76:79]
	v_mfma_f32_16x16x32_bf16 v[72:75], v[160:163], v[208:211], v[72:75]
	v_mfma_f32_16x16x32_bf16 v[116:119], v[164:167], v[180:183], v[116:119]
	v_mfma_f32_16x16x32_bf16 v[112:115], v[172:175], v[180:183], v[112:115]
	v_mfma_f32_16x16x32_bf16 v[100:103], v[164:167], v[188:191], v[100:103]
	v_mfma_f32_16x16x32_bf16 v[96:99], v[172:175], v[188:191], v[96:99]
	v_mfma_f32_16x16x32_bf16 v[84:87], v[164:167], v[196:199], v[84:87]
	v_mfma_f32_16x16x32_bf16 v[80:83], v[172:175], v[196:199], v[80:83]
	v_mfma_f32_16x16x32_bf16 v[68:71], v[164:167], v[204:207], v[68:71]
	v_mfma_f32_16x16x32_bf16 v[64:67], v[172:175], v[204:207], v[64:67]
	v_mfma_f32_16x16x32_bf16 v[116:119], v[168:171], v[184:187], v[116:119]
	v_mfma_f32_16x16x32_bf16 v[112:115], v[176:179], v[184:187], v[112:115]
	v_mfma_f32_16x16x32_bf16 v[100:103], v[168:171], v[192:195], v[100:103]
	v_mfma_f32_16x16x32_bf16 v[96:99], v[176:179], v[192:195], v[96:99]
	v_mfma_f32_16x16x32_bf16 v[84:87], v[168:171], v[200:203], v[84:87]
	v_mfma_f32_16x16x32_bf16 v[80:83], v[176:179], v[200:203], v[80:83]
	v_mfma_f32_16x16x32_bf16 v[68:71], v[168:171], v[208:211], v[68:71]
	v_mfma_f32_16x16x32_bf16 v[64:67], v[176:179], v[208:211], v[64:67]
	s_barrier
	s_add_i32 s3, s68, s8
	s_mov_b32 m0, s3
	ds_read_b128 v[180:183], v151 offset:16384
	ds_read_b128 v[184:187], v151 offset:17408
	ds_read_b128 v[188:191], v151 offset:18432
	ds_read_b128 v[192:195], v151 offset:19456
	ds_read_b128 v[196:199], v151 offset:20480
	ds_read_b128 v[200:203], v151 offset:21504
	ds_read_b128 v[204:207], v151 offset:22528
	ds_read_b128 v[208:211], v151 offset:23552
	global_load_lds_dwordx4 v128, s[72:73]
	s_add_i32 m0, s3, 0x2000
	s_add_u32 s70, s72, 0x80000
	s_addc_u32 s71, s73, 0
	s_add_i32 s3, s69, s8
	global_load_lds_dwordx4 v130, s[72:73]
	s_mov_b32 m0, s3
	s_nop 0
	global_load_lds_dwordx4 v128, s[70:71]
	s_add_i32 m0, s3, 0x2000
	s_nop 0
	global_load_lds_dwordx4 v130, s[70:71]
	s_mov_b32 m0, s9
	s_nop 0
	global_load_lds_dwordx4 v128, s[74:75]
	s_mov_b32 m0, s18
	s_nop 0
	global_load_lds_dwordx4 v130, s[74:75]
	s_waitcnt vmcnt(8)
	s_waitcnt lgkmcnt(0)
	s_barrier
	v_mfma_f32_16x16x32_bf16 v[60:63], v[140:143], v[180:183], v[60:63]
	v_mfma_f32_16x16x32_bf16 v[56:59], v[156:159], v[180:183], v[56:59]
	v_mfma_f32_16x16x32_bf16 v[44:47], v[140:143], v[188:191], v[44:47]
	v_mfma_f32_16x16x32_bf16 v[40:43], v[156:159], v[188:191], v[40:43]
	v_mfma_f32_16x16x32_bf16 v[28:31], v[140:143], v[196:199], v[28:31]
	v_mfma_f32_16x16x32_bf16 v[24:27], v[156:159], v[196:199], v[24:27]
	v_mfma_f32_16x16x32_bf16 v[12:15], v[140:143], v[204:207], v[12:15]
	v_mfma_f32_16x16x32_bf16 v[8:11], v[156:159], v[204:207], v[8:11]
	v_mfma_f32_16x16x32_bf16 v[60:63], v[152:155], v[184:187], v[60:63]
	v_mfma_f32_16x16x32_bf16 v[56:59], v[160:163], v[184:187], v[56:59]
	v_mfma_f32_16x16x32_bf16 v[44:47], v[152:155], v[192:195], v[44:47]
	v_mfma_f32_16x16x32_bf16 v[40:43], v[160:163], v[192:195], v[40:43]
	v_mfma_f32_16x16x32_bf16 v[28:31], v[152:155], v[200:203], v[28:31]
	v_mfma_f32_16x16x32_bf16 v[24:27], v[160:163], v[200:203], v[24:27]
	v_mfma_f32_16x16x32_bf16 v[12:15], v[152:155], v[208:211], v[12:15]
	v_mfma_f32_16x16x32_bf16 v[8:11], v[160:163], v[208:211], v[8:11]
	v_mfma_f32_16x16x32_bf16 v[52:55], v[164:167], v[180:183], v[52:55]
	v_mfma_f32_16x16x32_bf16 v[48:51], v[172:175], v[180:183], v[48:51]
	v_mfma_f32_16x16x32_bf16 v[36:39], v[164:167], v[188:191], v[36:39]
	v_mfma_f32_16x16x32_bf16 v[32:35], v[172:175], v[188:191], v[32:35]
	v_mfma_f32_16x16x32_bf16 v[20:23], v[164:167], v[196:199], v[20:23]
	v_mfma_f32_16x16x32_bf16 v[16:19], v[172:175], v[196:199], v[16:19]
	v_mfma_f32_16x16x32_bf16 v[4:7], v[164:167], v[204:207], v[4:7]
	v_mfma_f32_16x16x32_bf16 v[0:3], v[172:175], v[204:207], v[0:3]
	v_mfma_f32_16x16x32_bf16 v[52:55], v[168:171], v[184:187], v[52:55]
	v_mfma_f32_16x16x32_bf16 v[48:51], v[176:179], v[184:187], v[48:51]
	v_mfma_f32_16x16x32_bf16 v[36:39], v[168:171], v[192:195], v[36:39]
	v_mfma_f32_16x16x32_bf16 v[32:35], v[176:179], v[192:195], v[32:35]
	v_mfma_f32_16x16x32_bf16 v[20:23], v[168:171], v[200:203], v[20:23]
	v_mfma_f32_16x16x32_bf16 v[16:19], v[176:179], v[200:203], v[16:19]
	v_mfma_f32_16x16x32_bf16 v[4:7], v[168:171], v[208:211], v[4:7]
	v_mfma_f32_16x16x32_bf16 v[0:3], v[176:179], v[208:211], v[0:3]
	s_barrier
	s_add_i32 s3, 0, 0x18000
	s_add_i32 s59, 0, 0x1c000
	v_add_u32_e32 v160, s3, v147
	v_add_u32_e32 v176, s59, v147
	ds_read_b128 v[140:143], v160
	ds_read_b128 v[152:155], v160 offset:1024
	ds_read_b128 v[156:159], v160 offset:2048
	ds_read_b128 v[160:163], v160 offset:3072
	ds_read_b128 v[164:167], v176
	ds_read_b128 v[168:171], v176 offset:1024
	ds_read_b128 v[172:175], v176 offset:2048
	ds_read_b128 v[176:179], v176 offset:3072
	s_add_u32 s70, s74, 0x80000
	s_addc_u32 s71, s75, 0
	s_mov_b32 m0, s19
	ds_read_b128 v[180:183], v151 offset:32768
	ds_read_b128 v[184:187], v151 offset:33792
	ds_read_b128 v[188:191], v151 offset:34816
	ds_read_b128 v[192:195], v151 offset:35840
	ds_read_b128 v[196:199], v151 offset:36864
	ds_read_b128 v[200:203], v151 offset:37888
	ds_read_b128 v[204:207], v151 offset:38912
	ds_read_b128 v[208:211], v151 offset:39936
	global_load_lds_dwordx4 v128, s[70:71]
	s_mov_b32 m0, s25
	s_nop 0
	global_load_lds_dwordx4 v130, s[70:71]
	s_waitcnt vmcnt(8)
	s_waitcnt lgkmcnt(0)
	s_barrier
	v_mfma_f32_16x16x32_bf16 v[124:127], v[140:143], v[180:183], v[124:127]
	v_mfma_f32_16x16x32_bf16 v[120:123], v[156:159], v[180:183], v[120:123]
	v_mfma_f32_16x16x32_bf16 v[108:111], v[140:143], v[188:191], v[108:111]
	v_mfma_f32_16x16x32_bf16 v[104:107], v[156:159], v[188:191], v[104:107]
	v_mfma_f32_16x16x32_bf16 v[92:95], v[140:143], v[196:199], v[92:95]
	v_mfma_f32_16x16x32_bf16 v[88:91], v[156:159], v[196:199], v[88:91]
	v_mfma_f32_16x16x32_bf16 v[76:79], v[140:143], v[204:207], v[76:79]
	v_mfma_f32_16x16x32_bf16 v[72:75], v[156:159], v[204:207], v[72:75]
	v_mfma_f32_16x16x32_bf16 v[124:127], v[152:155], v[184:187], v[124:127]
	v_mfma_f32_16x16x32_bf16 v[120:123], v[160:163], v[184:187], v[120:123]
	v_mfma_f32_16x16x32_bf16 v[108:111], v[152:155], v[192:195], v[108:111]
	v_mfma_f32_16x16x32_bf16 v[104:107], v[160:163], v[192:195], v[104:107]
	v_mfma_f32_16x16x32_bf16 v[92:95], v[152:155], v[200:203], v[92:95]
	v_mfma_f32_16x16x32_bf16 v[88:91], v[160:163], v[200:203], v[88:91]
	v_mfma_f32_16x16x32_bf16 v[76:79], v[152:155], v[208:211], v[76:79]
	v_mfma_f32_16x16x32_bf16 v[72:75], v[160:163], v[208:211], v[72:75]
	v_mfma_f32_16x16x32_bf16 v[116:119], v[164:167], v[180:183], v[116:119]
	v_mfma_f32_16x16x32_bf16 v[112:115], v[172:175], v[180:183], v[112:115]
	v_mfma_f32_16x16x32_bf16 v[100:103], v[164:167], v[188:191], v[100:103]
	v_mfma_f32_16x16x32_bf16 v[96:99], v[172:175], v[188:191], v[96:99]
	v_mfma_f32_16x16x32_bf16 v[84:87], v[164:167], v[196:199], v[84:87]
	v_mfma_f32_16x16x32_bf16 v[80:83], v[172:175], v[196:199], v[80:83]
	v_mfma_f32_16x16x32_bf16 v[68:71], v[164:167], v[204:207], v[68:71]
	v_mfma_f32_16x16x32_bf16 v[64:67], v[172:175], v[204:207], v[64:67]
	v_mfma_f32_16x16x32_bf16 v[116:119], v[168:171], v[184:187], v[116:119]
	v_mfma_f32_16x16x32_bf16 v[112:115], v[176:179], v[184:187], v[112:115]
	v_mfma_f32_16x16x32_bf16 v[100:103], v[168:171], v[192:195], v[100:103]
	v_mfma_f32_16x16x32_bf16 v[96:99], v[176:179], v[192:195], v[96:99]
	v_mfma_f32_16x16x32_bf16 v[84:87], v[168:171], v[200:203], v[84:87]
	v_mfma_f32_16x16x32_bf16 v[80:83], v[176:179], v[200:203], v[80:83]
	v_mfma_f32_16x16x32_bf16 v[68:71], v[168:171], v[208:211], v[68:71]
	v_mfma_f32_16x16x32_bf16 v[64:67], v[176:179], v[208:211], v[64:67]
	s_barrier
	s_add_i32 s3, s3, s8
	s_add_u32 s70, s72, 0x80
	s_addc_u32 s71, s73, 0
	s_mov_b32 m0, s3
	ds_read_b128 v[180:183], v151 offset:49152
	ds_read_b128 v[184:187], v151 offset:50176
	ds_read_b128 v[188:191], v151 offset:51200
	ds_read_b128 v[192:195], v151 offset:52224
	ds_read_b128 v[196:199], v151 offset:53248
	ds_read_b128 v[200:203], v151 offset:54272
	ds_read_b128 v[204:207], v151 offset:55296
	ds_read_b128 v[208:211], v151 offset:56320
	global_load_lds_dwordx4 v128, s[70:71]
	s_add_i32 m0, s3, 0x2000
	s_add_i32 s3, s59, s8
	global_load_lds_dwordx4 v130, s[70:71]
	s_add_u32 s70, s70, 0x80000
	s_addc_u32 s71, s71, 0
	s_mov_b32 m0, s3
	s_nop 0
	global_load_lds_dwordx4 v128, s[70:71]
	s_add_i32 m0, s3, 0x2000
	s_nop 0
	global_load_lds_dwordx4 v130, s[70:71]
	s_add_u32 s74, s74, 0x80
	s_addc_u32 s75, s75, 0
	s_mov_b32 m0, s33
	s_nop 0
	global_load_lds_dwordx4 v128, s[74:75]
	s_mov_b32 m0, s65
	s_nop 0
	global_load_lds_dwordx4 v130, s[74:75]
	s_waitcnt vmcnt(8)
	s_waitcnt lgkmcnt(0)
	s_barrier
	v_mfma_f32_16x16x32_bf16 v[60:63], v[140:143], v[180:183], v[60:63]
	v_mfma_f32_16x16x32_bf16 v[56:59], v[156:159], v[180:183], v[56:59]
	v_mfma_f32_16x16x32_bf16 v[44:47], v[140:143], v[188:191], v[44:47]
	v_mfma_f32_16x16x32_bf16 v[40:43], v[156:159], v[188:191], v[40:43]
	v_mfma_f32_16x16x32_bf16 v[28:31], v[140:143], v[196:199], v[28:31]
	v_mfma_f32_16x16x32_bf16 v[24:27], v[156:159], v[196:199], v[24:27]
	v_mfma_f32_16x16x32_bf16 v[12:15], v[140:143], v[204:207], v[12:15]
	v_mfma_f32_16x16x32_bf16 v[8:11], v[156:159], v[204:207], v[8:11]
	v_mfma_f32_16x16x32_bf16 v[60:63], v[152:155], v[184:187], v[60:63]
	v_mfma_f32_16x16x32_bf16 v[56:59], v[160:163], v[184:187], v[56:59]
	v_mfma_f32_16x16x32_bf16 v[44:47], v[152:155], v[192:195], v[44:47]
	v_mfma_f32_16x16x32_bf16 v[40:43], v[160:163], v[192:195], v[40:43]
	v_mfma_f32_16x16x32_bf16 v[28:31], v[152:155], v[200:203], v[28:31]
	v_mfma_f32_16x16x32_bf16 v[24:27], v[160:163], v[200:203], v[24:27]
	v_mfma_f32_16x16x32_bf16 v[12:15], v[152:155], v[208:211], v[12:15]
	v_mfma_f32_16x16x32_bf16 v[8:11], v[160:163], v[208:211], v[8:11]
	v_mfma_f32_16x16x32_bf16 v[52:55], v[164:167], v[180:183], v[52:55]
	v_mfma_f32_16x16x32_bf16 v[48:51], v[172:175], v[180:183], v[48:51]
	v_mfma_f32_16x16x32_bf16 v[36:39], v[164:167], v[188:191], v[36:39]
	v_mfma_f32_16x16x32_bf16 v[32:35], v[172:175], v[188:191], v[32:35]
	v_mfma_f32_16x16x32_bf16 v[20:23], v[164:167], v[196:199], v[20:23]
	v_mfma_f32_16x16x32_bf16 v[16:19], v[172:175], v[196:199], v[16:19]
	v_mfma_f32_16x16x32_bf16 v[4:7], v[164:167], v[204:207], v[4:7]
	v_mfma_f32_16x16x32_bf16 v[0:3], v[172:175], v[204:207], v[0:3]
	v_mfma_f32_16x16x32_bf16 v[52:55], v[168:171], v[184:187], v[52:55]
	v_mfma_f32_16x16x32_bf16 v[48:51], v[176:179], v[184:187], v[48:51]
	v_mfma_f32_16x16x32_bf16 v[36:39], v[168:171], v[192:195], v[36:39]
	v_mfma_f32_16x16x32_bf16 v[32:35], v[176:179], v[192:195], v[32:35]
	v_mfma_f32_16x16x32_bf16 v[20:23], v[168:171], v[200:203], v[20:23]
	v_mfma_f32_16x16x32_bf16 v[16:19], v[176:179], v[200:203], v[16:19]
	v_mfma_f32_16x16x32_bf16 v[4:7], v[168:171], v[208:211], v[4:7]
	v_mfma_f32_16x16x32_bf16 v[0:3], v[176:179], v[208:211], v[0:3]
	s_barrier
	s_add_i32 s57, s57, 2
	s_add_u32 s66, s66, 0x100
	s_addc_u32 s67, s67, 0
	s_add_u32 s50, s50, 0x100
	s_addc_u32 s51, s51, 0
	s_cmp_gt_u32 s57, 29
	s_cbranch_scc0 .LBB0_2348
	s_and_b64 vcc, exec, s[14:15]
	s_cbranch_vccz .LBB0_2351
	s_barrier

.LBB0_2479:
	ds_read_b128 v[154:157], v150
	ds_read_b128 v[158:161], v150 offset:1024
	ds_read_b128 v[162:165], v150 offset:2048
	ds_read_b128 v[166:169], v150 offset:3072
	ds_read_b128 v[170:173], v151
	ds_read_b128 v[174:177], v151 offset:1024
	ds_read_b128 v[178:181], v151 offset:2048
	ds_read_b128 v[182:185], v151 offset:3072
	s_add_u32 s3, s42, 0xfff80080
	s_addc_u32 s44, s43, -1
	s_cmp_eq_u32 s51, 28
	s_cselect_b32 s49, s0, s44
	s_cselect_b32 s48, s1, s3
	s_cselect_b32 s45, s15, s50
	s_cselect_b32 s44, s17, s41
	s_add_i32 m0, s19, 0xc000
	ds_read_b128 v[186:189], v152
	ds_read_b128 v[190:193], v152 offset:1024
	ds_read_b128 v[194:197], v152 offset:2048
	ds_read_b128 v[198:201], v152 offset:3072
	ds_read_b128 v[202:205], v152 offset:4096
	ds_read_b128 v[206:209], v152 offset:5120
	ds_read_b128 v[210:213], v152 offset:6144
	ds_read_b128 v[214:217], v152 offset:7168
	global_load_lds_dwordx4 v138, s[42:43]
	s_add_i32 m0, s19, 0xe000
	s_nop 0
	global_load_lds_dwordx4 v140, s[42:43]
	s_waitcnt vmcnt(8)
	s_waitcnt lgkmcnt(0)
	s_barrier
	v_mfma_f32_16x16x32_bf16 v[124:127], v[154:157], v[186:189], v[124:127]
	v_mfma_f32_16x16x32_bf16 v[120:123], v[162:165], v[186:189], v[120:123]
	v_mfma_f32_16x16x32_bf16 v[108:111], v[154:157], v[194:197], v[108:111]
	v_mfma_f32_16x16x32_bf16 v[104:107], v[162:165], v[194:197], v[104:107]
	v_mfma_f32_16x16x32_bf16 v[92:95], v[154:157], v[202:205], v[92:95]
	v_mfma_f32_16x16x32_bf16 v[88:91], v[162:165], v[202:205], v[88:91]
	v_mfma_f32_16x16x32_bf16 v[76:79], v[154:157], v[210:213], v[76:79]
	v_mfma_f32_16x16x32_bf16 v[72:75], v[162:165], v[210:213], v[72:75]
	v_mfma_f32_16x16x32_bf16 v[124:127], v[158:161], v[190:193], v[124:127]
	v_mfma_f32_16x16x32_bf16 v[120:123], v[166:169], v[190:193], v[120:123]
	v_mfma_f32_16x16x32_bf16 v[108:111], v[158:161], v[198:201], v[108:111]
	v_mfma_f32_16x16x32_bf16 v[104:107], v[166:169], v[198:201], v[104:107]
	v_mfma_f32_16x16x32_bf16 v[92:95], v[158:161], v[206:209], v[92:95]
	v_mfma_f32_16x16x32_bf16 v[88:91], v[166:169], v[206:209], v[88:91]
	v_mfma_f32_16x16x32_bf16 v[76:79], v[158:161], v[214:217], v[76:79]
	v_mfma_f32_16x16x32_bf16 v[72:75], v[166:169], v[214:217], v[72:75]
	v_mfma_f32_16x16x32_bf16 v[116:119], v[170:173], v[186:189], v[116:119]
	v_mfma_f32_16x16x32_bf16 v[112:115], v[178:181], v[186:189], v[112:115]
	v_mfma_f32_16x16x32_bf16 v[100:103], v[170:173], v[194:197], v[100:103]
	v_mfma_f32_16x16x32_bf16 v[96:99], v[178:181], v[194:197], v[96:99]
	v_mfma_f32_16x16x32_bf16 v[84:87], v[170:173], v[202:205], v[84:87]
	v_mfma_f32_16x16x32_bf16 v[80:83], v[178:181], v[202:205], v[80:83]
	v_mfma_f32_16x16x32_bf16 v[68:71], v[170:173], v[210:213], v[68:71]
	v_mfma_f32_16x16x32_bf16 v[64:67], v[178:181], v[210:213], v[64:67]
	v_mfma_f32_16x16x32_bf16 v[116:119], v[174:177], v[190:193], v[116:119]
	v_mfma_f32_16x16x32_bf16 v[112:115], v[182:185], v[190:193], v[112:115]
	v_mfma_f32_16x16x32_bf16 v[100:103], v[174:177], v[198:201], v[100:103]
	v_mfma_f32_16x16x32_bf16 v[96:99], v[182:185], v[198:201], v[96:99]
	v_mfma_f32_16x16x32_bf16 v[84:87], v[174:177], v[206:209], v[84:87]
	v_mfma_f32_16x16x32_bf16 v[80:83], v[182:185], v[206:209], v[80:83]
	v_mfma_f32_16x16x32_bf16 v[68:71], v[174:177], v[214:217], v[68:71]
	v_mfma_f32_16x16x32_bf16 v[64:67], v[182:185], v[214:217], v[64:67]
	s_barrier
	s_add_i32 s3, s54, s18
	s_mov_b32 m0, s3
	ds_read_b128 v[186:189], v152 offset:16384
	ds_read_b128 v[190:193], v152 offset:17408
	ds_read_b128 v[194:197], v152 offset:18432
	ds_read_b128 v[198:201], v152 offset:19456
	ds_read_b128 v[202:205], v152 offset:20480
	ds_read_b128 v[206:209], v152 offset:21504
	ds_read_b128 v[210:213], v152 offset:22528
	ds_read_b128 v[214:217], v152 offset:23552
	global_load_lds_dwordx4 v130, s[44:45]
	s_add_i32 m0, s3, 0x2000
	s_add_u32 s58, s44, 0x80000
	s_addc_u32 s59, s45, 0
	s_add_i32 s3, s55, s18
	global_load_lds_dwordx4 v134, s[44:45]
	s_mov_b32 m0, s3
	s_nop 0
	global_load_lds_dwordx4 v130, s[58:59]
	s_add_i32 m0, s3, 0x2000
	s_nop 0
	global_load_lds_dwordx4 v134, s[58:59]
	s_mov_b32 m0, s19
	s_nop 0
	global_load_lds_dwordx4 v128, s[48:49]
	s_mov_b32 m0, s25
	s_nop 0
	global_load_lds_dwordx4 v132, s[48:49]
	s_waitcnt vmcnt(8)
	s_waitcnt lgkmcnt(0)
	s_barrier
	v_mfma_f32_16x16x32_bf16 v[60:63], v[154:157], v[186:189], v[60:63]
	v_mfma_f32_16x16x32_bf16 v[56:59], v[162:165], v[186:189], v[56:59]
	v_mfma_f32_16x16x32_bf16 v[44:47], v[154:157], v[194:197], v[44:47]
	v_mfma_f32_16x16x32_bf16 v[40:43], v[162:165], v[194:197], v[40:43]
	v_mfma_f32_16x16x32_bf16 v[28:31], v[154:157], v[202:205], v[28:31]
	v_mfma_f32_16x16x32_bf16 v[24:27], v[162:165], v[202:205], v[24:27]
	v_mfma_f32_16x16x32_bf16 v[12:15], v[154:157], v[210:213], v[12:15]
	v_mfma_f32_16x16x32_bf16 v[8:11], v[162:165], v[210:213], v[8:11]
	v_mfma_f32_16x16x32_bf16 v[60:63], v[158:161], v[190:193], v[60:63]
	v_mfma_f32_16x16x32_bf16 v[56:59], v[166:169], v[190:193], v[56:59]
	v_mfma_f32_16x16x32_bf16 v[44:47], v[158:161], v[198:201], v[44:47]
	v_mfma_f32_16x16x32_bf16 v[40:43], v[166:169], v[198:201], v[40:43]
	v_mfma_f32_16x16x32_bf16 v[28:31], v[158:161], v[206:209], v[28:31]
	v_mfma_f32_16x16x32_bf16 v[24:27], v[166:169], v[206:209], v[24:27]
	v_mfma_f32_16x16x32_bf16 v[12:15], v[158:161], v[214:217], v[12:15]
	v_mfma_f32_16x16x32_bf16 v[8:11], v[166:169], v[214:217], v[8:11]
	v_mfma_f32_16x16x32_bf16 v[52:55], v[170:173], v[186:189], v[52:55]
	v_mfma_f32_16x16x32_bf16 v[48:51], v[178:181], v[186:189], v[48:51]
	v_mfma_f32_16x16x32_bf16 v[36:39], v[170:173], v[194:197], v[36:39]
	v_mfma_f32_16x16x32_bf16 v[32:35], v[178:181], v[194:197], v[32:35]
	v_mfma_f32_16x16x32_bf16 v[20:23], v[170:173], v[202:205], v[20:23]
	v_mfma_f32_16x16x32_bf16 v[16:19], v[178:181], v[202:205], v[16:19]
	v_mfma_f32_16x16x32_bf16 v[4:7], v[170:173], v[210:213], v[4:7]
	v_mfma_f32_16x16x32_bf16 v[0:3], v[178:181], v[210:213], v[0:3]
	v_mfma_f32_16x16x32_bf16 v[52:55], v[174:177], v[190:193], v[52:55]
	v_mfma_f32_16x16x32_bf16 v[48:51], v[182:185], v[190:193], v[48:51]
	v_mfma_f32_16x16x32_bf16 v[36:39], v[174:177], v[198:201], v[36:39]
	v_mfma_f32_16x16x32_bf16 v[32:35], v[182:185], v[198:201], v[32:35]
	v_mfma_f32_16x16x32_bf16 v[20:23], v[174:177], v[206:209], v[20:23]
	v_mfma_f32_16x16x32_bf16 v[16:19], v[182:185], v[206:209], v[16:19]
	v_mfma_f32_16x16x32_bf16 v[4:7], v[174:177], v[214:217], v[4:7]
	v_mfma_f32_16x16x32_bf16 v[0:3], v[182:185], v[214:217], v[0:3]
	s_barrier
	s_add_i32 s3, 0, 0x18000
	v_add_u32_e32 v153, s3, v149
	s_add_i32 s57, 0, 0x1c000
	ds_read_b128 v[154:157], v153
	ds_read_b128 v[158:161], v153 offset:1024
	ds_read_b128 v[162:165], v153 offset:2048
	ds_read_b128 v[166:169], v153 offset:3072
	v_add_u32_e32 v153, s57, v149
	ds_read_b128 v[170:173], v153
	ds_read_b128 v[174:177], v153 offset:1024
	ds_read_b128 v[178:181], v153 offset:2048
	ds_read_b128 v[182:185], v153 offset:3072
	s_add_u32 s48, s48, 0x80000
	s_addc_u32 s49, s49, 0
	s_mov_b32 m0, s27
	ds_read_b128 v[186:189], v152 offset:32768
	ds_read_b128 v[190:193], v152 offset:33792
	ds_read_b128 v[194:197], v152 offset:34816
	ds_read_b128 v[198:201], v152 offset:35840
	ds_read_b128 v[202:205], v152 offset:36864
	ds_read_b128 v[206:209], v152 offset:37888
	ds_read_b128 v[210:213], v152 offset:38912
	ds_read_b128 v[214:217], v152 offset:39936
	global_load_lds_dwordx4 v128, s[48:49]
	s_mov_b32 m0, s33
	s_nop 0
	global_load_lds_dwordx4 v132, s[48:49]
	s_waitcnt vmcnt(8)
	s_waitcnt lgkmcnt(0)
	s_barrier
	v_mfma_f32_16x16x32_bf16 v[124:127], v[154:157], v[186:189], v[124:127]
	v_mfma_f32_16x16x32_bf16 v[120:123], v[162:165], v[186:189], v[120:123]
	v_mfma_f32_16x16x32_bf16 v[108:111], v[154:157], v[194:197], v[108:111]
	v_mfma_f32_16x16x32_bf16 v[104:107], v[162:165], v[194:197], v[104:107]
	v_mfma_f32_16x16x32_bf16 v[92:95], v[154:157], v[202:205], v[92:95]
	v_mfma_f32_16x16x32_bf16 v[88:91], v[162:165], v[202:205], v[88:91]
	v_mfma_f32_16x16x32_bf16 v[76:79], v[154:157], v[210:213], v[76:79]
	v_mfma_f32_16x16x32_bf16 v[72:75], v[162:165], v[210:213], v[72:75]
	v_mfma_f32_16x16x32_bf16 v[124:127], v[158:161], v[190:193], v[124:127]
	v_mfma_f32_16x16x32_bf16 v[120:123], v[166:169], v[190:193], v[120:123]
	v_mfma_f32_16x16x32_bf16 v[108:111], v[158:161], v[198:201], v[108:111]
	v_mfma_f32_16x16x32_bf16 v[104:107], v[166:169], v[198:201], v[104:107]
	v_mfma_f32_16x16x32_bf16 v[92:95], v[158:161], v[206:209], v[92:95]
	v_mfma_f32_16x16x32_bf16 v[88:91], v[166:169], v[206:209], v[88:91]
	v_mfma_f32_16x16x32_bf16 v[76:79], v[158:161], v[214:217], v[76:79]
	v_mfma_f32_16x16x32_bf16 v[72:75], v[166:169], v[214:217], v[72:75]
	v_mfma_f32_16x16x32_bf16 v[116:119], v[170:173], v[186:189], v[116:119]
	v_mfma_f32_16x16x32_bf16 v[112:115], v[178:181], v[186:189], v[112:115]
	v_mfma_f32_16x16x32_bf16 v[100:103], v[170:173], v[194:197], v[100:103]
	v_mfma_f32_16x16x32_bf16 v[96:99], v[178:181], v[194:197], v[96:99]
	v_mfma_f32_16x16x32_bf16 v[84:87], v[170:173], v[202:205], v[84:87]
	v_mfma_f32_16x16x32_bf16 v[80:83], v[178:181], v[202:205], v[80:83]
	v_mfma_f32_16x16x32_bf16 v[68:71], v[170:173], v[210:213], v[68:71]
	v_mfma_f32_16x16x32_bf16 v[64:67], v[178:181], v[210:213], v[64:67]
	v_mfma_f32_16x16x32_bf16 v[116:119], v[174:177], v[190:193], v[116:119]
	v_mfma_f32_16x16x32_bf16 v[112:115], v[182:185], v[190:193], v[112:115]
	v_mfma_f32_16x16x32_bf16 v[100:103], v[174:177], v[198:201], v[100:103]
	v_mfma_f32_16x16x32_bf16 v[96:99], v[182:185], v[198:201], v[96:99]
	v_mfma_f32_16x16x32_bf16 v[84:87], v[174:177], v[206:209], v[84:87]
	v_mfma_f32_16x16x32_bf16 v[80:83], v[182:185], v[206:209], v[80:83]
	v_mfma_f32_16x16x32_bf16 v[68:71], v[174:177], v[214:217], v[68:71]
	v_mfma_f32_16x16x32_bf16 v[64:67], v[182:185], v[214:217], v[64:67]
	s_barrier
	s_add_i32 s3, s3, s18
	s_add_u32 s44, s44, 0x80
	s_addc_u32 s45, s45, 0
	s_mov_b32 m0, s3
	ds_read_b128 v[186:189], v152 offset:49152
	ds_read_b128 v[190:193], v152 offset:50176
	ds_read_b128 v[194:197], v152 offset:51200
	ds_read_b128 v[198:201], v152 offset:52224
	ds_read_b128 v[202:205], v152 offset:53248
	ds_read_b128 v[206:209], v152 offset:54272
	ds_read_b128 v[210:213], v152 offset:55296
	ds_read_b128 v[214:217], v152 offset:56320
	global_load_lds_dwordx4 v130, s[44:45]
	s_add_i32 m0, s3, 0x2000
	s_add_i32 s3, s57, s18
	global_load_lds_dwordx4 v134, s[44:45]
	s_add_u32 s44, s44, 0x80000
	s_addc_u32 s45, s45, 0
	s_mov_b32 m0, s3
	s_nop 0
	global_load_lds_dwordx4 v130, s[44:45]
	s_add_i32 m0, s3, 0x2000
	s_nop 0
	global_load_lds_dwordx4 v134, s[44:45]
	s_add_u32 s48, s48, 0xfff80080
	s_addc_u32 s49, s49, -1
	s_mov_b32 m0, s52
	s_nop 0
	global_load_lds_dwordx4 v128, s[48:49]
	s_mov_b32 m0, s53
	s_nop 0
	global_load_lds_dwordx4 v132, s[48:49]
	s_waitcnt vmcnt(8)
	s_waitcnt lgkmcnt(0)
	s_barrier
	v_mfma_f32_16x16x32_bf16 v[60:63], v[154:157], v[186:189], v[60:63]
	v_mfma_f32_16x16x32_bf16 v[56:59], v[162:165], v[186:189], v[56:59]
	v_mfma_f32_16x16x32_bf16 v[44:47], v[154:157], v[194:197], v[44:47]
	v_mfma_f32_16x16x32_bf16 v[40:43], v[162:165], v[194:197], v[40:43]
	v_mfma_f32_16x16x32_bf16 v[28:31], v[154:157], v[202:205], v[28:31]
	v_mfma_f32_16x16x32_bf16 v[24:27], v[162:165], v[202:205], v[24:27]
	v_mfma_f32_16x16x32_bf16 v[12:15], v[154:157], v[210:213], v[12:15]
	v_mfma_f32_16x16x32_bf16 v[8:11], v[162:165], v[210:213], v[8:11]
	v_mfma_f32_16x16x32_bf16 v[60:63], v[158:161], v[190:193], v[60:63]
	v_mfma_f32_16x16x32_bf16 v[56:59], v[166:169], v[190:193], v[56:59]
	v_mfma_f32_16x16x32_bf16 v[44:47], v[158:161], v[198:201], v[44:47]
	v_mfma_f32_16x16x32_bf16 v[40:43], v[166:169], v[198:201], v[40:43]
	v_mfma_f32_16x16x32_bf16 v[28:31], v[158:161], v[206:209], v[28:31]
	v_mfma_f32_16x16x32_bf16 v[24:27], v[166:169], v[206:209], v[24:27]
	v_mfma_f32_16x16x32_bf16 v[12:15], v[158:161], v[214:217], v[12:15]
	v_mfma_f32_16x16x32_bf16 v[8:11], v[166:169], v[214:217], v[8:11]
	v_mfma_f32_16x16x32_bf16 v[52:55], v[170:173], v[186:189], v[52:55]
	v_mfma_f32_16x16x32_bf16 v[48:51], v[178:181], v[186:189], v[48:51]
	v_mfma_f32_16x16x32_bf16 v[36:39], v[170:173], v[194:197], v[36:39]
	v_mfma_f32_16x16x32_bf16 v[32:35], v[178:181], v[194:197], v[32:35]
	v_mfma_f32_16x16x32_bf16 v[20:23], v[170:173], v[202:205], v[20:23]
	v_mfma_f32_16x16x32_bf16 v[16:19], v[178:181], v[202:205], v[16:19]
	v_mfma_f32_16x16x32_bf16 v[4:7], v[170:173], v[210:213], v[4:7]
	v_mfma_f32_16x16x32_bf16 v[0:3], v[178:181], v[210:213], v[0:3]
	v_mfma_f32_16x16x32_bf16 v[52:55], v[174:177], v[190:193], v[52:55]
	v_mfma_f32_16x16x32_bf16 v[48:51], v[182:185], v[190:193], v[48:51]
	v_mfma_f32_16x16x32_bf16 v[36:39], v[174:177], v[198:201], v[36:39]
	v_mfma_f32_16x16x32_bf16 v[32:35], v[182:185], v[198:201], v[32:35]
	v_mfma_f32_16x16x32_bf16 v[20:23], v[174:177], v[206:209], v[20:23]
	v_mfma_f32_16x16x32_bf16 v[16:19], v[182:185], v[206:209], v[16:19]
	v_mfma_f32_16x16x32_bf16 v[4:7], v[174:177], v[214:217], v[4:7]
	v_mfma_f32_16x16x32_bf16 v[0:3], v[182:185], v[214:217], v[0:3]
	s_barrier
	s_add_i32 s51, s51, 2
	s_add_u32 s42, s42, 0x100
	s_addc_u32 s43, s43, 0
	s_add_u32 s41, s41, 0x100
	s_addc_u32 s50, s50, 0
	s_cmp_gt_u32 s51, 29
	s_cbranch_scc0 .LBB0_2479
	s_and_b64 vcc, exec, s[12:13]
	s_cbranch_vccz .LBB0_2482
	s_barrier

.LBB0_2555:
	ds_read_b128 v[140:143], v149
	ds_read_b128 v[152:155], v149 offset:1024
	ds_read_b128 v[156:159], v149 offset:2048
	ds_read_b128 v[160:163], v149 offset:3072
	ds_read_b128 v[164:167], v150
	ds_read_b128 v[168:171], v150 offset:1024
	ds_read_b128 v[172:175], v150 offset:2048
	ds_read_b128 v[176:179], v150 offset:3072
	s_add_u32 s3, s48, 0xffe00080
	s_addc_u32 s52, s49, -1
	s_cmpk_eq_i32 s64, 0x7c
	s_cselect_b32 s55, s0, s52
	s_cselect_b32 s54, s1, s3
	s_cselect_b32 s53, s35, s51
	s_cselect_b32 s52, s37, s50
	s_add_i32 m0, s27, 0xc000
	ds_read_b128 v[180:183], v151
	ds_read_b128 v[184:187], v151 offset:1024
	ds_read_b128 v[188:191], v151 offset:2048
	ds_read_b128 v[192:195], v151 offset:3072
	ds_read_b128 v[196:199], v151 offset:4096
	ds_read_b128 v[200:203], v151 offset:5120
	ds_read_b128 v[204:207], v151 offset:6144
	ds_read_b128 v[208:211], v151 offset:7168
	global_load_lds_dwordx4 v132, s[48:49]
	s_add_i32 m0, s27, 0xe000
	s_nop 0
	global_load_lds_dwordx4 v134, s[48:49]
	s_waitcnt vmcnt(8)
	s_waitcnt lgkmcnt(0)
	s_barrier
	v_mfma_f32_16x16x32_bf16 v[124:127], v[140:143], v[180:183], v[124:127]
	v_mfma_f32_16x16x32_bf16 v[120:123], v[156:159], v[180:183], v[120:123]
	v_mfma_f32_16x16x32_bf16 v[112:115], v[140:143], v[188:191], v[112:115]
	v_mfma_f32_16x16x32_bf16 v[104:107], v[156:159], v[188:191], v[104:107]
	v_mfma_f32_16x16x32_bf16 v[96:99], v[140:143], v[196:199], v[96:99]
	v_mfma_f32_16x16x32_bf16 v[88:91], v[156:159], v[196:199], v[88:91]
	v_mfma_f32_16x16x32_bf16 v[80:83], v[140:143], v[204:207], v[80:83]
	v_mfma_f32_16x16x32_bf16 v[72:75], v[156:159], v[204:207], v[72:75]
	v_mfma_f32_16x16x32_bf16 v[124:127], v[152:155], v[184:187], v[124:127]
	v_mfma_f32_16x16x32_bf16 v[120:123], v[160:163], v[184:187], v[120:123]
	v_mfma_f32_16x16x32_bf16 v[112:115], v[152:155], v[192:195], v[112:115]
	v_mfma_f32_16x16x32_bf16 v[104:107], v[160:163], v[192:195], v[104:107]
	v_mfma_f32_16x16x32_bf16 v[96:99], v[152:155], v[200:203], v[96:99]
	v_mfma_f32_16x16x32_bf16 v[88:91], v[160:163], v[200:203], v[88:91]
	v_mfma_f32_16x16x32_bf16 v[80:83], v[152:155], v[208:211], v[80:83]
	v_mfma_f32_16x16x32_bf16 v[72:75], v[160:163], v[208:211], v[72:75]
	v_mfma_f32_16x16x32_bf16 v[116:119], v[164:167], v[180:183], v[116:119]
	v_mfma_f32_16x16x32_bf16 v[108:111], v[172:175], v[180:183], v[108:111]
	v_mfma_f32_16x16x32_bf16 v[100:103], v[164:167], v[188:191], v[100:103]
	v_mfma_f32_16x16x32_bf16 v[92:95], v[172:175], v[188:191], v[92:95]
	v_mfma_f32_16x16x32_bf16 v[84:87], v[164:167], v[196:199], v[84:87]
	v_mfma_f32_16x16x32_bf16 v[76:79], v[172:175], v[196:199], v[76:79]
	v_mfma_f32_16x16x32_bf16 v[68:71], v[164:167], v[204:207], v[68:71]
	v_mfma_f32_16x16x32_bf16 v[64:67], v[172:175], v[204:207], v[64:67]
	v_mfma_f32_16x16x32_bf16 v[116:119], v[168:171], v[184:187], v[116:119]
	v_mfma_f32_16x16x32_bf16 v[108:111], v[176:179], v[184:187], v[108:111]
	v_mfma_f32_16x16x32_bf16 v[100:103], v[168:171], v[192:195], v[100:103]
	v_mfma_f32_16x16x32_bf16 v[92:95], v[176:179], v[192:195], v[92:95]
	v_mfma_f32_16x16x32_bf16 v[84:87], v[168:171], v[200:203], v[84:87]
	v_mfma_f32_16x16x32_bf16 v[76:79], v[176:179], v[200:203], v[76:79]
	v_mfma_f32_16x16x32_bf16 v[68:71], v[168:171], v[208:211], v[68:71]
	v_mfma_f32_16x16x32_bf16 v[64:67], v[176:179], v[208:211], v[64:67]
	s_barrier
	s_add_i32 s3, s58, s25
	s_mov_b32 m0, s3
	ds_read_b128 v[180:183], v151 offset:16384
	ds_read_b128 v[184:187], v151 offset:17408
	ds_read_b128 v[188:191], v151 offset:18432
	ds_read_b128 v[192:195], v151 offset:19456
	ds_read_b128 v[196:199], v151 offset:20480
	ds_read_b128 v[200:203], v151 offset:21504
	ds_read_b128 v[204:207], v151 offset:22528
	ds_read_b128 v[208:211], v151 offset:23552
	global_load_lds_dwordx4 v128, s[52:53]
	s_add_i32 m0, s3, 0x2000
	s_add_u32 s66, s52, 0x200000
	s_addc_u32 s67, s53, 0
	s_add_i32 s3, s59, s25
	global_load_lds_dwordx4 v130, s[52:53]
	s_mov_b32 m0, s3
	s_nop 0
	global_load_lds_dwordx4 v128, s[66:67]
	s_add_i32 m0, s3, 0x2000
	s_nop 0
	global_load_lds_dwordx4 v130, s[66:67]
	s_mov_b32 m0, s27
	s_nop 0
	global_load_lds_dwordx4 v128, s[54:55]
	s_mov_b32 m0, s30
	s_nop 0
	global_load_lds_dwordx4 v130, s[54:55]
	s_waitcnt vmcnt(8)
	s_waitcnt lgkmcnt(0)
	s_barrier
	v_mfma_f32_16x16x32_bf16 v[60:63], v[140:143], v[180:183], v[60:63]
	v_mfma_f32_16x16x32_bf16 v[56:59], v[156:159], v[180:183], v[56:59]
	v_mfma_f32_16x16x32_bf16 v[48:51], v[140:143], v[188:191], v[48:51]
	v_mfma_f32_16x16x32_bf16 v[40:43], v[156:159], v[188:191], v[40:43]
	v_mfma_f32_16x16x32_bf16 v[32:35], v[140:143], v[196:199], v[32:35]
	v_mfma_f32_16x16x32_bf16 v[24:27], v[156:159], v[196:199], v[24:27]
	v_mfma_f32_16x16x32_bf16 v[16:19], v[140:143], v[204:207], v[16:19]
	v_mfma_f32_16x16x32_bf16 v[8:11], v[156:159], v[204:207], v[8:11]
	v_mfma_f32_16x16x32_bf16 v[60:63], v[152:155], v[184:187], v[60:63]
	v_mfma_f32_16x16x32_bf16 v[56:59], v[160:163], v[184:187], v[56:59]
	v_mfma_f32_16x16x32_bf16 v[48:51], v[152:155], v[192:195], v[48:51]
	v_mfma_f32_16x16x32_bf16 v[40:43], v[160:163], v[192:195], v[40:43]
	v_mfma_f32_16x16x32_bf16 v[32:35], v[152:155], v[200:203], v[32:35]
	v_mfma_f32_16x16x32_bf16 v[24:27], v[160:163], v[200:203], v[24:27]
	v_mfma_f32_16x16x32_bf16 v[16:19], v[152:155], v[208:211], v[16:19]
	v_mfma_f32_16x16x32_bf16 v[8:11], v[160:163], v[208:211], v[8:11]
	v_mfma_f32_16x16x32_bf16 v[52:55], v[164:167], v[180:183], v[52:55]
	v_mfma_f32_16x16x32_bf16 v[44:47], v[172:175], v[180:183], v[44:47]
	v_mfma_f32_16x16x32_bf16 v[36:39], v[164:167], v[188:191], v[36:39]
	v_mfma_f32_16x16x32_bf16 v[28:31], v[172:175], v[188:191], v[28:31]
	v_mfma_f32_16x16x32_bf16 v[20:23], v[164:167], v[196:199], v[20:23]
	v_mfma_f32_16x16x32_bf16 v[12:15], v[172:175], v[196:199], v[12:15]
	v_mfma_f32_16x16x32_bf16 v[4:7], v[164:167], v[204:207], v[4:7]
	v_mfma_f32_16x16x32_bf16 v[0:3], v[172:175], v[204:207], v[0:3]
	v_mfma_f32_16x16x32_bf16 v[52:55], v[168:171], v[184:187], v[52:55]
	v_mfma_f32_16x16x32_bf16 v[44:47], v[176:179], v[184:187], v[44:47]
	v_mfma_f32_16x16x32_bf16 v[36:39], v[168:171], v[192:195], v[36:39]
	v_mfma_f32_16x16x32_bf16 v[28:31], v[176:179], v[192:195], v[28:31]
	v_mfma_f32_16x16x32_bf16 v[20:23], v[168:171], v[200:203], v[20:23]
	v_mfma_f32_16x16x32_bf16 v[12:15], v[176:179], v[200:203], v[12:15]
	v_mfma_f32_16x16x32_bf16 v[4:7], v[168:171], v[208:211], v[4:7]
	v_mfma_f32_16x16x32_bf16 v[0:3], v[176:179], v[208:211], v[0:3]
	s_barrier
	s_add_i32 s3, 0, 0x18000
	s_add_i32 s65, 0, 0x1c000
	v_add_u32_e32 v160, s3, v147
	v_add_u32_e32 v176, s65, v147
	ds_read_b128 v[140:143], v160
	ds_read_b128 v[152:155], v160 offset:1024
	ds_read_b128 v[156:159], v160 offset:2048
	ds_read_b128 v[160:163], v160 offset:3072
	ds_read_b128 v[164:167], v176
	ds_read_b128 v[168:171], v176 offset:1024
	ds_read_b128 v[172:175], v176 offset:2048
	ds_read_b128 v[176:179], v176 offset:3072
	s_add_u32 s54, s54, 0x200000
	s_addc_u32 s55, s55, 0
	s_mov_b32 m0, s31
	ds_read_b128 v[180:183], v151 offset:32768
	ds_read_b128 v[184:187], v151 offset:33792
	ds_read_b128 v[188:191], v151 offset:34816
	ds_read_b128 v[192:195], v151 offset:35840
	ds_read_b128 v[196:199], v151 offset:36864
	ds_read_b128 v[200:203], v151 offset:37888
	ds_read_b128 v[204:207], v151 offset:38912
	ds_read_b128 v[208:211], v151 offset:39936
	global_load_lds_dwordx4 v128, s[54:55]
	s_mov_b32 m0, s33
	s_nop 0
	global_load_lds_dwordx4 v130, s[54:55]
	s_waitcnt vmcnt(8)
	s_waitcnt lgkmcnt(0)
	s_barrier
	v_mfma_f32_16x16x32_bf16 v[124:127], v[140:143], v[180:183], v[124:127]
	v_mfma_f32_16x16x32_bf16 v[120:123], v[156:159], v[180:183], v[120:123]
	v_mfma_f32_16x16x32_bf16 v[112:115], v[140:143], v[188:191], v[112:115]
	v_mfma_f32_16x16x32_bf16 v[104:107], v[156:159], v[188:191], v[104:107]
	v_mfma_f32_16x16x32_bf16 v[96:99], v[140:143], v[196:199], v[96:99]
	v_mfma_f32_16x16x32_bf16 v[88:91], v[156:159], v[196:199], v[88:91]
	v_mfma_f32_16x16x32_bf16 v[80:83], v[140:143], v[204:207], v[80:83]
	v_mfma_f32_16x16x32_bf16 v[72:75], v[156:159], v[204:207], v[72:75]
	v_mfma_f32_16x16x32_bf16 v[124:127], v[152:155], v[184:187], v[124:127]
	v_mfma_f32_16x16x32_bf16 v[120:123], v[160:163], v[184:187], v[120:123]
	v_mfma_f32_16x16x32_bf16 v[112:115], v[152:155], v[192:195], v[112:115]
	v_mfma_f32_16x16x32_bf16 v[104:107], v[160:163], v[192:195], v[104:107]
	v_mfma_f32_16x16x32_bf16 v[96:99], v[152:155], v[200:203], v[96:99]
	v_mfma_f32_16x16x32_bf16 v[88:91], v[160:163], v[200:203], v[88:91]
	v_mfma_f32_16x16x32_bf16 v[80:83], v[152:155], v[208:211], v[80:83]
	v_mfma_f32_16x16x32_bf16 v[72:75], v[160:163], v[208:211], v[72:75]
	v_mfma_f32_16x16x32_bf16 v[116:119], v[164:167], v[180:183], v[116:119]
	v_mfma_f32_16x16x32_bf16 v[108:111], v[172:175], v[180:183], v[108:111]
	v_mfma_f32_16x16x32_bf16 v[100:103], v[164:167], v[188:191], v[100:103]
	v_mfma_f32_16x16x32_bf16 v[92:95], v[172:175], v[188:191], v[92:95]
	v_mfma_f32_16x16x32_bf16 v[84:87], v[164:167], v[196:199], v[84:87]
	v_mfma_f32_16x16x32_bf16 v[76:79], v[172:175], v[196:199], v[76:79]
	v_mfma_f32_16x16x32_bf16 v[68:71], v[164:167], v[204:207], v[68:71]
	v_mfma_f32_16x16x32_bf16 v[64:67], v[172:175], v[204:207], v[64:67]
	v_mfma_f32_16x16x32_bf16 v[116:119], v[168:171], v[184:187], v[116:119]
	v_mfma_f32_16x16x32_bf16 v[108:111], v[176:179], v[184:187], v[108:111]
	v_mfma_f32_16x16x32_bf16 v[100:103], v[168:171], v[192:195], v[100:103]
	v_mfma_f32_16x16x32_bf16 v[92:95], v[176:179], v[192:195], v[92:95]
	v_mfma_f32_16x16x32_bf16 v[84:87], v[168:171], v[200:203], v[84:87]
	v_mfma_f32_16x16x32_bf16 v[76:79], v[176:179], v[200:203], v[76:79]
	v_mfma_f32_16x16x32_bf16 v[68:71], v[168:171], v[208:211], v[68:71]
	v_mfma_f32_16x16x32_bf16 v[64:67], v[176:179], v[208:211], v[64:67]
	s_barrier
	s_add_i32 s3, s3, s25
	s_add_u32 s52, s52, 0x80
	s_addc_u32 s53, s53, 0
	s_mov_b32 m0, s3
	ds_read_b128 v[180:183], v151 offset:49152
	ds_read_b128 v[184:187], v151 offset:50176
	ds_read_b128 v[188:191], v151 offset:51200
	ds_read_b128 v[192:195], v151 offset:52224
	ds_read_b128 v[196:199], v151 offset:53248
	ds_read_b128 v[200:203], v151 offset:54272
	ds_read_b128 v[204:207], v151 offset:55296
	ds_read_b128 v[208:211], v151 offset:56320
	global_load_lds_dwordx4 v128, s[52:53]
	s_add_i32 m0, s3, 0x2000
	s_add_i32 s3, s65, s25
	global_load_lds_dwordx4 v130, s[52:53]
	s_add_u32 s52, s52, 0x200000
	s_addc_u32 s53, s53, 0
	s_mov_b32 m0, s3
	s_nop 0
	global_load_lds_dwordx4 v128, s[52:53]
	s_add_i32 m0, s3, 0x2000
	s_nop 0
	global_load_lds_dwordx4 v130, s[52:53]
	s_add_u32 s54, s54, 0xffe00080
	s_addc_u32 s55, s55, -1
	s_mov_b32 m0, s56
	s_nop 0
	global_load_lds_dwordx4 v128, s[54:55]
	s_mov_b32 m0, s57
	s_nop 0
	global_load_lds_dwordx4 v130, s[54:55]
	s_waitcnt vmcnt(8)
	s_waitcnt lgkmcnt(0)
	s_barrier
	v_mfma_f32_16x16x32_bf16 v[60:63], v[140:143], v[180:183], v[60:63]
	v_mfma_f32_16x16x32_bf16 v[56:59], v[156:159], v[180:183], v[56:59]
	v_mfma_f32_16x16x32_bf16 v[48:51], v[140:143], v[188:191], v[48:51]
	v_mfma_f32_16x16x32_bf16 v[40:43], v[156:159], v[188:191], v[40:43]
	v_mfma_f32_16x16x32_bf16 v[32:35], v[140:143], v[196:199], v[32:35]
	v_mfma_f32_16x16x32_bf16 v[24:27], v[156:159], v[196:199], v[24:27]
	v_mfma_f32_16x16x32_bf16 v[16:19], v[140:143], v[204:207], v[16:19]
	v_mfma_f32_16x16x32_bf16 v[8:11], v[156:159], v[204:207], v[8:11]
	v_mfma_f32_16x16x32_bf16 v[60:63], v[152:155], v[184:187], v[60:63]
	v_mfma_f32_16x16x32_bf16 v[56:59], v[160:163], v[184:187], v[56:59]
	v_mfma_f32_16x16x32_bf16 v[48:51], v[152:155], v[192:195], v[48:51]
	v_mfma_f32_16x16x32_bf16 v[40:43], v[160:163], v[192:195], v[40:43]
	v_mfma_f32_16x16x32_bf16 v[32:35], v[152:155], v[200:203], v[32:35]
	v_mfma_f32_16x16x32_bf16 v[24:27], v[160:163], v[200:203], v[24:27]
	v_mfma_f32_16x16x32_bf16 v[16:19], v[152:155], v[208:211], v[16:19]
	v_mfma_f32_16x16x32_bf16 v[8:11], v[160:163], v[208:211], v[8:11]
	v_mfma_f32_16x16x32_bf16 v[52:55], v[164:167], v[180:183], v[52:55]
	v_mfma_f32_16x16x32_bf16 v[44:47], v[172:175], v[180:183], v[44:47]
	v_mfma_f32_16x16x32_bf16 v[36:39], v[164:167], v[188:191], v[36:39]
	v_mfma_f32_16x16x32_bf16 v[28:31], v[172:175], v[188:191], v[28:31]
	v_mfma_f32_16x16x32_bf16 v[20:23], v[164:167], v[196:199], v[20:23]
	v_mfma_f32_16x16x32_bf16 v[12:15], v[172:175], v[196:199], v[12:15]
	v_mfma_f32_16x16x32_bf16 v[4:7], v[164:167], v[204:207], v[4:7]
	v_mfma_f32_16x16x32_bf16 v[0:3], v[172:175], v[204:207], v[0:3]
	v_mfma_f32_16x16x32_bf16 v[52:55], v[168:171], v[184:187], v[52:55]
	v_mfma_f32_16x16x32_bf16 v[44:47], v[176:179], v[184:187], v[44:47]
	v_mfma_f32_16x16x32_bf16 v[36:39], v[168:171], v[192:195], v[36:39]
	v_mfma_f32_16x16x32_bf16 v[28:31], v[176:179], v[192:195], v[28:31]
	v_mfma_f32_16x16x32_bf16 v[20:23], v[168:171], v[200:203], v[20:23]
	v_mfma_f32_16x16x32_bf16 v[12:15], v[176:179], v[200:203], v[12:15]
	v_mfma_f32_16x16x32_bf16 v[4:7], v[168:171], v[208:211], v[4:7]
	v_mfma_f32_16x16x32_bf16 v[0:3], v[176:179], v[208:211], v[0:3]
	s_barrier
	s_add_i32 s64, s64, 2
	s_add_u32 s48, s48, 0x100
	s_addc_u32 s49, s49, 0
	s_add_u32 s50, s50, 0x100
	s_addc_u32 s51, s51, 0
	s_cmpk_gt_u32 s64, 0x7d
	s_cbranch_scc0 .LBB0_2555
	s_and_b64 vcc, exec, s[10:11]
	s_cbranch_vccz .LBB0_2558
	s_barrier
